# dil lean unrolled loop plus K loads coalesced (8 lanes per 128B row) and transposed through a padded per-wave LDS stage
# baseline (speedup 1.0000x reference)
; #define LAS __attribute__((address_space(3)))
; #define GAS __attribute__((address_space(1)))
; __device__ __forceinline__ void dil_unit(LAS unsigned char* lds, bf16_t* proj, int seq, int hd, int T0, int rho) {
;     int tid_ = threadIdx.x; asm volatile("" : "+v"(tid_));
;     const int tid = tid_, lane = tid & 63, r32 = lane & 31, hi = lane >> 5, wid = __builtin_amdgcn_readfirstlane(tid >> 6);
;     bf16_t* base = proj + (size_t)seq * SEQ * NIN;
;     LAS unsigned char* wbuf = lds + wid * 4096;
;     const LAS unsigned char* vp = wbuf + ((lane >> 4) & 1) * 32 + (lane & 3) * 8 + (4 * hi + ((lane & 15) >> 2)) * 64;
;     const int P0 = T0 + rho;
;     bf16x8 qr[4];
; #pragma unroll
;     for (int ks = 0; ks < 4; ++ks) qr[ks] = *(const GAS bf16x8*)(base + (size_t)(P0 + 16 * r32) * NIN + PC_LQ + hd * 64 + 16 * ks + 8 * hi);
;     f32x16 o0 = {}, o1 = {}; float l = 0.f;
;     const bool bound = (T0 < 1024) || (T0 >= 15360);
.LBB0_554:
	s_lshr_b32 s82, s33, 8
	s_mul_i32 s82, s82, 13
	s_add_i32 s82, s82, s33
	s_ashr_i32 s2, s33, 6
	s_mul_hi_i32 s7, s2, 0x2aaaaaab
	s_lshl_b32 s3, s82, 8
	s_lshr_b32 s8, s7, 31
	s_and_b32 s6, s3, 0x3e00
	s_lshl_b32 s3, s82, 3
	s_add_i32 s7, s7, s8
	s_and_b32 s3, s3, 8
	s_mul_i32 s8, s7, 6
	s_add_i32 s3, s3, s64
	s_sub_i32 s8, s2, s8
	s_mul_hi_i32 s2, s7, 0x6000000
	s_mul_i32 s7, s7, 0x6000000
	v_mov_b32_e32 v2, v154
	s_add_u32 s56, s48, s7
	s_addc_u32 s57, s49, s2
	v_and_b32_e32 v105, 31, v2
	s_add_i32 s76, s3, s6
	v_lshl_add_u32 v3, v105, 4, s76
	v_mov_b64_e32 v[0:1], s[56:57]
	s_lshl_b32 s58, s8, 6
	v_bfe_u32 v106, v2, 5, 1
	v_mad_u64_u32 v[0:1], s[2:3], v3, s65, v[0:1]
	s_ashr_i32 s59, s58, 31
	v_lshl_add_u64 v[0:1], s[58:59], 1, v[0:1]
	v_lshlrev_b32_e32 v80, 4, v106
	v_lshl_add_u64 v[0:1], v[0:1], 0, v[80:81]
	global_load_dwordx4 v[48:51], v[0:1], off offset:1280
	global_load_dwordx4 v[52:55], v[0:1], off offset:1312
	global_load_dwordx4 v[56:59], v[0:1], off offset:1344
	global_load_dwordx4 v[60:63], v[0:1], off offset:1376
	v_readfirstlane_b32 s2, v2
	s_lshl_b32 s2, s2, 6
	s_and_b32 s2, s2, 0xfffff000
	v_lshlrev_b32_e32 v0, 1, v2
	v_lshlrev_b32_e32 v104, 3, v2
	v_lshlrev_b32_e32 v107, 2, v106
	v_lshrrev_b32_e32 v1, 2, v2
	v_and_b32_e32 v103, 63, v2
	v_and_b32_e32 v0, 32, v0
	v_and_b32_e32 v98, 24, v104
	v_and_or_b32 v1, v1, 3, v107
	s_add_i32 s77, s2, 0
	v_lshlrev_b32_e32 v108, 6, v1
	v_lshlrev_b32_e32 v1, 3, v106
	v_add3_u32 v109, s77, v0, v98
	s_addk_i32 s6, 0xc400
	v_lshrrev_b32_e32 v110, 2, v103
	v_lshlrev_b32_e32 v0, 4, v103
	s_mov_b64 s[2:3], -1
	s_cmp_gt_u32 s6, 0xffffc7ff
	v_lshlrev_b32_e32 v100, 1, v98
	s_mul_i32 s6, s8, 0x1c00
	v_lshlrev_b32_e32 v82, 1, v1
	v_or_b32_e32 v111, 16, v110
	v_add_u32_e32 v112, s77, v0
	s_cbranch_scc0 .LBB0_558
	s_movk_i32 s100, 0x1800
	s_add_i32 s101, s6, 0x15c00
	s_lshl_b32 s90, s58, 1
	s_add_u32 s82, s56, s90
	s_addc_u32 s83, s57, 0
	s_add_u32 s82, s82, 0x1200
	s_addc_u32 s83, s83, 0
	s_sub_i32 s90, s76, 64
	s_mul_i32 s90, s90, 0x1800
	s_add_u32 s84, s82, s90
	s_addc_u32 s85, s83, 0
	s_sub_i32 s90, s76, 256
	s_mul_i32 s90, s90, 0x1800
	s_add_u32 s86, s82, s90
	s_addc_u32 s87, s83, 0
	s_sub_i32 s90, s76, 1024
	s_mul_i32 s90, s90, 0x1800
	s_add_u32 s88, s82, s90
	s_addc_u32 s89, s83, 0
	v_lshlrev_b32_e32 v153, 1, v98
	v_mad_u32_u24 v80, v105, s100, v82
	v_mad_u32_u24 v100, v110, s100, v153
	v_add_u32_e32 v149, 0x18000, v100
	v_lshlrev_b32_e32 v83, 2, v105
	v_mad_u32_u24 v83, v83, s100, v82
	v_lshlrev_b32_e32 v101, 2, v110
	v_mad_u32_u24 v101, v101, s100, v153
	v_add_u32_e32 v150, 0x60000, v101
	v_lshlrev_b32_e32 v99, 4, v105
	v_mad_u32_u24 v99, v99, s100, v82
	v_lshlrev_b32_e32 v148, 4, v110
	v_mad_u32_u24 v148, v148, s100, v153
	v_add_u32_e32 v151, 0x180000, v148
	s_lshr_b32 s90, s77, 12
	s_mul_i32 s90, s90, 4608
	s_add_i32 s91, s90, 0x8000
	s_movk_i32 s35, 144
	v_lshrrev_b32_e32 v249, 3, v103
	v_and_b32_e32 v250, 7, v103
	v_lshlrev_b32_e32 v250, 4, v250
	v_mad_u32_u24 v247, v249, s35, v250
	v_add_u32_e32 v247, s91, v247
	v_mad_u32_u24 v248, v105, s35, v82
	v_add_u32_e32 v248, s91, v248
	v_add_u32_e32 v235, 0, v249
	v_mad_u32_u24 v235, v235, s100, v250
	v_add_u32_e32 v236, 8, v249
	v_mad_u32_u24 v236, v236, s100, v250
	v_add_u32_e32 v237, 16, v249
	v_mad_u32_u24 v237, v237, s100, v250
	v_add_u32_e32 v238, 24, v249
	v_mad_u32_u24 v238, v238, s100, v250
	v_add_u32_e32 v239, 0, v249
	v_lshlrev_b32_e32 v239, 2, v239
	v_mad_u32_u24 v239, v239, s100, v250
	v_add_u32_e32 v240, 8, v249
	v_lshlrev_b32_e32 v240, 2, v240
	v_mad_u32_u24 v240, v240, s100, v250
	v_add_u32_e32 v241, 16, v249
	v_lshlrev_b32_e32 v241, 2, v241
	v_mad_u32_u24 v241, v241, s100, v250
	v_add_u32_e32 v242, 24, v249
	v_lshlrev_b32_e32 v242, 2, v242
	v_mad_u32_u24 v242, v242, s100, v250
	v_add_u32_e32 v243, 0, v249
	v_lshlrev_b32_e32 v243, 4, v243
	v_mad_u32_u24 v243, v243, s100, v250
	v_add_u32_e32 v244, 8, v249
	v_lshlrev_b32_e32 v244, 4, v244
	v_mad_u32_u24 v244, v244, s100, v250
	v_add_u32_e32 v245, 16, v249
	v_lshlrev_b32_e32 v245, 4, v245
	v_mad_u32_u24 v245, v245, s100, v250
	v_add_u32_e32 v246, 24, v249
	v_lshlrev_b32_e32 v246, 4, v246
	v_mad_u32_u24 v246, v246, s100, v250
	v_lshlrev_b32_e32 v228, 4, v105
	v_sub_u32_e32 v228, v107, v228
	s_add_i32 s90, s101, 1984
	v_lshl_add_u32 v228, v228, 2, s90
	v_lshlrev_b32_e32 v229, 2, v105
	v_sub_u32_e32 v229, v107, v229
	s_add_i32 s90, s101, 5104
	v_lshl_add_u32 v229, v229, 2, s90
	v_sub_u32_e32 v230, v107, v105
	s_add_i32 s90, s101, 6364
	v_lshl_add_u32 v230, v230, 2, s90
	v_add_u32_e32 v231, v109, v108
	v_mov_b64_e32 v[232:233], 0
	v_mov_b64_e32 v[0:1], 0
	v_mov_b64_e32 v[2:3], 0
	v_mov_b64_e32 v[4:5], 0
	v_mov_b64_e32 v[6:7], 0
	v_mov_b64_e32 v[8:9], 0
	v_mov_b64_e32 v[10:11], 0
	v_mov_b64_e32 v[12:13], 0
	v_mov_b64_e32 v[14:15], 0
	v_mov_b64_e32 v[16:17], 0
	v_mov_b64_e32 v[18:19], 0
	v_mov_b64_e32 v[20:21], 0
	v_mov_b64_e32 v[22:23], 0
	v_mov_b64_e32 v[24:25], 0
	v_mov_b64_e32 v[26:27], 0
	v_mov_b64_e32 v[28:29], 0
	v_mov_b64_e32 v[30:31], 0
	global_load_dwordx4 v[116:119], v235, s[84:85]
	global_load_dwordx4 v[120:123], v236, s[84:85]
	global_load_dwordx4 v[124:127], v237, s[84:85]
	global_load_dwordx4 v[128:131], v238, s[84:85]
	global_load_dwordx4 v[132:135], v100, s[84:85] offset:768
	global_load_dwordx4 v[136:139], v149, s[84:85] offset:768
	global_load_dwordx4 v[140:143], v100, s[84:85] offset:832
	global_load_dwordx4 v[144:147], v149, s[84:85] offset:832
	s_add_u32 s84, s84, 0x30000
	s_addc_u32 s85, s85, 0
	global_load_dwordx4 v[156:159], v235, s[84:85]
	global_load_dwordx4 v[160:163], v236, s[84:85]
	global_load_dwordx4 v[164:167], v237, s[84:85]
	global_load_dwordx4 v[168:171], v238, s[84:85]
	global_load_dwordx4 v[172:175], v100, s[84:85] offset:768
	global_load_dwordx4 v[176:179], v149, s[84:85] offset:768
	global_load_dwordx4 v[180:183], v100, s[84:85] offset:832
	global_load_dwordx4 v[184:187], v149, s[84:85] offset:832
	s_add_u32 s84, s84, 0x30000
	s_addc_u32 s85, s85, 0
	global_load_dwordx4 v[188:191], v235, s[84:85]
	global_load_dwordx4 v[192:195], v236, s[84:85]
	global_load_dwordx4 v[196:199], v237, s[84:85]
	global_load_dwordx4 v[200:203], v238, s[84:85]
	global_load_dwordx4 v[204:207], v100, s[84:85] offset:768
	global_load_dwordx4 v[208:211], v149, s[84:85] offset:768
	global_load_dwordx4 v[212:215], v100, s[84:85] offset:832
	global_load_dwordx4 v[216:219], v149, s[84:85] offset:832
	s_add_u32 s84, s84, 0x30000
	s_addc_u32 s85, s85, 0
	s_waitcnt vmcnt(16)
	ds_write_b128 v247, v[116:119]
	ds_write_b128 v247, v[120:123] offset:1152
	ds_write_b128 v247, v[124:127] offset:2304
	ds_write_b128 v247, v[128:131] offset:3456
	ds_write_b128 v112, v[132:135]
	ds_write_b128 v112, v[136:139] offset:1024
	ds_write_b128 v112, v[140:143] offset:2048
	ds_write_b128 v112, v[144:147] offset:3072
	v_mov_b32_e32 v115, v228
	ds_read2_b32 v[32:33], v115 offset0:0 offset1:1
	ds_read2_b32 v[34:35], v115 offset0:2 offset1:3
	ds_read2_b32 v[36:37], v115 offset0:8 offset1:9
	ds_read2_b32 v[38:39], v115 offset0:10 offset1:11
	ds_read2_b32 v[40:41], v115 offset0:16 offset1:17
	ds_read2_b32 v[42:43], v115 offset0:18 offset1:19
	ds_read2_b32 v[44:45], v115 offset0:24 offset1:25
	ds_read2_b32 v[46:47], v115 offset0:26 offset1:27
	ds_read_b128 v[116:119], v248
	ds_read_b128 v[120:123], v248 offset:32
	ds_read_b128 v[124:127], v248 offset:64
	ds_read_b128 v[128:131], v248 offset:96
	ds_read_b64_tr_b16 v[72:73], v231
	ds_read_b64_tr_b16 v[74:75], v231 offset:512
	ds_read_b64_tr_b16 v[76:77], v231 offset:2048
	ds_read_b64_tr_b16 v[78:79], v231 offset:2560
	ds_read_b64_tr_b16 v[220:221], v231 offset:1024
	ds_read_b64_tr_b16 v[222:223], v231 offset:1536
	ds_read_b64_tr_b16 v[224:225], v231 offset:3072
	ds_read_b64_tr_b16 v[226:227], v231 offset:3584
	s_waitcnt lgkmcnt(8)
	v_mfma_f32_32x32x16_bf16 v[32:47], v[116:119], v[48:51], v[32:47]
	v_mfma_f32_32x32x16_bf16 v[32:47], v[120:123], v[52:55], v[32:47]
	v_mfma_f32_32x32x16_bf16 v[32:47], v[124:127], v[56:59], v[32:47]
	v_mfma_f32_32x32x16_bf16 v[32:47], v[128:131], v[60:63], v[32:47]
	s_nop 11
	v_exp_f32_e32 v32, v32
	v_exp_f32_e32 v33, v33
	v_exp_f32_e32 v34, v34
	v_exp_f32_e32 v35, v35
	v_exp_f32_e32 v36, v36
	v_exp_f32_e32 v37, v37
	v_exp_f32_e32 v38, v38
	v_exp_f32_e32 v39, v39
	v_exp_f32_e32 v40, v40
	v_exp_f32_e32 v41, v41
	v_exp_f32_e32 v42, v42
	v_exp_f32_e32 v43, v43
	v_exp_f32_e32 v44, v44
	v_exp_f32_e32 v45, v45
	v_exp_f32_e32 v46, v46
	v_exp_f32_e32 v47, v47
	v_cvt_pk_bf16_f32 v64, v32, v33
	v_cvt_pk_bf16_f32 v65, v34, v35
	v_cvt_pk_bf16_f32 v66, v36, v37
	v_cvt_pk_bf16_f32 v67, v38, v39
	v_cvt_pk_bf16_f32 v68, v40, v41
	v_cvt_pk_bf16_f32 v69, v42, v43
	v_cvt_pk_bf16_f32 v70, v44, v45
	v_cvt_pk_bf16_f32 v71, v46, v47
	v_pk_add_f32 v[232:233], v[232:233], v[32:33]
	v_pk_add_f32 v[232:233], v[232:233], v[34:35]
	v_pk_add_f32 v[232:233], v[232:233], v[36:37]
	v_pk_add_f32 v[232:233], v[232:233], v[38:39]
	v_pk_add_f32 v[232:233], v[232:233], v[40:41]
	v_pk_add_f32 v[232:233], v[232:233], v[42:43]
	v_pk_add_f32 v[232:233], v[232:233], v[44:45]
	v_pk_add_f32 v[232:233], v[232:233], v[46:47]
	s_waitcnt lgkmcnt(0)
	v_mfma_f32_32x32x16_bf16 v[0:15], v[64:67], v[72:75], v[0:15]
	v_mfma_f32_32x32x16_bf16 v[16:31], v[64:67], v[76:79], v[16:31]
	v_mfma_f32_32x32x16_bf16 v[0:15], v[68:71], v[220:223], v[0:15]
	v_mfma_f32_32x32x16_bf16 v[16:31], v[68:71], v[224:227], v[16:31]
	global_load_dwordx4 v[116:119], v235, s[84:85]
	global_load_dwordx4 v[120:123], v236, s[84:85]
	global_load_dwordx4 v[124:127], v237, s[84:85]
	global_load_dwordx4 v[128:131], v238, s[84:85]
	global_load_dwordx4 v[132:135], v100, s[84:85] offset:768
	global_load_dwordx4 v[136:139], v149, s[84:85] offset:768
	global_load_dwordx4 v[140:143], v100, s[84:85] offset:832
	global_load_dwordx4 v[144:147], v149, s[84:85] offset:832
	s_add_u32 s84, s84, 0x30000
	s_addc_u32 s85, s85, 0
	s_waitcnt vmcnt(16)
	ds_write_b128 v247, v[156:159]
	ds_write_b128 v247, v[160:163] offset:1152
	ds_write_b128 v247, v[164:167] offset:2304
	ds_write_b128 v247, v[168:171] offset:3456
	ds_write_b128 v112, v[172:175]
	ds_write_b128 v112, v[176:179] offset:1024
	ds_write_b128 v112, v[180:183] offset:2048
	ds_write_b128 v112, v[184:187] offset:3072
	ds_read2_b32 v[32:33], v115 offset0:32 offset1:33
	ds_read2_b32 v[34:35], v115 offset0:34 offset1:35
	ds_read2_b32 v[36:37], v115 offset0:40 offset1:41
	ds_read2_b32 v[38:39], v115 offset0:42 offset1:43
	ds_read2_b32 v[40:41], v115 offset0:48 offset1:49
	ds_read2_b32 v[42:43], v115 offset0:50 offset1:51
	ds_read2_b32 v[44:45], v115 offset0:56 offset1:57
	ds_read2_b32 v[46:47], v115 offset0:58 offset1:59
	ds_read_b128 v[156:159], v248
	ds_read_b128 v[160:163], v248 offset:32
	ds_read_b128 v[164:167], v248 offset:64
	ds_read_b128 v[168:171], v248 offset:96
	ds_read_b64_tr_b16 v[72:73], v231
	ds_read_b64_tr_b16 v[74:75], v231 offset:512
	ds_read_b64_tr_b16 v[76:77], v231 offset:2048
	ds_read_b64_tr_b16 v[78:79], v231 offset:2560
	ds_read_b64_tr_b16 v[220:221], v231 offset:1024
	ds_read_b64_tr_b16 v[222:223], v231 offset:1536
	ds_read_b64_tr_b16 v[224:225], v231 offset:3072
	ds_read_b64_tr_b16 v[226:227], v231 offset:3584
	s_waitcnt lgkmcnt(8)
	v_mfma_f32_32x32x16_bf16 v[32:47], v[156:159], v[48:51], v[32:47]
	v_mfma_f32_32x32x16_bf16 v[32:47], v[160:163], v[52:55], v[32:47]
	v_mfma_f32_32x32x16_bf16 v[32:47], v[164:167], v[56:59], v[32:47]
	v_mfma_f32_32x32x16_bf16 v[32:47], v[168:171], v[60:63], v[32:47]
	s_nop 11
	v_exp_f32_e32 v32, v32
	v_exp_f32_e32 v33, v33
	v_exp_f32_e32 v34, v34
	v_exp_f32_e32 v35, v35
	v_exp_f32_e32 v36, v36
	v_exp_f32_e32 v37, v37
	v_exp_f32_e32 v38, v38
	v_exp_f32_e32 v39, v39
	v_exp_f32_e32 v40, v40
	v_exp_f32_e32 v41, v41
	v_exp_f32_e32 v42, v42
	v_exp_f32_e32 v43, v43
	v_exp_f32_e32 v44, v44
	v_exp_f32_e32 v45, v45
	v_exp_f32_e32 v46, v46
	v_exp_f32_e32 v47, v47
	v_cvt_pk_bf16_f32 v64, v32, v33
	v_cvt_pk_bf16_f32 v65, v34, v35
	v_cvt_pk_bf16_f32 v66, v36, v37
	v_cvt_pk_bf16_f32 v67, v38, v39
	v_cvt_pk_bf16_f32 v68, v40, v41
	v_cvt_pk_bf16_f32 v69, v42, v43
	v_cvt_pk_bf16_f32 v70, v44, v45
	v_cvt_pk_bf16_f32 v71, v46, v47
	v_pk_add_f32 v[232:233], v[232:233], v[32:33]
	v_pk_add_f32 v[232:233], v[232:233], v[34:35]
	v_pk_add_f32 v[232:233], v[232:233], v[36:37]
	v_pk_add_f32 v[232:233], v[232:233], v[38:39]
	v_pk_add_f32 v[232:233], v[232:233], v[40:41]
	v_pk_add_f32 v[232:233], v[232:233], v[42:43]
	v_pk_add_f32 v[232:233], v[232:233], v[44:45]
	v_pk_add_f32 v[232:233], v[232:233], v[46:47]
	s_waitcnt lgkmcnt(0)
	v_mfma_f32_32x32x16_bf16 v[0:15], v[64:67], v[72:75], v[0:15]
	v_mfma_f32_32x32x16_bf16 v[16:31], v[64:67], v[76:79], v[16:31]
	v_mfma_f32_32x32x16_bf16 v[0:15], v[68:71], v[220:223], v[0:15]
	v_mfma_f32_32x32x16_bf16 v[16:31], v[68:71], v[224:227], v[16:31]
	global_load_dwordx4 v[156:159], v235, s[84:85]
	global_load_dwordx4 v[160:163], v236, s[84:85]
	global_load_dwordx4 v[164:167], v237, s[84:85]
	global_load_dwordx4 v[168:171], v238, s[84:85]
	global_load_dwordx4 v[172:175], v100, s[84:85] offset:768
	global_load_dwordx4 v[176:179], v149, s[84:85] offset:768
	global_load_dwordx4 v[180:183], v100, s[84:85] offset:832
	global_load_dwordx4 v[184:187], v149, s[84:85] offset:832
	s_add_u32 s84, s84, 0x30000
	s_addc_u32 s85, s85, 0
	s_waitcnt vmcnt(16)
	ds_write_b128 v247, v[188:191]
	ds_write_b128 v247, v[192:195] offset:1152
	ds_write_b128 v247, v[196:199] offset:2304
	ds_write_b128 v247, v[200:203] offset:3456
	ds_write_b128 v112, v[204:207]
	ds_write_b128 v112, v[208:211] offset:1024
	ds_write_b128 v112, v[212:215] offset:2048
	ds_write_b128 v112, v[216:219] offset:3072
	ds_read2_b32 v[32:33], v115 offset0:64 offset1:65
	ds_read2_b32 v[34:35], v115 offset0:66 offset1:67
	ds_read2_b32 v[36:37], v115 offset0:72 offset1:73
	ds_read2_b32 v[38:39], v115 offset0:74 offset1:75
	ds_read2_b32 v[40:41], v115 offset0:80 offset1:81
	ds_read2_b32 v[42:43], v115 offset0:82 offset1:83
	ds_read2_b32 v[44:45], v115 offset0:88 offset1:89
	ds_read2_b32 v[46:47], v115 offset0:90 offset1:91
	ds_read_b128 v[188:191], v248
	ds_read_b128 v[192:195], v248 offset:32
	ds_read_b128 v[196:199], v248 offset:64
	ds_read_b128 v[200:203], v248 offset:96
	ds_read_b64_tr_b16 v[72:73], v231
	ds_read_b64_tr_b16 v[74:75], v231 offset:512
	ds_read_b64_tr_b16 v[76:77], v231 offset:2048
	ds_read_b64_tr_b16 v[78:79], v231 offset:2560
	ds_read_b64_tr_b16 v[220:221], v231 offset:1024
	ds_read_b64_tr_b16 v[222:223], v231 offset:1536
	ds_read_b64_tr_b16 v[224:225], v231 offset:3072
	ds_read_b64_tr_b16 v[226:227], v231 offset:3584
	s_waitcnt lgkmcnt(8)
	v_mfma_f32_32x32x16_bf16 v[32:47], v[188:191], v[48:51], v[32:47]
	v_mfma_f32_32x32x16_bf16 v[32:47], v[192:195], v[52:55], v[32:47]
	v_mfma_f32_32x32x16_bf16 v[32:47], v[196:199], v[56:59], v[32:47]
	v_mfma_f32_32x32x16_bf16 v[32:47], v[200:203], v[60:63], v[32:47]
	s_nop 11
	v_exp_f32_e32 v32, v32
	v_exp_f32_e32 v33, v33
	v_exp_f32_e32 v34, v34
	v_exp_f32_e32 v35, v35
	v_exp_f32_e32 v36, v36
	v_exp_f32_e32 v37, v37
	v_exp_f32_e32 v38, v38
	v_exp_f32_e32 v39, v39
	v_exp_f32_e32 v40, v40
	v_exp_f32_e32 v41, v41
	v_exp_f32_e32 v42, v42
	v_exp_f32_e32 v43, v43
	v_exp_f32_e32 v44, v44
	v_exp_f32_e32 v45, v45
	v_exp_f32_e32 v46, v46
	v_exp_f32_e32 v47, v47
	v_cvt_pk_bf16_f32 v64, v32, v33
	v_cvt_pk_bf16_f32 v65, v34, v35
	v_cvt_pk_bf16_f32 v66, v36, v37
	v_cvt_pk_bf16_f32 v67, v38, v39
	v_cvt_pk_bf16_f32 v68, v40, v41
	v_cvt_pk_bf16_f32 v69, v42, v43
	v_cvt_pk_bf16_f32 v70, v44, v45
	v_cvt_pk_bf16_f32 v71, v46, v47
	v_pk_add_f32 v[232:233], v[232:233], v[32:33]
	v_pk_add_f32 v[232:233], v[232:233], v[34:35]
	v_pk_add_f32 v[232:233], v[232:233], v[36:37]
	v_pk_add_f32 v[232:233], v[232:233], v[38:39]
	v_pk_add_f32 v[232:233], v[232:233], v[40:41]
	v_pk_add_f32 v[232:233], v[232:233], v[42:43]
	v_pk_add_f32 v[232:233], v[232:233], v[44:45]
	v_pk_add_f32 v[232:233], v[232:233], v[46:47]
	s_waitcnt lgkmcnt(0)
	v_mfma_f32_32x32x16_bf16 v[0:15], v[64:67], v[72:75], v[0:15]
	v_mfma_f32_32x32x16_bf16 v[16:31], v[64:67], v[76:79], v[16:31]
	v_mfma_f32_32x32x16_bf16 v[0:15], v[68:71], v[220:223], v[0:15]
	v_mfma_f32_32x32x16_bf16 v[16:31], v[68:71], v[224:227], v[16:31]
	global_load_dwordx4 v[188:191], v235, s[84:85]
	global_load_dwordx4 v[192:195], v236, s[84:85]
	global_load_dwordx4 v[196:199], v237, s[84:85]
	global_load_dwordx4 v[200:203], v238, s[84:85]
	global_load_dwordx4 v[204:207], v100, s[84:85] offset:768
	global_load_dwordx4 v[208:211], v149, s[84:85] offset:768
	global_load_dwordx4 v[212:215], v100, s[84:85] offset:832
	global_load_dwordx4 v[216:219], v149, s[84:85] offset:832
	s_add_u32 s84, s84, 0x30000
	s_addc_u32 s85, s85, 0
	s_waitcnt vmcnt(16)
	ds_write_b128 v247, v[116:119]
	ds_write_b128 v247, v[120:123] offset:1152
	ds_write_b128 v247, v[124:127] offset:2304
	ds_write_b128 v247, v[128:131] offset:3456
	ds_write_b128 v112, v[132:135]
	ds_write_b128 v112, v[136:139] offset:1024
	ds_write_b128 v112, v[140:143] offset:2048
	ds_write_b128 v112, v[144:147] offset:3072
	ds_read2_b32 v[32:33], v115 offset0:96 offset1:97
	ds_read2_b32 v[34:35], v115 offset0:98 offset1:99
	ds_read2_b32 v[36:37], v115 offset0:104 offset1:105
	ds_read2_b32 v[38:39], v115 offset0:106 offset1:107
	ds_read2_b32 v[40:41], v115 offset0:112 offset1:113
	ds_read2_b32 v[42:43], v115 offset0:114 offset1:115
	ds_read2_b32 v[44:45], v115 offset0:120 offset1:121
	ds_read2_b32 v[46:47], v115 offset0:122 offset1:123
	ds_read_b128 v[116:119], v248
	ds_read_b128 v[120:123], v248 offset:32
	ds_read_b128 v[124:127], v248 offset:64
	ds_read_b128 v[128:131], v248 offset:96
	ds_read_b64_tr_b16 v[72:73], v231
	ds_read_b64_tr_b16 v[74:75], v231 offset:512
	ds_read_b64_tr_b16 v[76:77], v231 offset:2048
	ds_read_b64_tr_b16 v[78:79], v231 offset:2560
	ds_read_b64_tr_b16 v[220:221], v231 offset:1024
	ds_read_b64_tr_b16 v[222:223], v231 offset:1536
	ds_read_b64_tr_b16 v[224:225], v231 offset:3072
	ds_read_b64_tr_b16 v[226:227], v231 offset:3584
	s_waitcnt lgkmcnt(8)
	v_mfma_f32_32x32x16_bf16 v[32:47], v[116:119], v[48:51], v[32:47]
	v_mfma_f32_32x32x16_bf16 v[32:47], v[120:123], v[52:55], v[32:47]
	v_mfma_f32_32x32x16_bf16 v[32:47], v[124:127], v[56:59], v[32:47]
	v_mfma_f32_32x32x16_bf16 v[32:47], v[128:131], v[60:63], v[32:47]
	s_nop 11
	v_exp_f32_e32 v32, v32
	v_exp_f32_e32 v33, v33
	v_exp_f32_e32 v34, v34
	v_exp_f32_e32 v35, v35
	v_exp_f32_e32 v36, v36
	v_exp_f32_e32 v37, v37
	v_exp_f32_e32 v38, v38
	v_exp_f32_e32 v39, v39
	v_exp_f32_e32 v40, v40
	v_exp_f32_e32 v41, v41
	v_exp_f32_e32 v42, v42
	v_exp_f32_e32 v43, v43
	v_exp_f32_e32 v44, v44
	v_exp_f32_e32 v45, v45
	v_exp_f32_e32 v46, v46
	v_exp_f32_e32 v47, v47
	v_cvt_pk_bf16_f32 v64, v32, v33
	v_cvt_pk_bf16_f32 v65, v34, v35
	v_cvt_pk_bf16_f32 v66, v36, v37
	v_cvt_pk_bf16_f32 v67, v38, v39
	v_cvt_pk_bf16_f32 v68, v40, v41
	v_cvt_pk_bf16_f32 v69, v42, v43
	v_cvt_pk_bf16_f32 v70, v44, v45
	v_cvt_pk_bf16_f32 v71, v46, v47
	v_pk_add_f32 v[232:233], v[232:233], v[32:33]
	v_pk_add_f32 v[232:233], v[232:233], v[34:35]
	v_pk_add_f32 v[232:233], v[232:233], v[36:37]
	v_pk_add_f32 v[232:233], v[232:233], v[38:39]
	v_pk_add_f32 v[232:233], v[232:233], v[40:41]
	v_pk_add_f32 v[232:233], v[232:233], v[42:43]
	v_pk_add_f32 v[232:233], v[232:233], v[44:45]
	v_pk_add_f32 v[232:233], v[232:233], v[46:47]
	s_waitcnt lgkmcnt(0)
	v_mfma_f32_32x32x16_bf16 v[0:15], v[64:67], v[72:75], v[0:15]
	v_mfma_f32_32x32x16_bf16 v[16:31], v[64:67], v[76:79], v[16:31]
	v_mfma_f32_32x32x16_bf16 v[0:15], v[68:71], v[220:223], v[0:15]
	v_mfma_f32_32x32x16_bf16 v[16:31], v[68:71], v[224:227], v[16:31]
	global_load_dwordx4 v[116:119], v235, s[84:85]
	global_load_dwordx4 v[120:123], v236, s[84:85]
	global_load_dwordx4 v[124:127], v237, s[84:85]
	global_load_dwordx4 v[128:131], v238, s[84:85]
	global_load_dwordx4 v[132:135], v100, s[84:85] offset:768
	global_load_dwordx4 v[136:139], v149, s[84:85] offset:768
	global_load_dwordx4 v[140:143], v100, s[84:85] offset:832
	global_load_dwordx4 v[144:147], v149, s[84:85] offset:832
	s_add_u32 s84, s84, 0x30000
	s_addc_u32 s85, s85, 0
	s_waitcnt vmcnt(16)
	ds_write_b128 v247, v[156:159]
	ds_write_b128 v247, v[160:163] offset:1152
	ds_write_b128 v247, v[164:167] offset:2304
	ds_write_b128 v247, v[168:171] offset:3456
	ds_write_b128 v112, v[172:175]
	ds_write_b128 v112, v[176:179] offset:1024
	ds_write_b128 v112, v[180:183] offset:2048
	ds_write_b128 v112, v[184:187] offset:3072
	ds_read2_b32 v[32:33], v115 offset0:128 offset1:129
	ds_read2_b32 v[34:35], v115 offset0:130 offset1:131
	ds_read2_b32 v[36:37], v115 offset0:136 offset1:137
	ds_read2_b32 v[38:39], v115 offset0:138 offset1:139
	ds_read2_b32 v[40:41], v115 offset0:144 offset1:145
	ds_read2_b32 v[42:43], v115 offset0:146 offset1:147
	ds_read2_b32 v[44:45], v115 offset0:152 offset1:153
	ds_read2_b32 v[46:47], v115 offset0:154 offset1:155
	ds_read_b128 v[156:159], v248
	ds_read_b128 v[160:163], v248 offset:32
	ds_read_b128 v[164:167], v248 offset:64
	ds_read_b128 v[168:171], v248 offset:96
	ds_read_b64_tr_b16 v[72:73], v231
	ds_read_b64_tr_b16 v[74:75], v231 offset:512
	ds_read_b64_tr_b16 v[76:77], v231 offset:2048
	ds_read_b64_tr_b16 v[78:79], v231 offset:2560
	ds_read_b64_tr_b16 v[220:221], v231 offset:1024
	ds_read_b64_tr_b16 v[222:223], v231 offset:1536
	ds_read_b64_tr_b16 v[224:225], v231 offset:3072
	ds_read_b64_tr_b16 v[226:227], v231 offset:3584
	s_waitcnt lgkmcnt(8)
	v_mfma_f32_32x32x16_bf16 v[32:47], v[156:159], v[48:51], v[32:47]
	v_mfma_f32_32x32x16_bf16 v[32:47], v[160:163], v[52:55], v[32:47]
	v_mfma_f32_32x32x16_bf16 v[32:47], v[164:167], v[56:59], v[32:47]
	v_mfma_f32_32x32x16_bf16 v[32:47], v[168:171], v[60:63], v[32:47]
	s_nop 11
	v_exp_f32_e32 v32, v32
	v_exp_f32_e32 v33, v33
	v_exp_f32_e32 v34, v34
	v_exp_f32_e32 v35, v35
	v_exp_f32_e32 v36, v36
	v_exp_f32_e32 v37, v37
	v_exp_f32_e32 v38, v38
	v_exp_f32_e32 v39, v39
	v_exp_f32_e32 v40, v40
	v_exp_f32_e32 v41, v41
	v_exp_f32_e32 v42, v42
	v_exp_f32_e32 v43, v43
	v_exp_f32_e32 v44, v44
	v_exp_f32_e32 v45, v45
	v_exp_f32_e32 v46, v46
	v_exp_f32_e32 v47, v47
	v_cvt_pk_bf16_f32 v64, v32, v33
	v_cvt_pk_bf16_f32 v65, v34, v35
	v_cvt_pk_bf16_f32 v66, v36, v37
	v_cvt_pk_bf16_f32 v67, v38, v39
	v_cvt_pk_bf16_f32 v68, v40, v41
	v_cvt_pk_bf16_f32 v69, v42, v43
	v_cvt_pk_bf16_f32 v70, v44, v45
	v_cvt_pk_bf16_f32 v71, v46, v47
	v_pk_add_f32 v[232:233], v[232:233], v[32:33]
	v_pk_add_f32 v[232:233], v[232:233], v[34:35]
	v_pk_add_f32 v[232:233], v[232:233], v[36:37]
	v_pk_add_f32 v[232:233], v[232:233], v[38:39]
	v_pk_add_f32 v[232:233], v[232:233], v[40:41]
	v_pk_add_f32 v[232:233], v[232:233], v[42:43]
	v_pk_add_f32 v[232:233], v[232:233], v[44:45]
	v_pk_add_f32 v[232:233], v[232:233], v[46:47]
	s_waitcnt lgkmcnt(0)
	v_mfma_f32_32x32x16_bf16 v[0:15], v[64:67], v[72:75], v[0:15]
	v_mfma_f32_32x32x16_bf16 v[16:31], v[64:67], v[76:79], v[16:31]
	v_mfma_f32_32x32x16_bf16 v[0:15], v[68:71], v[220:223], v[0:15]
	v_mfma_f32_32x32x16_bf16 v[16:31], v[68:71], v[224:227], v[16:31]
	global_load_dwordx4 v[156:159], v235, s[84:85]
	global_load_dwordx4 v[160:163], v236, s[84:85]
	global_load_dwordx4 v[164:167], v237, s[84:85]
	global_load_dwordx4 v[168:171], v238, s[84:85]
	global_load_dwordx4 v[172:175], v100, s[84:85] offset:768
	global_load_dwordx4 v[176:179], v149, s[84:85] offset:768
	global_load_dwordx4 v[180:183], v100, s[84:85] offset:832
	global_load_dwordx4 v[184:187], v149, s[84:85] offset:832
	s_add_u32 s84, s84, 0x30000
	s_addc_u32 s85, s85, 0
	s_waitcnt vmcnt(16)
	ds_write_b128 v247, v[188:191]
	ds_write_b128 v247, v[192:195] offset:1152
	ds_write_b128 v247, v[196:199] offset:2304
	ds_write_b128 v247, v[200:203] offset:3456
	ds_write_b128 v112, v[204:207]
	ds_write_b128 v112, v[208:211] offset:1024
	ds_write_b128 v112, v[212:215] offset:2048
	ds_write_b128 v112, v[216:219] offset:3072
	ds_read2_b32 v[32:33], v115 offset0:160 offset1:161
	ds_read2_b32 v[34:35], v115 offset0:162 offset1:163
	ds_read2_b32 v[36:37], v115 offset0:168 offset1:169
	ds_read2_b32 v[38:39], v115 offset0:170 offset1:171
	ds_read2_b32 v[40:41], v115 offset0:176 offset1:177
	ds_read2_b32 v[42:43], v115 offset0:178 offset1:179
	ds_read2_b32 v[44:45], v115 offset0:184 offset1:185
	ds_read2_b32 v[46:47], v115 offset0:186 offset1:187
	ds_read_b128 v[188:191], v248
	ds_read_b128 v[192:195], v248 offset:32
	ds_read_b128 v[196:199], v248 offset:64
	ds_read_b128 v[200:203], v248 offset:96
	ds_read_b64_tr_b16 v[72:73], v231
	ds_read_b64_tr_b16 v[74:75], v231 offset:512
	ds_read_b64_tr_b16 v[76:77], v231 offset:2048
	ds_read_b64_tr_b16 v[78:79], v231 offset:2560
	ds_read_b64_tr_b16 v[220:221], v231 offset:1024
	ds_read_b64_tr_b16 v[222:223], v231 offset:1536
	ds_read_b64_tr_b16 v[224:225], v231 offset:3072
	ds_read_b64_tr_b16 v[226:227], v231 offset:3584
	s_waitcnt lgkmcnt(8)
	v_mfma_f32_32x32x16_bf16 v[32:47], v[188:191], v[48:51], v[32:47]
	v_mfma_f32_32x32x16_bf16 v[32:47], v[192:195], v[52:55], v[32:47]
	v_mfma_f32_32x32x16_bf16 v[32:47], v[196:199], v[56:59], v[32:47]
	v_mfma_f32_32x32x16_bf16 v[32:47], v[200:203], v[60:63], v[32:47]
	s_nop 11
	v_exp_f32_e32 v32, v32
	v_exp_f32_e32 v33, v33
	v_exp_f32_e32 v34, v34
	v_exp_f32_e32 v35, v35
	v_exp_f32_e32 v36, v36
	v_exp_f32_e32 v37, v37
	v_exp_f32_e32 v38, v38
	v_exp_f32_e32 v39, v39
	v_exp_f32_e32 v40, v40
	v_exp_f32_e32 v41, v41
	v_exp_f32_e32 v42, v42
	v_exp_f32_e32 v43, v43
	v_exp_f32_e32 v44, v44
	v_exp_f32_e32 v45, v45
	v_exp_f32_e32 v46, v46
	v_exp_f32_e32 v47, v47
	v_cvt_pk_bf16_f32 v64, v32, v33
	v_cvt_pk_bf16_f32 v65, v34, v35
	v_cvt_pk_bf16_f32 v66, v36, v37
	v_cvt_pk_bf16_f32 v67, v38, v39
	v_cvt_pk_bf16_f32 v68, v40, v41
	v_cvt_pk_bf16_f32 v69, v42, v43
	v_cvt_pk_bf16_f32 v70, v44, v45
	v_cvt_pk_bf16_f32 v71, v46, v47
	v_pk_add_f32 v[232:233], v[232:233], v[32:33]
	v_pk_add_f32 v[232:233], v[232:233], v[34:35]
	v_pk_add_f32 v[232:233], v[232:233], v[36:37]
	v_pk_add_f32 v[232:233], v[232:233], v[38:39]
	v_pk_add_f32 v[232:233], v[232:233], v[40:41]
	v_pk_add_f32 v[232:233], v[232:233], v[42:43]
	v_pk_add_f32 v[232:233], v[232:233], v[44:45]
	v_pk_add_f32 v[232:233], v[232:233], v[46:47]
	s_waitcnt lgkmcnt(0)
	v_mfma_f32_32x32x16_bf16 v[0:15], v[64:67], v[72:75], v[0:15]
	v_mfma_f32_32x32x16_bf16 v[16:31], v[64:67], v[76:79], v[16:31]
	v_mfma_f32_32x32x16_bf16 v[0:15], v[68:71], v[220:223], v[0:15]
	v_mfma_f32_32x32x16_bf16 v[16:31], v[68:71], v[224:227], v[16:31]
	global_load_dwordx4 v[188:191], v235, s[84:85]
	global_load_dwordx4 v[192:195], v236, s[84:85]
	global_load_dwordx4 v[196:199], v237, s[84:85]
	global_load_dwordx4 v[200:203], v238, s[84:85]
	global_load_dwordx4 v[204:207], v100, s[84:85] offset:768
	global_load_dwordx4 v[208:211], v149, s[84:85] offset:768
	global_load_dwordx4 v[212:215], v100, s[84:85] offset:832
	global_load_dwordx4 v[216:219], v149, s[84:85] offset:832
	s_add_u32 s84, s84, 0x30000
	s_addc_u32 s85, s85, 0
	s_waitcnt vmcnt(16)
	ds_write_b128 v247, v[116:119]
	ds_write_b128 v247, v[120:123] offset:1152
	ds_write_b128 v247, v[124:127] offset:2304
	ds_write_b128 v247, v[128:131] offset:3456
	ds_write_b128 v112, v[132:135]
	ds_write_b128 v112, v[136:139] offset:1024
	ds_write_b128 v112, v[140:143] offset:2048
	ds_write_b128 v112, v[144:147] offset:3072
	ds_read2_b32 v[32:33], v115 offset0:192 offset1:193
	ds_read2_b32 v[34:35], v115 offset0:194 offset1:195
	ds_read2_b32 v[36:37], v115 offset0:200 offset1:201
	ds_read2_b32 v[38:39], v115 offset0:202 offset1:203
	ds_read2_b32 v[40:41], v115 offset0:208 offset1:209
	ds_read2_b32 v[42:43], v115 offset0:210 offset1:211
	ds_read2_b32 v[44:45], v115 offset0:216 offset1:217
	ds_read2_b32 v[46:47], v115 offset0:218 offset1:219
	ds_read_b128 v[116:119], v248
	ds_read_b128 v[120:123], v248 offset:32
	ds_read_b128 v[124:127], v248 offset:64
	ds_read_b128 v[128:131], v248 offset:96
	ds_read_b64_tr_b16 v[72:73], v231
	ds_read_b64_tr_b16 v[74:75], v231 offset:512
	ds_read_b64_tr_b16 v[76:77], v231 offset:2048
	ds_read_b64_tr_b16 v[78:79], v231 offset:2560
	ds_read_b64_tr_b16 v[220:221], v231 offset:1024
	ds_read_b64_tr_b16 v[222:223], v231 offset:1536
	ds_read_b64_tr_b16 v[224:225], v231 offset:3072
	ds_read_b64_tr_b16 v[226:227], v231 offset:3584
	s_waitcnt lgkmcnt(8)
	v_mfma_f32_32x32x16_bf16 v[32:47], v[116:119], v[48:51], v[32:47]
	v_mfma_f32_32x32x16_bf16 v[32:47], v[120:123], v[52:55], v[32:47]
	v_mfma_f32_32x32x16_bf16 v[32:47], v[124:127], v[56:59], v[32:47]
	v_mfma_f32_32x32x16_bf16 v[32:47], v[128:131], v[60:63], v[32:47]
	s_nop 11
	v_exp_f32_e32 v32, v32
	v_exp_f32_e32 v33, v33
	v_exp_f32_e32 v34, v34
	v_exp_f32_e32 v35, v35
	v_exp_f32_e32 v36, v36
	v_exp_f32_e32 v37, v37
	v_exp_f32_e32 v38, v38
	v_exp_f32_e32 v39, v39
	v_exp_f32_e32 v40, v40
	v_exp_f32_e32 v41, v41
	v_exp_f32_e32 v42, v42
	v_exp_f32_e32 v43, v43
	v_exp_f32_e32 v44, v44
	v_exp_f32_e32 v45, v45
	v_exp_f32_e32 v46, v46
	v_exp_f32_e32 v47, v47
	v_cvt_pk_bf16_f32 v64, v32, v33
	v_cvt_pk_bf16_f32 v65, v34, v35
	v_cvt_pk_bf16_f32 v66, v36, v37
	v_cvt_pk_bf16_f32 v67, v38, v39
	v_cvt_pk_bf16_f32 v68, v40, v41
	v_cvt_pk_bf16_f32 v69, v42, v43
	v_cvt_pk_bf16_f32 v70, v44, v45
	v_cvt_pk_bf16_f32 v71, v46, v47
	v_pk_add_f32 v[232:233], v[232:233], v[32:33]
	v_pk_add_f32 v[232:233], v[232:233], v[34:35]
	v_pk_add_f32 v[232:233], v[232:233], v[36:37]
	v_pk_add_f32 v[232:233], v[232:233], v[38:39]
	v_pk_add_f32 v[232:233], v[232:233], v[40:41]
	v_pk_add_f32 v[232:233], v[232:233], v[42:43]
	v_pk_add_f32 v[232:233], v[232:233], v[44:45]
	v_pk_add_f32 v[232:233], v[232:233], v[46:47]
	s_waitcnt lgkmcnt(0)
	v_mfma_f32_32x32x16_bf16 v[0:15], v[64:67], v[72:75], v[0:15]
	v_mfma_f32_32x32x16_bf16 v[16:31], v[64:67], v[76:79], v[16:31]
	v_mfma_f32_32x32x16_bf16 v[0:15], v[68:71], v[220:223], v[0:15]
	v_mfma_f32_32x32x16_bf16 v[16:31], v[68:71], v[224:227], v[16:31]
	global_load_dwordx4 v[116:119], v235, s[84:85]
	global_load_dwordx4 v[120:123], v236, s[84:85]
	global_load_dwordx4 v[124:127], v237, s[84:85]
	global_load_dwordx4 v[128:131], v238, s[84:85]
	global_load_dwordx4 v[132:135], v100, s[84:85] offset:768
	global_load_dwordx4 v[136:139], v149, s[84:85] offset:768
	global_load_dwordx4 v[140:143], v100, s[84:85] offset:832
	global_load_dwordx4 v[144:147], v149, s[84:85] offset:832
	s_add_u32 s84, s84, 0x30000
	s_addc_u32 s85, s85, 0
	s_waitcnt vmcnt(16)
	ds_write_b128 v247, v[156:159]
	ds_write_b128 v247, v[160:163] offset:1152
	ds_write_b128 v247, v[164:167] offset:2304
	ds_write_b128 v247, v[168:171] offset:3456
	ds_write_b128 v112, v[172:175]
	ds_write_b128 v112, v[176:179] offset:1024
	ds_write_b128 v112, v[180:183] offset:2048
	ds_write_b128 v112, v[184:187] offset:3072
	ds_read2_b32 v[32:33], v115 offset0:224 offset1:225
	ds_read2_b32 v[34:35], v115 offset0:226 offset1:227
	ds_read2_b32 v[36:37], v115 offset0:232 offset1:233
	ds_read2_b32 v[38:39], v115 offset0:234 offset1:235
	ds_read2_b32 v[40:41], v115 offset0:240 offset1:241
	ds_read2_b32 v[42:43], v115 offset0:242 offset1:243
	ds_read2_b32 v[44:45], v115 offset0:248 offset1:249
	ds_read2_b32 v[46:47], v115 offset0:250 offset1:251
	ds_read_b128 v[156:159], v248
	ds_read_b128 v[160:163], v248 offset:32
	ds_read_b128 v[164:167], v248 offset:64
	ds_read_b128 v[168:171], v248 offset:96
	ds_read_b64_tr_b16 v[72:73], v231
	ds_read_b64_tr_b16 v[74:75], v231 offset:512
	ds_read_b64_tr_b16 v[76:77], v231 offset:2048
	ds_read_b64_tr_b16 v[78:79], v231 offset:2560
	ds_read_b64_tr_b16 v[220:221], v231 offset:1024
	ds_read_b64_tr_b16 v[222:223], v231 offset:1536
	ds_read_b64_tr_b16 v[224:225], v231 offset:3072
	ds_read_b64_tr_b16 v[226:227], v231 offset:3584
	s_waitcnt lgkmcnt(8)
	v_mfma_f32_32x32x16_bf16 v[32:47], v[156:159], v[48:51], v[32:47]
	v_mfma_f32_32x32x16_bf16 v[32:47], v[160:163], v[52:55], v[32:47]
	v_mfma_f32_32x32x16_bf16 v[32:47], v[164:167], v[56:59], v[32:47]
	v_mfma_f32_32x32x16_bf16 v[32:47], v[168:171], v[60:63], v[32:47]
	s_nop 11
	v_exp_f32_e32 v32, v32
	v_exp_f32_e32 v33, v33
	v_exp_f32_e32 v34, v34
	v_exp_f32_e32 v35, v35
	v_exp_f32_e32 v36, v36
	v_exp_f32_e32 v37, v37
	v_exp_f32_e32 v38, v38
	v_exp_f32_e32 v39, v39
	v_exp_f32_e32 v40, v40
	v_exp_f32_e32 v41, v41
	v_exp_f32_e32 v42, v42
	v_exp_f32_e32 v43, v43
	v_exp_f32_e32 v44, v44
	v_exp_f32_e32 v45, v45
	v_exp_f32_e32 v46, v46
	v_exp_f32_e32 v47, v47
	v_cvt_pk_bf16_f32 v64, v32, v33
	v_cvt_pk_bf16_f32 v65, v34, v35
	v_cvt_pk_bf16_f32 v66, v36, v37
	v_cvt_pk_bf16_f32 v67, v38, v39
	v_cvt_pk_bf16_f32 v68, v40, v41
	v_cvt_pk_bf16_f32 v69, v42, v43
	v_cvt_pk_bf16_f32 v70, v44, v45
	v_cvt_pk_bf16_f32 v71, v46, v47
	v_pk_add_f32 v[232:233], v[232:233], v[32:33]
	v_pk_add_f32 v[232:233], v[232:233], v[34:35]
	v_pk_add_f32 v[232:233], v[232:233], v[36:37]
	v_pk_add_f32 v[232:233], v[232:233], v[38:39]
	v_pk_add_f32 v[232:233], v[232:233], v[40:41]
	v_pk_add_f32 v[232:233], v[232:233], v[42:43]
	v_pk_add_f32 v[232:233], v[232:233], v[44:45]
	v_pk_add_f32 v[232:233], v[232:233], v[46:47]
	s_waitcnt lgkmcnt(0)
	v_mfma_f32_32x32x16_bf16 v[0:15], v[64:67], v[72:75], v[0:15]
	v_mfma_f32_32x32x16_bf16 v[16:31], v[64:67], v[76:79], v[16:31]
	v_mfma_f32_32x32x16_bf16 v[0:15], v[68:71], v[220:223], v[0:15]
	v_mfma_f32_32x32x16_bf16 v[16:31], v[68:71], v[224:227], v[16:31]
	global_load_dwordx4 v[156:159], v235, s[84:85]
	global_load_dwordx4 v[160:163], v236, s[84:85]
	global_load_dwordx4 v[164:167], v237, s[84:85]
	global_load_dwordx4 v[168:171], v238, s[84:85]
	global_load_dwordx4 v[172:175], v100, s[84:85] offset:768
	global_load_dwordx4 v[176:179], v149, s[84:85] offset:768
	global_load_dwordx4 v[180:183], v100, s[84:85] offset:832
	global_load_dwordx4 v[184:187], v149, s[84:85] offset:832
	s_add_u32 s84, s84, 0x30000
	s_addc_u32 s85, s85, 0
	s_waitcnt vmcnt(16)
	ds_write_b128 v247, v[188:191]
	ds_write_b128 v247, v[192:195] offset:1152
	ds_write_b128 v247, v[196:199] offset:2304
	ds_write_b128 v247, v[200:203] offset:3456
	ds_write_b128 v112, v[204:207]
	ds_write_b128 v112, v[208:211] offset:1024
	ds_write_b128 v112, v[212:215] offset:2048
	ds_write_b128 v112, v[216:219] offset:3072
	v_add_u32_e32 v115, 0x400, v115
	ds_read2_b32 v[32:33], v115 offset0:0 offset1:1
	ds_read2_b32 v[34:35], v115 offset0:2 offset1:3
	ds_read2_b32 v[36:37], v115 offset0:8 offset1:9
	ds_read2_b32 v[38:39], v115 offset0:10 offset1:11
	ds_read2_b32 v[40:41], v115 offset0:16 offset1:17
	ds_read2_b32 v[42:43], v115 offset0:18 offset1:19
	ds_read2_b32 v[44:45], v115 offset0:24 offset1:25
	ds_read2_b32 v[46:47], v115 offset0:26 offset1:27
	ds_read_b128 v[188:191], v248
	ds_read_b128 v[192:195], v248 offset:32
	ds_read_b128 v[196:199], v248 offset:64
	ds_read_b128 v[200:203], v248 offset:96
	ds_read_b64_tr_b16 v[72:73], v231
	ds_read_b64_tr_b16 v[74:75], v231 offset:512
	ds_read_b64_tr_b16 v[76:77], v231 offset:2048
	ds_read_b64_tr_b16 v[78:79], v231 offset:2560
	ds_read_b64_tr_b16 v[220:221], v231 offset:1024
	ds_read_b64_tr_b16 v[222:223], v231 offset:1536
	ds_read_b64_tr_b16 v[224:225], v231 offset:3072
	ds_read_b64_tr_b16 v[226:227], v231 offset:3584
	s_waitcnt lgkmcnt(8)
	v_mfma_f32_32x32x16_bf16 v[32:47], v[188:191], v[48:51], v[32:47]
	v_mfma_f32_32x32x16_bf16 v[32:47], v[192:195], v[52:55], v[32:47]
	v_mfma_f32_32x32x16_bf16 v[32:47], v[196:199], v[56:59], v[32:47]
	v_mfma_f32_32x32x16_bf16 v[32:47], v[200:203], v[60:63], v[32:47]
	s_nop 11
	v_exp_f32_e32 v32, v32
	v_exp_f32_e32 v33, v33
	v_exp_f32_e32 v34, v34
	v_exp_f32_e32 v35, v35
	v_exp_f32_e32 v36, v36
	v_exp_f32_e32 v37, v37
	v_exp_f32_e32 v38, v38
	v_exp_f32_e32 v39, v39
	v_exp_f32_e32 v40, v40
	v_exp_f32_e32 v41, v41
	v_exp_f32_e32 v42, v42
	v_exp_f32_e32 v43, v43
	v_exp_f32_e32 v44, v44
	v_exp_f32_e32 v45, v45
	v_exp_f32_e32 v46, v46
	v_exp_f32_e32 v47, v47
	v_cvt_pk_bf16_f32 v64, v32, v33
	v_cvt_pk_bf16_f32 v65, v34, v35
	v_cvt_pk_bf16_f32 v66, v36, v37
	v_cvt_pk_bf16_f32 v67, v38, v39
	v_cvt_pk_bf16_f32 v68, v40, v41
	v_cvt_pk_bf16_f32 v69, v42, v43
	v_cvt_pk_bf16_f32 v70, v44, v45
	v_cvt_pk_bf16_f32 v71, v46, v47
	v_pk_add_f32 v[232:233], v[232:233], v[32:33]
	v_pk_add_f32 v[232:233], v[232:233], v[34:35]
	v_pk_add_f32 v[232:233], v[232:233], v[36:37]
	v_pk_add_f32 v[232:233], v[232:233], v[38:39]
	v_pk_add_f32 v[232:233], v[232:233], v[40:41]
	v_pk_add_f32 v[232:233], v[232:233], v[42:43]
	v_pk_add_f32 v[232:233], v[232:233], v[44:45]
	v_pk_add_f32 v[232:233], v[232:233], v[46:47]
	s_waitcnt lgkmcnt(0)
	v_mfma_f32_32x32x16_bf16 v[0:15], v[64:67], v[72:75], v[0:15]
	v_mfma_f32_32x32x16_bf16 v[16:31], v[64:67], v[76:79], v[16:31]
	v_mfma_f32_32x32x16_bf16 v[0:15], v[68:71], v[220:223], v[0:15]
	v_mfma_f32_32x32x16_bf16 v[16:31], v[68:71], v[224:227], v[16:31]
	global_load_dwordx4 v[188:191], v235, s[84:85]
	global_load_dwordx4 v[192:195], v236, s[84:85]
	global_load_dwordx4 v[196:199], v237, s[84:85]
	global_load_dwordx4 v[200:203], v238, s[84:85]
	global_load_dwordx4 v[204:207], v100, s[84:85] offset:768
	global_load_dwordx4 v[208:211], v149, s[84:85] offset:768
	global_load_dwordx4 v[212:215], v100, s[84:85] offset:832
	global_load_dwordx4 v[216:219], v149, s[84:85] offset:832
	s_add_u32 s84, s84, 0x30000
	s_addc_u32 s85, s85, 0
	s_waitcnt vmcnt(16)
	ds_write_b128 v247, v[116:119]
	ds_write_b128 v247, v[120:123] offset:1152
	ds_write_b128 v247, v[124:127] offset:2304
	ds_write_b128 v247, v[128:131] offset:3456
	ds_write_b128 v112, v[132:135]
	ds_write_b128 v112, v[136:139] offset:1024
	ds_write_b128 v112, v[140:143] offset:2048
	ds_write_b128 v112, v[144:147] offset:3072
	ds_read2_b32 v[32:33], v115 offset0:32 offset1:33
	ds_read2_b32 v[34:35], v115 offset0:34 offset1:35
	ds_read2_b32 v[36:37], v115 offset0:40 offset1:41
	ds_read2_b32 v[38:39], v115 offset0:42 offset1:43
	ds_read2_b32 v[40:41], v115 offset0:48 offset1:49
	ds_read2_b32 v[42:43], v115 offset0:50 offset1:51
	ds_read2_b32 v[44:45], v115 offset0:56 offset1:57
	ds_read2_b32 v[46:47], v115 offset0:58 offset1:59
	ds_read_b128 v[116:119], v248
	ds_read_b128 v[120:123], v248 offset:32
	ds_read_b128 v[124:127], v248 offset:64
	ds_read_b128 v[128:131], v248 offset:96
	ds_read_b64_tr_b16 v[72:73], v231
	ds_read_b64_tr_b16 v[74:75], v231 offset:512
	ds_read_b64_tr_b16 v[76:77], v231 offset:2048
	ds_read_b64_tr_b16 v[78:79], v231 offset:2560
	ds_read_b64_tr_b16 v[220:221], v231 offset:1024
	ds_read_b64_tr_b16 v[222:223], v231 offset:1536
	ds_read_b64_tr_b16 v[224:225], v231 offset:3072
	ds_read_b64_tr_b16 v[226:227], v231 offset:3584
	s_waitcnt lgkmcnt(8)
	v_mfma_f32_32x32x16_bf16 v[32:47], v[116:119], v[48:51], v[32:47]
	v_mfma_f32_32x32x16_bf16 v[32:47], v[120:123], v[52:55], v[32:47]
	v_mfma_f32_32x32x16_bf16 v[32:47], v[124:127], v[56:59], v[32:47]
	v_mfma_f32_32x32x16_bf16 v[32:47], v[128:131], v[60:63], v[32:47]
	s_nop 11
	v_exp_f32_e32 v32, v32
	v_exp_f32_e32 v33, v33
	v_exp_f32_e32 v34, v34
	v_exp_f32_e32 v35, v35
	v_exp_f32_e32 v36, v36
	v_exp_f32_e32 v37, v37
	v_exp_f32_e32 v38, v38
	v_exp_f32_e32 v39, v39
	v_exp_f32_e32 v40, v40
	v_exp_f32_e32 v41, v41
	v_exp_f32_e32 v42, v42
	v_exp_f32_e32 v43, v43
	v_exp_f32_e32 v44, v44
	v_exp_f32_e32 v45, v45
	v_exp_f32_e32 v46, v46
	v_exp_f32_e32 v47, v47
	v_cvt_pk_bf16_f32 v64, v32, v33
	v_cvt_pk_bf16_f32 v65, v34, v35
	v_cvt_pk_bf16_f32 v66, v36, v37
	v_cvt_pk_bf16_f32 v67, v38, v39
	v_cvt_pk_bf16_f32 v68, v40, v41
	v_cvt_pk_bf16_f32 v69, v42, v43
	v_cvt_pk_bf16_f32 v70, v44, v45
	v_cvt_pk_bf16_f32 v71, v46, v47
	v_pk_add_f32 v[232:233], v[232:233], v[32:33]
	v_pk_add_f32 v[232:233], v[232:233], v[34:35]
	v_pk_add_f32 v[232:233], v[232:233], v[36:37]
	v_pk_add_f32 v[232:233], v[232:233], v[38:39]
	v_pk_add_f32 v[232:233], v[232:233], v[40:41]
	v_pk_add_f32 v[232:233], v[232:233], v[42:43]
	v_pk_add_f32 v[232:233], v[232:233], v[44:45]
	v_pk_add_f32 v[232:233], v[232:233], v[46:47]
	s_waitcnt lgkmcnt(0)
	v_mfma_f32_32x32x16_bf16 v[0:15], v[64:67], v[72:75], v[0:15]
	v_mfma_f32_32x32x16_bf16 v[16:31], v[64:67], v[76:79], v[16:31]
	v_mfma_f32_32x32x16_bf16 v[0:15], v[68:71], v[220:223], v[0:15]
	v_mfma_f32_32x32x16_bf16 v[16:31], v[68:71], v[224:227], v[16:31]
	global_load_dwordx4 v[116:119], v235, s[84:85]
	global_load_dwordx4 v[120:123], v236, s[84:85]
	global_load_dwordx4 v[124:127], v237, s[84:85]
	global_load_dwordx4 v[128:131], v238, s[84:85]
	global_load_dwordx4 v[132:135], v100, s[84:85] offset:768
	global_load_dwordx4 v[136:139], v149, s[84:85] offset:768
	global_load_dwordx4 v[140:143], v100, s[84:85] offset:832
	global_load_dwordx4 v[144:147], v149, s[84:85] offset:832
	s_add_u32 s84, s84, 0x30000
	s_addc_u32 s85, s85, 0
	s_waitcnt vmcnt(16)
	ds_write_b128 v247, v[156:159]
	ds_write_b128 v247, v[160:163] offset:1152
	ds_write_b128 v247, v[164:167] offset:2304
	ds_write_b128 v247, v[168:171] offset:3456
	ds_write_b128 v112, v[172:175]
	ds_write_b128 v112, v[176:179] offset:1024
	ds_write_b128 v112, v[180:183] offset:2048
	ds_write_b128 v112, v[184:187] offset:3072
	ds_read2_b32 v[32:33], v115 offset0:64 offset1:65
	ds_read2_b32 v[34:35], v115 offset0:66 offset1:67
	ds_read2_b32 v[36:37], v115 offset0:72 offset1:73
	ds_read2_b32 v[38:39], v115 offset0:74 offset1:75
	ds_read2_b32 v[40:41], v115 offset0:80 offset1:81
	ds_read2_b32 v[42:43], v115 offset0:82 offset1:83
	ds_read2_b32 v[44:45], v115 offset0:88 offset1:89
	ds_read2_b32 v[46:47], v115 offset0:90 offset1:91
	ds_read_b128 v[156:159], v248
	ds_read_b128 v[160:163], v248 offset:32
	ds_read_b128 v[164:167], v248 offset:64
	ds_read_b128 v[168:171], v248 offset:96
	ds_read_b64_tr_b16 v[72:73], v231
	ds_read_b64_tr_b16 v[74:75], v231 offset:512
	ds_read_b64_tr_b16 v[76:77], v231 offset:2048
	ds_read_b64_tr_b16 v[78:79], v231 offset:2560
	ds_read_b64_tr_b16 v[220:221], v231 offset:1024
	ds_read_b64_tr_b16 v[222:223], v231 offset:1536
	ds_read_b64_tr_b16 v[224:225], v231 offset:3072
	ds_read_b64_tr_b16 v[226:227], v231 offset:3584
	s_waitcnt lgkmcnt(8)
	v_mfma_f32_32x32x16_bf16 v[32:47], v[156:159], v[48:51], v[32:47]
	v_mfma_f32_32x32x16_bf16 v[32:47], v[160:163], v[52:55], v[32:47]
	v_mfma_f32_32x32x16_bf16 v[32:47], v[164:167], v[56:59], v[32:47]
	v_mfma_f32_32x32x16_bf16 v[32:47], v[168:171], v[60:63], v[32:47]
	s_nop 11
	v_exp_f32_e32 v32, v32
	v_exp_f32_e32 v33, v33
	v_exp_f32_e32 v34, v34
	v_exp_f32_e32 v35, v35
	v_exp_f32_e32 v36, v36
	v_exp_f32_e32 v37, v37
	v_exp_f32_e32 v38, v38
	v_exp_f32_e32 v39, v39
	v_exp_f32_e32 v40, v40
	v_exp_f32_e32 v41, v41
	v_exp_f32_e32 v42, v42
	v_exp_f32_e32 v43, v43
	v_exp_f32_e32 v44, v44
	v_exp_f32_e32 v45, v45
	v_exp_f32_e32 v46, v46
	v_exp_f32_e32 v47, v47
	v_cvt_pk_bf16_f32 v64, v32, v33
	v_cvt_pk_bf16_f32 v65, v34, v35
	v_cvt_pk_bf16_f32 v66, v36, v37
	v_cvt_pk_bf16_f32 v67, v38, v39
	v_cvt_pk_bf16_f32 v68, v40, v41
	v_cvt_pk_bf16_f32 v69, v42, v43
	v_cvt_pk_bf16_f32 v70, v44, v45
	v_cvt_pk_bf16_f32 v71, v46, v47
	v_pk_add_f32 v[232:233], v[232:233], v[32:33]
	v_pk_add_f32 v[232:233], v[232:233], v[34:35]
	v_pk_add_f32 v[232:233], v[232:233], v[36:37]
	v_pk_add_f32 v[232:233], v[232:233], v[38:39]
	v_pk_add_f32 v[232:233], v[232:233], v[40:41]
	v_pk_add_f32 v[232:233], v[232:233], v[42:43]
	v_pk_add_f32 v[232:233], v[232:233], v[44:45]
	v_pk_add_f32 v[232:233], v[232:233], v[46:47]
	s_waitcnt lgkmcnt(0)
	v_mfma_f32_32x32x16_bf16 v[0:15], v[64:67], v[72:75], v[0:15]
	v_mfma_f32_32x32x16_bf16 v[16:31], v[64:67], v[76:79], v[16:31]
	v_mfma_f32_32x32x16_bf16 v[0:15], v[68:71], v[220:223], v[0:15]
	v_mfma_f32_32x32x16_bf16 v[16:31], v[68:71], v[224:227], v[16:31]
	global_load_dwordx4 v[156:159], v235, s[84:85]
	global_load_dwordx4 v[160:163], v236, s[84:85]
	global_load_dwordx4 v[164:167], v237, s[84:85]
	global_load_dwordx4 v[168:171], v238, s[84:85]
	global_load_dwordx4 v[172:175], v100, s[84:85] offset:768
	global_load_dwordx4 v[176:179], v149, s[84:85] offset:768
	global_load_dwordx4 v[180:183], v100, s[84:85] offset:832
	global_load_dwordx4 v[184:187], v149, s[84:85] offset:832
	s_add_u32 s84, s84, 0x30000
	s_addc_u32 s85, s85, 0
	s_waitcnt vmcnt(16)
	ds_write_b128 v247, v[188:191]
	ds_write_b128 v247, v[192:195] offset:1152
	ds_write_b128 v247, v[196:199] offset:2304
	ds_write_b128 v247, v[200:203] offset:3456
	ds_write_b128 v112, v[204:207]
	ds_write_b128 v112, v[208:211] offset:1024
	ds_write_b128 v112, v[212:215] offset:2048
	ds_write_b128 v112, v[216:219] offset:3072
	ds_read2_b32 v[32:33], v115 offset0:96 offset1:97
	ds_read2_b32 v[34:35], v115 offset0:98 offset1:99
	ds_read2_b32 v[36:37], v115 offset0:104 offset1:105
	ds_read2_b32 v[38:39], v115 offset0:106 offset1:107
	ds_read2_b32 v[40:41], v115 offset0:112 offset1:113
	ds_read2_b32 v[42:43], v115 offset0:114 offset1:115
	ds_read2_b32 v[44:45], v115 offset0:120 offset1:121
	ds_read2_b32 v[46:47], v115 offset0:122 offset1:123
	ds_read_b128 v[188:191], v248
	ds_read_b128 v[192:195], v248 offset:32
	ds_read_b128 v[196:199], v248 offset:64
	ds_read_b128 v[200:203], v248 offset:96
	ds_read_b64_tr_b16 v[72:73], v231
	ds_read_b64_tr_b16 v[74:75], v231 offset:512
	ds_read_b64_tr_b16 v[76:77], v231 offset:2048
	ds_read_b64_tr_b16 v[78:79], v231 offset:2560
	ds_read_b64_tr_b16 v[220:221], v231 offset:1024
	ds_read_b64_tr_b16 v[222:223], v231 offset:1536
	ds_read_b64_tr_b16 v[224:225], v231 offset:3072
	ds_read_b64_tr_b16 v[226:227], v231 offset:3584
	s_waitcnt lgkmcnt(8)
	v_mfma_f32_32x32x16_bf16 v[32:47], v[188:191], v[48:51], v[32:47]
	v_mfma_f32_32x32x16_bf16 v[32:47], v[192:195], v[52:55], v[32:47]
	v_mfma_f32_32x32x16_bf16 v[32:47], v[196:199], v[56:59], v[32:47]
	v_mfma_f32_32x32x16_bf16 v[32:47], v[200:203], v[60:63], v[32:47]
	s_nop 11
	v_exp_f32_e32 v32, v32
	v_exp_f32_e32 v33, v33
	v_exp_f32_e32 v34, v34
	v_exp_f32_e32 v35, v35
	v_exp_f32_e32 v36, v36
	v_exp_f32_e32 v37, v37
	v_exp_f32_e32 v38, v38
	v_exp_f32_e32 v39, v39
	v_exp_f32_e32 v40, v40
	v_exp_f32_e32 v41, v41
	v_exp_f32_e32 v42, v42
	v_exp_f32_e32 v43, v43
	v_exp_f32_e32 v44, v44
	v_exp_f32_e32 v45, v45
	v_exp_f32_e32 v46, v46
	v_exp_f32_e32 v47, v47
	v_cvt_pk_bf16_f32 v64, v32, v33
	v_cvt_pk_bf16_f32 v65, v34, v35
	v_cvt_pk_bf16_f32 v66, v36, v37
	v_cvt_pk_bf16_f32 v67, v38, v39
	v_cvt_pk_bf16_f32 v68, v40, v41
	v_cvt_pk_bf16_f32 v69, v42, v43
	v_cvt_pk_bf16_f32 v70, v44, v45
	v_cvt_pk_bf16_f32 v71, v46, v47
	v_pk_add_f32 v[232:233], v[232:233], v[32:33]
	v_pk_add_f32 v[232:233], v[232:233], v[34:35]
	v_pk_add_f32 v[232:233], v[232:233], v[36:37]
	v_pk_add_f32 v[232:233], v[232:233], v[38:39]
	v_pk_add_f32 v[232:233], v[232:233], v[40:41]
	v_pk_add_f32 v[232:233], v[232:233], v[42:43]
	v_pk_add_f32 v[232:233], v[232:233], v[44:45]
	v_pk_add_f32 v[232:233], v[232:233], v[46:47]
	s_waitcnt lgkmcnt(0)
	v_mfma_f32_32x32x16_bf16 v[0:15], v[64:67], v[72:75], v[0:15]
	v_mfma_f32_32x32x16_bf16 v[16:31], v[64:67], v[76:79], v[16:31]
	v_mfma_f32_32x32x16_bf16 v[0:15], v[68:71], v[220:223], v[0:15]
	v_mfma_f32_32x32x16_bf16 v[16:31], v[68:71], v[224:227], v[16:31]
	global_load_dwordx4 v[188:191], v235, s[84:85]
	global_load_dwordx4 v[192:195], v236, s[84:85]
	global_load_dwordx4 v[196:199], v237, s[84:85]
	global_load_dwordx4 v[200:203], v238, s[84:85]
	global_load_dwordx4 v[204:207], v100, s[84:85] offset:768
	global_load_dwordx4 v[208:211], v149, s[84:85] offset:768
	global_load_dwordx4 v[212:215], v100, s[84:85] offset:832
	global_load_dwordx4 v[216:219], v149, s[84:85] offset:832
	s_add_u32 s84, s84, 0x30000
	s_addc_u32 s85, s85, 0
	s_waitcnt vmcnt(16)
	ds_write_b128 v247, v[116:119]
	ds_write_b128 v247, v[120:123] offset:1152
	ds_write_b128 v247, v[124:127] offset:2304
	ds_write_b128 v247, v[128:131] offset:3456
	ds_write_b128 v112, v[132:135]
	ds_write_b128 v112, v[136:139] offset:1024
	ds_write_b128 v112, v[140:143] offset:2048
	ds_write_b128 v112, v[144:147] offset:3072
	ds_read2_b32 v[32:33], v115 offset0:128 offset1:129
	ds_read2_b32 v[34:35], v115 offset0:130 offset1:131
	ds_read2_b32 v[36:37], v115 offset0:136 offset1:137
	ds_read2_b32 v[38:39], v115 offset0:138 offset1:139
	ds_read2_b32 v[40:41], v115 offset0:144 offset1:145
	ds_read2_b32 v[42:43], v115 offset0:146 offset1:147
	ds_read2_b32 v[44:45], v115 offset0:152 offset1:153
	ds_read2_b32 v[46:47], v115 offset0:154 offset1:155
	ds_read_b128 v[116:119], v248
	ds_read_b128 v[120:123], v248 offset:32
	ds_read_b128 v[124:127], v248 offset:64
	ds_read_b128 v[128:131], v248 offset:96
	ds_read_b64_tr_b16 v[72:73], v231
	ds_read_b64_tr_b16 v[74:75], v231 offset:512
	ds_read_b64_tr_b16 v[76:77], v231 offset:2048
	ds_read_b64_tr_b16 v[78:79], v231 offset:2560
	ds_read_b64_tr_b16 v[220:221], v231 offset:1024
	ds_read_b64_tr_b16 v[222:223], v231 offset:1536
	ds_read_b64_tr_b16 v[224:225], v231 offset:3072
	ds_read_b64_tr_b16 v[226:227], v231 offset:3584
	s_waitcnt lgkmcnt(8)
	v_mfma_f32_32x32x16_bf16 v[32:47], v[116:119], v[48:51], v[32:47]
	v_mfma_f32_32x32x16_bf16 v[32:47], v[120:123], v[52:55], v[32:47]
	v_mfma_f32_32x32x16_bf16 v[32:47], v[124:127], v[56:59], v[32:47]
	v_mfma_f32_32x32x16_bf16 v[32:47], v[128:131], v[60:63], v[32:47]
	s_nop 11
	v_exp_f32_e32 v32, v32
	v_exp_f32_e32 v33, v33
	v_exp_f32_e32 v34, v34
	v_exp_f32_e32 v35, v35
	v_exp_f32_e32 v36, v36
	v_exp_f32_e32 v37, v37
	v_exp_f32_e32 v38, v38
	v_exp_f32_e32 v39, v39
	v_exp_f32_e32 v40, v40
	v_exp_f32_e32 v41, v41
	v_exp_f32_e32 v42, v42
	v_exp_f32_e32 v43, v43
	v_exp_f32_e32 v44, v44
	v_exp_f32_e32 v45, v45
	v_exp_f32_e32 v46, v46
	v_exp_f32_e32 v47, v47
	v_cvt_pk_bf16_f32 v64, v32, v33
	v_cvt_pk_bf16_f32 v65, v34, v35
	v_cvt_pk_bf16_f32 v66, v36, v37
	v_cvt_pk_bf16_f32 v67, v38, v39
	v_cvt_pk_bf16_f32 v68, v40, v41
	v_cvt_pk_bf16_f32 v69, v42, v43
	v_cvt_pk_bf16_f32 v70, v44, v45
	v_cvt_pk_bf16_f32 v71, v46, v47
	v_pk_add_f32 v[232:233], v[232:233], v[32:33]
	v_pk_add_f32 v[232:233], v[232:233], v[34:35]
	v_pk_add_f32 v[232:233], v[232:233], v[36:37]
	v_pk_add_f32 v[232:233], v[232:233], v[38:39]
	v_pk_add_f32 v[232:233], v[232:233], v[40:41]
	v_pk_add_f32 v[232:233], v[232:233], v[42:43]
	v_pk_add_f32 v[232:233], v[232:233], v[44:45]
	v_pk_add_f32 v[232:233], v[232:233], v[46:47]
	s_waitcnt lgkmcnt(0)
	v_mfma_f32_32x32x16_bf16 v[0:15], v[64:67], v[72:75], v[0:15]
	v_mfma_f32_32x32x16_bf16 v[16:31], v[64:67], v[76:79], v[16:31]
	v_mfma_f32_32x32x16_bf16 v[0:15], v[68:71], v[220:223], v[0:15]
	v_mfma_f32_32x32x16_bf16 v[16:31], v[68:71], v[224:227], v[16:31]
	global_load_dwordx4 v[116:119], v235, s[84:85]
	global_load_dwordx4 v[120:123], v236, s[84:85]
	global_load_dwordx4 v[124:127], v237, s[84:85]
	global_load_dwordx4 v[128:131], v238, s[84:85]
	global_load_dwordx4 v[132:135], v100, s[84:85] offset:768
	global_load_dwordx4 v[136:139], v149, s[84:85] offset:768
	global_load_dwordx4 v[140:143], v100, s[84:85] offset:832
	global_load_dwordx4 v[144:147], v149, s[84:85] offset:832
	s_add_u32 s84, s84, 0x30000
	s_addc_u32 s85, s85, 0
	s_waitcnt vmcnt(16)
	ds_write_b128 v247, v[156:159]
	ds_write_b128 v247, v[160:163] offset:1152
	ds_write_b128 v247, v[164:167] offset:2304
	ds_write_b128 v247, v[168:171] offset:3456
	ds_write_b128 v112, v[172:175]
	ds_write_b128 v112, v[176:179] offset:1024
	ds_write_b128 v112, v[180:183] offset:2048
	ds_write_b128 v112, v[184:187] offset:3072
	ds_read2_b32 v[32:33], v115 offset0:160 offset1:161
	ds_read2_b32 v[34:35], v115 offset0:162 offset1:163
	ds_read2_b32 v[36:37], v115 offset0:168 offset1:169
	ds_read2_b32 v[38:39], v115 offset0:170 offset1:171
	ds_read2_b32 v[40:41], v115 offset0:176 offset1:177
	ds_read2_b32 v[42:43], v115 offset0:178 offset1:179
	ds_read2_b32 v[44:45], v115 offset0:184 offset1:185
	ds_read2_b32 v[46:47], v115 offset0:186 offset1:187
	ds_read_b128 v[156:159], v248
	ds_read_b128 v[160:163], v248 offset:32
	ds_read_b128 v[164:167], v248 offset:64
	ds_read_b128 v[168:171], v248 offset:96
	ds_read_b64_tr_b16 v[72:73], v231
	ds_read_b64_tr_b16 v[74:75], v231 offset:512
	ds_read_b64_tr_b16 v[76:77], v231 offset:2048
	ds_read_b64_tr_b16 v[78:79], v231 offset:2560
	ds_read_b64_tr_b16 v[220:221], v231 offset:1024
	ds_read_b64_tr_b16 v[222:223], v231 offset:1536
	ds_read_b64_tr_b16 v[224:225], v231 offset:3072
	ds_read_b64_tr_b16 v[226:227], v231 offset:3584
	s_waitcnt lgkmcnt(8)
	v_mfma_f32_32x32x16_bf16 v[32:47], v[156:159], v[48:51], v[32:47]
	v_mfma_f32_32x32x16_bf16 v[32:47], v[160:163], v[52:55], v[32:47]
	v_mfma_f32_32x32x16_bf16 v[32:47], v[164:167], v[56:59], v[32:47]
	v_mfma_f32_32x32x16_bf16 v[32:47], v[168:171], v[60:63], v[32:47]
	s_nop 11
	v_exp_f32_e32 v32, v32
	v_exp_f32_e32 v33, v33
	v_exp_f32_e32 v34, v34
	v_exp_f32_e32 v35, v35
	v_exp_f32_e32 v36, v36
	v_exp_f32_e32 v37, v37
	v_exp_f32_e32 v38, v38
	v_exp_f32_e32 v39, v39
	v_exp_f32_e32 v40, v40
	v_exp_f32_e32 v41, v41
	v_exp_f32_e32 v42, v42
	v_exp_f32_e32 v43, v43
	v_exp_f32_e32 v44, v44
	v_exp_f32_e32 v45, v45
	v_exp_f32_e32 v46, v46
	v_exp_f32_e32 v47, v47
	v_cvt_pk_bf16_f32 v64, v32, v33
	v_cvt_pk_bf16_f32 v65, v34, v35
	v_cvt_pk_bf16_f32 v66, v36, v37
	v_cvt_pk_bf16_f32 v67, v38, v39
	v_cvt_pk_bf16_f32 v68, v40, v41
	v_cvt_pk_bf16_f32 v69, v42, v43
	v_cvt_pk_bf16_f32 v70, v44, v45
	v_cvt_pk_bf16_f32 v71, v46, v47
	v_pk_add_f32 v[232:233], v[232:233], v[32:33]
	v_pk_add_f32 v[232:233], v[232:233], v[34:35]
	v_pk_add_f32 v[232:233], v[232:233], v[36:37]
	v_pk_add_f32 v[232:233], v[232:233], v[38:39]
	v_pk_add_f32 v[232:233], v[232:233], v[40:41]
	v_pk_add_f32 v[232:233], v[232:233], v[42:43]
	v_pk_add_f32 v[232:233], v[232:233], v[44:45]
	v_pk_add_f32 v[232:233], v[232:233], v[46:47]
	s_waitcnt lgkmcnt(0)
	v_mfma_f32_32x32x16_bf16 v[0:15], v[64:67], v[72:75], v[0:15]
	v_mfma_f32_32x32x16_bf16 v[16:31], v[64:67], v[76:79], v[16:31]
	v_mfma_f32_32x32x16_bf16 v[0:15], v[68:71], v[220:223], v[0:15]
	v_mfma_f32_32x32x16_bf16 v[16:31], v[68:71], v[224:227], v[16:31]
	global_load_dwordx4 v[156:159], v235, s[84:85]
	global_load_dwordx4 v[160:163], v236, s[84:85]
	global_load_dwordx4 v[164:167], v237, s[84:85]
	global_load_dwordx4 v[168:171], v238, s[84:85]
	global_load_dwordx4 v[172:175], v100, s[84:85] offset:768
	global_load_dwordx4 v[176:179], v149, s[84:85] offset:768
	global_load_dwordx4 v[180:183], v100, s[84:85] offset:832
	global_load_dwordx4 v[184:187], v149, s[84:85] offset:832
	s_add_u32 s84, s84, 0x30000
	s_addc_u32 s85, s85, 0
	s_waitcnt vmcnt(16)
	ds_write_b128 v247, v[188:191]
	ds_write_b128 v247, v[192:195] offset:1152
	ds_write_b128 v247, v[196:199] offset:2304
	ds_write_b128 v247, v[200:203] offset:3456
	ds_write_b128 v112, v[204:207]
	ds_write_b128 v112, v[208:211] offset:1024
	ds_write_b128 v112, v[212:215] offset:2048
	ds_write_b128 v112, v[216:219] offset:3072
	ds_read2_b32 v[32:33], v115 offset0:192 offset1:193
	ds_read2_b32 v[34:35], v115 offset0:194 offset1:195
	ds_read2_b32 v[36:37], v115 offset0:200 offset1:201
	ds_read2_b32 v[38:39], v115 offset0:202 offset1:203
	ds_read2_b32 v[40:41], v115 offset0:208 offset1:209
	ds_read2_b32 v[42:43], v115 offset0:210 offset1:211
	ds_read2_b32 v[44:45], v115 offset0:216 offset1:217
	ds_read2_b32 v[46:47], v115 offset0:218 offset1:219
	ds_read_b128 v[188:191], v248
	ds_read_b128 v[192:195], v248 offset:32
	ds_read_b128 v[196:199], v248 offset:64
	ds_read_b128 v[200:203], v248 offset:96
	ds_read_b64_tr_b16 v[72:73], v231
	ds_read_b64_tr_b16 v[74:75], v231 offset:512
	ds_read_b64_tr_b16 v[76:77], v231 offset:2048
	ds_read_b64_tr_b16 v[78:79], v231 offset:2560
	ds_read_b64_tr_b16 v[220:221], v231 offset:1024
	ds_read_b64_tr_b16 v[222:223], v231 offset:1536
	ds_read_b64_tr_b16 v[224:225], v231 offset:3072
	ds_read_b64_tr_b16 v[226:227], v231 offset:3584
	s_waitcnt lgkmcnt(8)
	v_mfma_f32_32x32x16_bf16 v[32:47], v[188:191], v[48:51], v[32:47]
	v_mfma_f32_32x32x16_bf16 v[32:47], v[192:195], v[52:55], v[32:47]
	v_mfma_f32_32x32x16_bf16 v[32:47], v[196:199], v[56:59], v[32:47]
	v_mfma_f32_32x32x16_bf16 v[32:47], v[200:203], v[60:63], v[32:47]
	s_nop 11
	v_exp_f32_e32 v32, v32
	v_exp_f32_e32 v33, v33
	v_exp_f32_e32 v34, v34
	v_exp_f32_e32 v35, v35
	v_exp_f32_e32 v36, v36
	v_exp_f32_e32 v37, v37
	v_exp_f32_e32 v38, v38
	v_exp_f32_e32 v39, v39
	v_exp_f32_e32 v40, v40
	v_exp_f32_e32 v41, v41
	v_exp_f32_e32 v42, v42
	v_exp_f32_e32 v43, v43
	v_exp_f32_e32 v44, v44
	v_exp_f32_e32 v45, v45
	v_exp_f32_e32 v46, v46
	v_exp_f32_e32 v47, v47
	v_cvt_pk_bf16_f32 v64, v32, v33
	v_cvt_pk_bf16_f32 v65, v34, v35
	v_cvt_pk_bf16_f32 v66, v36, v37
	v_cvt_pk_bf16_f32 v67, v38, v39
	v_cvt_pk_bf16_f32 v68, v40, v41
	v_cvt_pk_bf16_f32 v69, v42, v43
	v_cvt_pk_bf16_f32 v70, v44, v45
	v_cvt_pk_bf16_f32 v71, v46, v47
	v_pk_add_f32 v[232:233], v[232:233], v[32:33]
	v_pk_add_f32 v[232:233], v[232:233], v[34:35]
	v_pk_add_f32 v[232:233], v[232:233], v[36:37]
	v_pk_add_f32 v[232:233], v[232:233], v[38:39]
	v_pk_add_f32 v[232:233], v[232:233], v[40:41]
	v_pk_add_f32 v[232:233], v[232:233], v[42:43]
	v_pk_add_f32 v[232:233], v[232:233], v[44:45]
	v_pk_add_f32 v[232:233], v[232:233], v[46:47]
	s_waitcnt lgkmcnt(0)
	v_mfma_f32_32x32x16_bf16 v[0:15], v[64:67], v[72:75], v[0:15]
	v_mfma_f32_32x32x16_bf16 v[16:31], v[64:67], v[76:79], v[16:31]
	v_mfma_f32_32x32x16_bf16 v[0:15], v[68:71], v[220:223], v[0:15]
	v_mfma_f32_32x32x16_bf16 v[16:31], v[68:71], v[224:227], v[16:31]
	global_load_dwordx4 v[188:191], v235, s[84:85]
	global_load_dwordx4 v[192:195], v236, s[84:85]
	global_load_dwordx4 v[196:199], v237, s[84:85]
	global_load_dwordx4 v[200:203], v238, s[84:85]
	global_load_dwordx4 v[204:207], v100, s[84:85] offset:768
	global_load_dwordx4 v[208:211], v149, s[84:85] offset:768
	global_load_dwordx4 v[212:215], v100, s[84:85] offset:832
	global_load_dwordx4 v[216:219], v149, s[84:85] offset:832
	s_add_u32 s84, s84, 0x30000
	s_addc_u32 s85, s85, 0
	s_waitcnt vmcnt(16)
	ds_write_b128 v247, v[116:119]
	ds_write_b128 v247, v[120:123] offset:1152
	ds_write_b128 v247, v[124:127] offset:2304
	ds_write_b128 v247, v[128:131] offset:3456
	ds_write_b128 v112, v[132:135]
	ds_write_b128 v112, v[136:139] offset:1024
	ds_write_b128 v112, v[140:143] offset:2048
	ds_write_b128 v112, v[144:147] offset:3072
	ds_read2_b32 v[32:33], v115 offset0:224 offset1:225
	ds_read2_b32 v[34:35], v115 offset0:226 offset1:227
	ds_read2_b32 v[36:37], v115 offset0:232 offset1:233
	ds_read2_b32 v[38:39], v115 offset0:234 offset1:235
	ds_read2_b32 v[40:41], v115 offset0:240 offset1:241
	ds_read2_b32 v[42:43], v115 offset0:242 offset1:243
	ds_read2_b32 v[44:45], v115 offset0:248 offset1:249
	ds_read2_b32 v[46:47], v115 offset0:250 offset1:251
	ds_read_b128 v[116:119], v248
	ds_read_b128 v[120:123], v248 offset:32
	ds_read_b128 v[124:127], v248 offset:64
	ds_read_b128 v[128:131], v248 offset:96
	ds_read_b64_tr_b16 v[72:73], v231
	ds_read_b64_tr_b16 v[74:75], v231 offset:512
	ds_read_b64_tr_b16 v[76:77], v231 offset:2048
	ds_read_b64_tr_b16 v[78:79], v231 offset:2560
	ds_read_b64_tr_b16 v[220:221], v231 offset:1024
	ds_read_b64_tr_b16 v[222:223], v231 offset:1536
	ds_read_b64_tr_b16 v[224:225], v231 offset:3072
	ds_read_b64_tr_b16 v[226:227], v231 offset:3584
	s_waitcnt lgkmcnt(8)
	v_mfma_f32_32x32x16_bf16 v[32:47], v[116:119], v[48:51], v[32:47]
	v_mfma_f32_32x32x16_bf16 v[32:47], v[120:123], v[52:55], v[32:47]
	v_mfma_f32_32x32x16_bf16 v[32:47], v[124:127], v[56:59], v[32:47]
	v_mfma_f32_32x32x16_bf16 v[32:47], v[128:131], v[60:63], v[32:47]
	s_nop 11
	v_exp_f32_e32 v32, v32
	v_exp_f32_e32 v33, v33
	v_exp_f32_e32 v34, v34
	v_exp_f32_e32 v35, v35
	v_exp_f32_e32 v36, v36
	v_exp_f32_e32 v37, v37
	v_exp_f32_e32 v38, v38
	v_exp_f32_e32 v39, v39
	v_exp_f32_e32 v40, v40
	v_exp_f32_e32 v41, v41
	v_exp_f32_e32 v42, v42
	v_exp_f32_e32 v43, v43
	v_exp_f32_e32 v44, v44
	v_exp_f32_e32 v45, v45
	v_exp_f32_e32 v46, v46
	v_exp_f32_e32 v47, v47
	v_cvt_pk_bf16_f32 v64, v32, v33
	v_cvt_pk_bf16_f32 v65, v34, v35
	v_cvt_pk_bf16_f32 v66, v36, v37
	v_cvt_pk_bf16_f32 v67, v38, v39
	v_cvt_pk_bf16_f32 v68, v40, v41
	v_cvt_pk_bf16_f32 v69, v42, v43
	v_cvt_pk_bf16_f32 v70, v44, v45
	v_cvt_pk_bf16_f32 v71, v46, v47
	v_pk_add_f32 v[232:233], v[232:233], v[32:33]
	v_pk_add_f32 v[232:233], v[232:233], v[34:35]
	v_pk_add_f32 v[232:233], v[232:233], v[36:37]
	v_pk_add_f32 v[232:233], v[232:233], v[38:39]
	v_pk_add_f32 v[232:233], v[232:233], v[40:41]
	v_pk_add_f32 v[232:233], v[232:233], v[42:43]
	v_pk_add_f32 v[232:233], v[232:233], v[44:45]
	v_pk_add_f32 v[232:233], v[232:233], v[46:47]
	s_waitcnt lgkmcnt(0)
	v_mfma_f32_32x32x16_bf16 v[0:15], v[64:67], v[72:75], v[0:15]
	v_mfma_f32_32x32x16_bf16 v[16:31], v[64:67], v[76:79], v[16:31]
	v_mfma_f32_32x32x16_bf16 v[0:15], v[68:71], v[220:223], v[0:15]
	v_mfma_f32_32x32x16_bf16 v[16:31], v[68:71], v[224:227], v[16:31]
	global_load_dwordx4 v[116:119], v235, s[84:85]
	global_load_dwordx4 v[120:123], v236, s[84:85]
	global_load_dwordx4 v[124:127], v237, s[84:85]
	global_load_dwordx4 v[128:131], v238, s[84:85]
	global_load_dwordx4 v[132:135], v100, s[84:85] offset:768
	global_load_dwordx4 v[136:139], v149, s[84:85] offset:768
	global_load_dwordx4 v[140:143], v100, s[84:85] offset:832
	global_load_dwordx4 v[144:147], v149, s[84:85] offset:832
	s_add_u32 s84, s84, 0x30000
	s_addc_u32 s85, s85, 0
	s_waitcnt vmcnt(16)
	ds_write_b128 v247, v[156:159]
	ds_write_b128 v247, v[160:163] offset:1152
	ds_write_b128 v247, v[164:167] offset:2304
	ds_write_b128 v247, v[168:171] offset:3456
	ds_write_b128 v112, v[172:175]
	ds_write_b128 v112, v[176:179] offset:1024
	ds_write_b128 v112, v[180:183] offset:2048
	ds_write_b128 v112, v[184:187] offset:3072
	v_add_u32_e32 v115, 0x400, v115
	ds_read2_b32 v[32:33], v115 offset0:0 offset1:1
	ds_read2_b32 v[34:35], v115 offset0:2 offset1:3
	ds_read2_b32 v[36:37], v115 offset0:8 offset1:9
	ds_read2_b32 v[38:39], v115 offset0:10 offset1:11
	ds_read2_b32 v[40:41], v115 offset0:16 offset1:17
	ds_read2_b32 v[42:43], v115 offset0:18 offset1:19
	ds_read2_b32 v[44:45], v115 offset0:24 offset1:25
	ds_read2_b32 v[46:47], v115 offset0:26 offset1:27
	ds_read_b128 v[156:159], v248
	ds_read_b128 v[160:163], v248 offset:32
	ds_read_b128 v[164:167], v248 offset:64
	ds_read_b128 v[168:171], v248 offset:96
	ds_read_b64_tr_b16 v[72:73], v231
	ds_read_b64_tr_b16 v[74:75], v231 offset:512
	ds_read_b64_tr_b16 v[76:77], v231 offset:2048
	ds_read_b64_tr_b16 v[78:79], v231 offset:2560
	ds_read_b64_tr_b16 v[220:221], v231 offset:1024
	ds_read_b64_tr_b16 v[222:223], v231 offset:1536
	ds_read_b64_tr_b16 v[224:225], v231 offset:3072
	ds_read_b64_tr_b16 v[226:227], v231 offset:3584
	s_waitcnt lgkmcnt(8)
	v_mfma_f32_32x32x16_bf16 v[32:47], v[156:159], v[48:51], v[32:47]
	v_mfma_f32_32x32x16_bf16 v[32:47], v[160:163], v[52:55], v[32:47]
	v_mfma_f32_32x32x16_bf16 v[32:47], v[164:167], v[56:59], v[32:47]
	v_mfma_f32_32x32x16_bf16 v[32:47], v[168:171], v[60:63], v[32:47]
	s_nop 11
	v_exp_f32_e32 v32, v32
	v_exp_f32_e32 v33, v33
	v_exp_f32_e32 v34, v34
	v_exp_f32_e32 v35, v35
	v_exp_f32_e32 v36, v36
	v_exp_f32_e32 v37, v37
	v_exp_f32_e32 v38, v38
	v_exp_f32_e32 v39, v39
	v_exp_f32_e32 v40, v40
	v_exp_f32_e32 v41, v41
	v_exp_f32_e32 v42, v42
	v_exp_f32_e32 v43, v43
	v_exp_f32_e32 v44, v44
	v_exp_f32_e32 v45, v45
	v_exp_f32_e32 v46, v46
	v_exp_f32_e32 v47, v47
	v_cvt_pk_bf16_f32 v64, v32, v33
	v_cvt_pk_bf16_f32 v65, v34, v35
	v_cvt_pk_bf16_f32 v66, v36, v37
	v_cvt_pk_bf16_f32 v67, v38, v39
	v_cvt_pk_bf16_f32 v68, v40, v41
	v_cvt_pk_bf16_f32 v69, v42, v43
	v_cvt_pk_bf16_f32 v70, v44, v45
	v_cvt_pk_bf16_f32 v71, v46, v47
	v_pk_add_f32 v[232:233], v[232:233], v[32:33]
	v_pk_add_f32 v[232:233], v[232:233], v[34:35]
	v_pk_add_f32 v[232:233], v[232:233], v[36:37]
	v_pk_add_f32 v[232:233], v[232:233], v[38:39]
	v_pk_add_f32 v[232:233], v[232:233], v[40:41]
	v_pk_add_f32 v[232:233], v[232:233], v[42:43]
	v_pk_add_f32 v[232:233], v[232:233], v[44:45]
	v_pk_add_f32 v[232:233], v[232:233], v[46:47]
	s_waitcnt lgkmcnt(0)
	v_mfma_f32_32x32x16_bf16 v[0:15], v[64:67], v[72:75], v[0:15]
	v_mfma_f32_32x32x16_bf16 v[16:31], v[64:67], v[76:79], v[16:31]
	v_mfma_f32_32x32x16_bf16 v[0:15], v[68:71], v[220:223], v[0:15]
	v_mfma_f32_32x32x16_bf16 v[16:31], v[68:71], v[224:227], v[16:31]
	global_load_dwordx4 v[156:159], v235, s[84:85]
	global_load_dwordx4 v[160:163], v236, s[84:85]
	global_load_dwordx4 v[164:167], v237, s[84:85]
	global_load_dwordx4 v[168:171], v238, s[84:85]
	global_load_dwordx4 v[172:175], v100, s[84:85] offset:768
	global_load_dwordx4 v[176:179], v149, s[84:85] offset:768
	global_load_dwordx4 v[180:183], v100, s[84:85] offset:832
	global_load_dwordx4 v[184:187], v149, s[84:85] offset:832
	s_waitcnt vmcnt(16)
	ds_write_b128 v247, v[188:191]
	ds_write_b128 v247, v[192:195] offset:1152
	ds_write_b128 v247, v[196:199] offset:2304
	ds_write_b128 v247, v[200:203] offset:3456
	ds_write_b128 v112, v[204:207]
	ds_write_b128 v112, v[208:211] offset:1024
	ds_write_b128 v112, v[212:215] offset:2048
	ds_write_b128 v112, v[216:219] offset:3072
	ds_read2_b32 v[32:33], v115 offset0:32 offset1:33
	ds_read2_b32 v[34:35], v115 offset0:34 offset1:35
	ds_read2_b32 v[36:37], v115 offset0:40 offset1:41
	ds_read2_b32 v[38:39], v115 offset0:42 offset1:43
	ds_read2_b32 v[40:41], v115 offset0:48 offset1:49
	ds_read2_b32 v[42:43], v115 offset0:50 offset1:51
	ds_read2_b32 v[44:45], v115 offset0:56 offset1:57
	ds_read2_b32 v[46:47], v115 offset0:58 offset1:59
	ds_read_b128 v[188:191], v248
	ds_read_b128 v[192:195], v248 offset:32
	ds_read_b128 v[196:199], v248 offset:64
	ds_read_b128 v[200:203], v248 offset:96
	ds_read_b64_tr_b16 v[72:73], v231
	ds_read_b64_tr_b16 v[74:75], v231 offset:512
	ds_read_b64_tr_b16 v[76:77], v231 offset:2048
	ds_read_b64_tr_b16 v[78:79], v231 offset:2560
	ds_read_b64_tr_b16 v[220:221], v231 offset:1024
	ds_read_b64_tr_b16 v[222:223], v231 offset:1536
	ds_read_b64_tr_b16 v[224:225], v231 offset:3072
	ds_read_b64_tr_b16 v[226:227], v231 offset:3584
	s_waitcnt lgkmcnt(8)
	v_mfma_f32_32x32x16_bf16 v[32:47], v[188:191], v[48:51], v[32:47]
	v_mfma_f32_32x32x16_bf16 v[32:47], v[192:195], v[52:55], v[32:47]
	v_mfma_f32_32x32x16_bf16 v[32:47], v[196:199], v[56:59], v[32:47]
	v_mfma_f32_32x32x16_bf16 v[32:47], v[200:203], v[60:63], v[32:47]
	s_nop 11
	v_exp_f32_e32 v32, v32
	v_exp_f32_e32 v33, v33
	v_exp_f32_e32 v34, v34
	v_exp_f32_e32 v35, v35
	v_exp_f32_e32 v36, v36
	v_exp_f32_e32 v37, v37
	v_exp_f32_e32 v38, v38
	v_exp_f32_e32 v39, v39
	v_exp_f32_e32 v40, v40
	v_exp_f32_e32 v41, v41
	v_exp_f32_e32 v42, v42
	v_exp_f32_e32 v43, v43
	v_exp_f32_e32 v44, v44
	v_exp_f32_e32 v45, v45
	v_exp_f32_e32 v46, v46
	v_exp_f32_e32 v47, v47
	v_cvt_pk_bf16_f32 v64, v32, v33
	v_cvt_pk_bf16_f32 v65, v34, v35
	v_cvt_pk_bf16_f32 v66, v36, v37
	v_cvt_pk_bf16_f32 v67, v38, v39
	v_cvt_pk_bf16_f32 v68, v40, v41
	v_cvt_pk_bf16_f32 v69, v42, v43
	v_cvt_pk_bf16_f32 v70, v44, v45
	v_cvt_pk_bf16_f32 v71, v46, v47
	v_pk_add_f32 v[232:233], v[232:233], v[32:33]
	v_pk_add_f32 v[232:233], v[232:233], v[34:35]
	v_pk_add_f32 v[232:233], v[232:233], v[36:37]
	v_pk_add_f32 v[232:233], v[232:233], v[38:39]
	v_pk_add_f32 v[232:233], v[232:233], v[40:41]
	v_pk_add_f32 v[232:233], v[232:233], v[42:43]
	v_pk_add_f32 v[232:233], v[232:233], v[44:45]
	v_pk_add_f32 v[232:233], v[232:233], v[46:47]
	s_waitcnt lgkmcnt(0)
	v_mfma_f32_32x32x16_bf16 v[0:15], v[64:67], v[72:75], v[0:15]
	v_mfma_f32_32x32x16_bf16 v[16:31], v[64:67], v[76:79], v[16:31]
	v_mfma_f32_32x32x16_bf16 v[0:15], v[68:71], v[220:223], v[0:15]
	v_mfma_f32_32x32x16_bf16 v[16:31], v[68:71], v[224:227], v[16:31]
	global_load_dwordx4 v[188:191], v239, s[86:87]
	global_load_dwordx4 v[192:195], v240, s[86:87]
	global_load_dwordx4 v[196:199], v241, s[86:87]
	global_load_dwordx4 v[200:203], v242, s[86:87]
	global_load_dwordx4 v[204:207], v101, s[86:87] offset:768
	global_load_dwordx4 v[208:211], v150, s[86:87] offset:768
	global_load_dwordx4 v[212:215], v101, s[86:87] offset:832
	global_load_dwordx4 v[216:219], v150, s[86:87] offset:832
	s_add_u32 s86, s86, 0xc0000
	s_addc_u32 s87, s87, 0
	s_waitcnt vmcnt(16)
	ds_write_b128 v247, v[116:119]
	ds_write_b128 v247, v[120:123] offset:1152
	ds_write_b128 v247, v[124:127] offset:2304
	ds_write_b128 v247, v[128:131] offset:3456
	ds_write_b128 v112, v[132:135]
	ds_write_b128 v112, v[136:139] offset:1024
	ds_write_b128 v112, v[140:143] offset:2048
	ds_write_b128 v112, v[144:147] offset:3072
	ds_read2_b32 v[32:33], v115 offset0:64 offset1:65
	ds_read2_b32 v[34:35], v115 offset0:66 offset1:67
	ds_read2_b32 v[36:37], v115 offset0:72 offset1:73
	ds_read2_b32 v[38:39], v115 offset0:74 offset1:75
	ds_read2_b32 v[40:41], v115 offset0:80 offset1:81
	ds_read2_b32 v[42:43], v115 offset0:82 offset1:83
	ds_read2_b32 v[44:45], v115 offset0:88 offset1:89
	ds_read2_b32 v[46:47], v115 offset0:90 offset1:91
	ds_read_b128 v[116:119], v248
	ds_read_b128 v[120:123], v248 offset:32
	ds_read_b128 v[124:127], v248 offset:64
	ds_read_b128 v[128:131], v248 offset:96
	ds_read_b64_tr_b16 v[72:73], v231
	ds_read_b64_tr_b16 v[74:75], v231 offset:512
	ds_read_b64_tr_b16 v[76:77], v231 offset:2048
	ds_read_b64_tr_b16 v[78:79], v231 offset:2560
	ds_read_b64_tr_b16 v[220:221], v231 offset:1024
	ds_read_b64_tr_b16 v[222:223], v231 offset:1536
	ds_read_b64_tr_b16 v[224:225], v231 offset:3072
	ds_read_b64_tr_b16 v[226:227], v231 offset:3584
	s_waitcnt lgkmcnt(8)
	v_mfma_f32_32x32x16_bf16 v[32:47], v[116:119], v[48:51], v[32:47]
	v_mfma_f32_32x32x16_bf16 v[32:47], v[120:123], v[52:55], v[32:47]
	v_mfma_f32_32x32x16_bf16 v[32:47], v[124:127], v[56:59], v[32:47]
	v_mfma_f32_32x32x16_bf16 v[32:47], v[128:131], v[60:63], v[32:47]
	s_nop 11
	v_exp_f32_e32 v32, v32
	v_exp_f32_e32 v33, v33
	v_exp_f32_e32 v34, v34
	v_exp_f32_e32 v35, v35
	v_exp_f32_e32 v36, v36
	v_exp_f32_e32 v37, v37
	v_exp_f32_e32 v38, v38
	v_exp_f32_e32 v39, v39
	v_exp_f32_e32 v40, v40
	v_exp_f32_e32 v41, v41
	v_exp_f32_e32 v42, v42
	v_exp_f32_e32 v43, v43
	v_exp_f32_e32 v44, v44
	v_exp_f32_e32 v45, v45
	v_exp_f32_e32 v46, v46
	v_exp_f32_e32 v47, v47
	v_cvt_pk_bf16_f32 v64, v32, v33
	v_cvt_pk_bf16_f32 v65, v34, v35
	v_cvt_pk_bf16_f32 v66, v36, v37
	v_cvt_pk_bf16_f32 v67, v38, v39
	v_cvt_pk_bf16_f32 v68, v40, v41
	v_cvt_pk_bf16_f32 v69, v42, v43
	v_cvt_pk_bf16_f32 v70, v44, v45
	v_cvt_pk_bf16_f32 v71, v46, v47
	v_pk_add_f32 v[232:233], v[232:233], v[32:33]
	v_pk_add_f32 v[232:233], v[232:233], v[34:35]
	v_pk_add_f32 v[232:233], v[232:233], v[36:37]
	v_pk_add_f32 v[232:233], v[232:233], v[38:39]
	v_pk_add_f32 v[232:233], v[232:233], v[40:41]
	v_pk_add_f32 v[232:233], v[232:233], v[42:43]
	v_pk_add_f32 v[232:233], v[232:233], v[44:45]
	v_pk_add_f32 v[232:233], v[232:233], v[46:47]
	s_waitcnt lgkmcnt(0)
	v_mfma_f32_32x32x16_bf16 v[0:15], v[64:67], v[72:75], v[0:15]
	v_mfma_f32_32x32x16_bf16 v[16:31], v[64:67], v[76:79], v[16:31]
	v_mfma_f32_32x32x16_bf16 v[0:15], v[68:71], v[220:223], v[0:15]
	v_mfma_f32_32x32x16_bf16 v[16:31], v[68:71], v[224:227], v[16:31]
	global_load_dwordx4 v[116:119], v239, s[86:87]
	global_load_dwordx4 v[120:123], v240, s[86:87]
	global_load_dwordx4 v[124:127], v241, s[86:87]
	global_load_dwordx4 v[128:131], v242, s[86:87]
	global_load_dwordx4 v[132:135], v101, s[86:87] offset:768
	global_load_dwordx4 v[136:139], v150, s[86:87] offset:768
	global_load_dwordx4 v[140:143], v101, s[86:87] offset:832
	global_load_dwordx4 v[144:147], v150, s[86:87] offset:832
	s_add_u32 s86, s86, 0xc0000
	s_addc_u32 s87, s87, 0
	s_waitcnt vmcnt(16)
	ds_write_b128 v247, v[156:159]
	ds_write_b128 v247, v[160:163] offset:1152
	ds_write_b128 v247, v[164:167] offset:2304
	ds_write_b128 v247, v[168:171] offset:3456
	ds_write_b128 v112, v[172:175]
	ds_write_b128 v112, v[176:179] offset:1024
	ds_write_b128 v112, v[180:183] offset:2048
	ds_write_b128 v112, v[184:187] offset:3072
	ds_read2_b32 v[32:33], v115 offset0:96 offset1:97
	ds_read2_b32 v[34:35], v115 offset0:98 offset1:99
	ds_read2_b32 v[36:37], v115 offset0:104 offset1:105
	ds_read2_b32 v[38:39], v115 offset0:106 offset1:107
	ds_read2_b32 v[40:41], v115 offset0:112 offset1:113
	ds_read2_b32 v[42:43], v115 offset0:114 offset1:115
	ds_read2_b32 v[44:45], v115 offset0:120 offset1:121
	ds_read2_b32 v[46:47], v115 offset0:122 offset1:123
	ds_read_b128 v[156:159], v248
	ds_read_b128 v[160:163], v248 offset:32
	ds_read_b128 v[164:167], v248 offset:64
	ds_read_b128 v[168:171], v248 offset:96
	ds_read_b64_tr_b16 v[72:73], v231
	ds_read_b64_tr_b16 v[74:75], v231 offset:512
	ds_read_b64_tr_b16 v[76:77], v231 offset:2048
	ds_read_b64_tr_b16 v[78:79], v231 offset:2560
	ds_read_b64_tr_b16 v[220:221], v231 offset:1024
	ds_read_b64_tr_b16 v[222:223], v231 offset:1536
	ds_read_b64_tr_b16 v[224:225], v231 offset:3072
	ds_read_b64_tr_b16 v[226:227], v231 offset:3584
	s_waitcnt lgkmcnt(8)
	v_mfma_f32_32x32x16_bf16 v[32:47], v[156:159], v[48:51], v[32:47]
	v_mfma_f32_32x32x16_bf16 v[32:47], v[160:163], v[52:55], v[32:47]
	v_mfma_f32_32x32x16_bf16 v[32:47], v[164:167], v[56:59], v[32:47]
	v_mfma_f32_32x32x16_bf16 v[32:47], v[168:171], v[60:63], v[32:47]
	s_nop 11
	v_exp_f32_e32 v32, v32
	v_exp_f32_e32 v33, v33
	v_exp_f32_e32 v34, v34
	v_exp_f32_e32 v35, v35
	v_exp_f32_e32 v36, v36
	v_exp_f32_e32 v37, v37
	v_exp_f32_e32 v38, v38
	v_exp_f32_e32 v39, v39
	v_exp_f32_e32 v40, v40
	v_exp_f32_e32 v41, v41
	v_exp_f32_e32 v42, v42
	v_exp_f32_e32 v43, v43
	v_exp_f32_e32 v44, v44
	v_exp_f32_e32 v45, v45
	v_exp_f32_e32 v46, v46
	v_exp_f32_e32 v47, v47
	v_cvt_pk_bf16_f32 v64, v32, v33
	v_cvt_pk_bf16_f32 v65, v34, v35
	v_cvt_pk_bf16_f32 v66, v36, v37
	v_cvt_pk_bf16_f32 v67, v38, v39
	v_cvt_pk_bf16_f32 v68, v40, v41
	v_cvt_pk_bf16_f32 v69, v42, v43
	v_cvt_pk_bf16_f32 v70, v44, v45
	v_cvt_pk_bf16_f32 v71, v46, v47
	v_pk_add_f32 v[232:233], v[232:233], v[32:33]
	v_pk_add_f32 v[232:233], v[232:233], v[34:35]
	v_pk_add_f32 v[232:233], v[232:233], v[36:37]
	v_pk_add_f32 v[232:233], v[232:233], v[38:39]
	v_pk_add_f32 v[232:233], v[232:233], v[40:41]
	v_pk_add_f32 v[232:233], v[232:233], v[42:43]
	v_pk_add_f32 v[232:233], v[232:233], v[44:45]
	v_pk_add_f32 v[232:233], v[232:233], v[46:47]
	s_waitcnt lgkmcnt(0)
	v_mfma_f32_32x32x16_bf16 v[0:15], v[64:67], v[72:75], v[0:15]
	v_mfma_f32_32x32x16_bf16 v[16:31], v[64:67], v[76:79], v[16:31]
	v_mfma_f32_32x32x16_bf16 v[0:15], v[68:71], v[220:223], v[0:15]
	v_mfma_f32_32x32x16_bf16 v[16:31], v[68:71], v[224:227], v[16:31]
	global_load_dwordx4 v[156:159], v239, s[86:87]
	global_load_dwordx4 v[160:163], v240, s[86:87]
	global_load_dwordx4 v[164:167], v241, s[86:87]
	global_load_dwordx4 v[168:171], v242, s[86:87]
	global_load_dwordx4 v[172:175], v101, s[86:87] offset:768
	global_load_dwordx4 v[176:179], v150, s[86:87] offset:768
	global_load_dwordx4 v[180:183], v101, s[86:87] offset:832
	global_load_dwordx4 v[184:187], v150, s[86:87] offset:832
	s_add_u32 s86, s86, 0xc0000
	s_addc_u32 s87, s87, 0
	s_waitcnt vmcnt(16)
	ds_write_b128 v247, v[188:191]
	ds_write_b128 v247, v[192:195] offset:1152
	ds_write_b128 v247, v[196:199] offset:2304
	ds_write_b128 v247, v[200:203] offset:3456
	ds_write_b128 v112, v[204:207]
	ds_write_b128 v112, v[208:211] offset:1024
	ds_write_b128 v112, v[212:215] offset:2048
	ds_write_b128 v112, v[216:219] offset:3072
	v_mov_b32_e32 v115, v229
	ds_read2_b32 v[32:33], v115 offset0:0 offset1:1
	ds_read2_b32 v[34:35], v115 offset0:2 offset1:3
	ds_read2_b32 v[36:37], v115 offset0:8 offset1:9
	ds_read2_b32 v[38:39], v115 offset0:10 offset1:11
	ds_read2_b32 v[40:41], v115 offset0:16 offset1:17
	ds_read2_b32 v[42:43], v115 offset0:18 offset1:19
	ds_read2_b32 v[44:45], v115 offset0:24 offset1:25
	ds_read2_b32 v[46:47], v115 offset0:26 offset1:27
	ds_read_b128 v[188:191], v248
	ds_read_b128 v[192:195], v248 offset:32
	ds_read_b128 v[196:199], v248 offset:64
	ds_read_b128 v[200:203], v248 offset:96
	ds_read_b64_tr_b16 v[72:73], v231
	ds_read_b64_tr_b16 v[74:75], v231 offset:512
	ds_read_b64_tr_b16 v[76:77], v231 offset:2048
	ds_read_b64_tr_b16 v[78:79], v231 offset:2560
	ds_read_b64_tr_b16 v[220:221], v231 offset:1024
	ds_read_b64_tr_b16 v[222:223], v231 offset:1536
	ds_read_b64_tr_b16 v[224:225], v231 offset:3072
	ds_read_b64_tr_b16 v[226:227], v231 offset:3584
	s_waitcnt lgkmcnt(8)
	v_mfma_f32_32x32x16_bf16 v[32:47], v[188:191], v[48:51], v[32:47]
	v_mfma_f32_32x32x16_bf16 v[32:47], v[192:195], v[52:55], v[32:47]
	v_mfma_f32_32x32x16_bf16 v[32:47], v[196:199], v[56:59], v[32:47]
	v_mfma_f32_32x32x16_bf16 v[32:47], v[200:203], v[60:63], v[32:47]
	s_nop 11
	v_exp_f32_e32 v32, v32
	v_exp_f32_e32 v33, v33
	v_exp_f32_e32 v34, v34
	v_exp_f32_e32 v35, v35
	v_exp_f32_e32 v36, v36
	v_exp_f32_e32 v37, v37
	v_exp_f32_e32 v38, v38
	v_exp_f32_e32 v39, v39
	v_exp_f32_e32 v40, v40
	v_exp_f32_e32 v41, v41
	v_exp_f32_e32 v42, v42
	v_exp_f32_e32 v43, v43
	v_exp_f32_e32 v44, v44
	v_exp_f32_e32 v45, v45
	v_exp_f32_e32 v46, v46
	v_exp_f32_e32 v47, v47
	v_cvt_pk_bf16_f32 v64, v32, v33
	v_cvt_pk_bf16_f32 v65, v34, v35
	v_cvt_pk_bf16_f32 v66, v36, v37
	v_cvt_pk_bf16_f32 v67, v38, v39
	v_cvt_pk_bf16_f32 v68, v40, v41
	v_cvt_pk_bf16_f32 v69, v42, v43
	v_cvt_pk_bf16_f32 v70, v44, v45
	v_cvt_pk_bf16_f32 v71, v46, v47
	v_pk_add_f32 v[232:233], v[232:233], v[32:33]
	v_pk_add_f32 v[232:233], v[232:233], v[34:35]
	v_pk_add_f32 v[232:233], v[232:233], v[36:37]
	v_pk_add_f32 v[232:233], v[232:233], v[38:39]
	v_pk_add_f32 v[232:233], v[232:233], v[40:41]
	v_pk_add_f32 v[232:233], v[232:233], v[42:43]
	v_pk_add_f32 v[232:233], v[232:233], v[44:45]
	v_pk_add_f32 v[232:233], v[232:233], v[46:47]
	s_waitcnt lgkmcnt(0)
	v_mfma_f32_32x32x16_bf16 v[0:15], v[64:67], v[72:75], v[0:15]
	v_mfma_f32_32x32x16_bf16 v[16:31], v[64:67], v[76:79], v[16:31]
	v_mfma_f32_32x32x16_bf16 v[0:15], v[68:71], v[220:223], v[0:15]
	v_mfma_f32_32x32x16_bf16 v[16:31], v[68:71], v[224:227], v[16:31]
	global_load_dwordx4 v[188:191], v239, s[86:87]
	global_load_dwordx4 v[192:195], v240, s[86:87]
	global_load_dwordx4 v[196:199], v241, s[86:87]
	global_load_dwordx4 v[200:203], v242, s[86:87]
	global_load_dwordx4 v[204:207], v101, s[86:87] offset:768
	global_load_dwordx4 v[208:211], v150, s[86:87] offset:768
	global_load_dwordx4 v[212:215], v101, s[86:87] offset:832
	global_load_dwordx4 v[216:219], v150, s[86:87] offset:832
	s_add_u32 s86, s86, 0xc0000
	s_addc_u32 s87, s87, 0
	s_waitcnt vmcnt(16)
	ds_write_b128 v247, v[116:119]
	ds_write_b128 v247, v[120:123] offset:1152
	ds_write_b128 v247, v[124:127] offset:2304
	ds_write_b128 v247, v[128:131] offset:3456
	ds_write_b128 v112, v[132:135]
	ds_write_b128 v112, v[136:139] offset:1024
	ds_write_b128 v112, v[140:143] offset:2048
	ds_write_b128 v112, v[144:147] offset:3072
	ds_read2_b32 v[32:33], v115 offset0:32 offset1:33
	ds_read2_b32 v[34:35], v115 offset0:34 offset1:35
	ds_read2_b32 v[36:37], v115 offset0:40 offset1:41
	ds_read2_b32 v[38:39], v115 offset0:42 offset1:43
	ds_read2_b32 v[40:41], v115 offset0:48 offset1:49
	ds_read2_b32 v[42:43], v115 offset0:50 offset1:51
	ds_read2_b32 v[44:45], v115 offset0:56 offset1:57
	ds_read2_b32 v[46:47], v115 offset0:58 offset1:59
	ds_read_b128 v[116:119], v248
	ds_read_b128 v[120:123], v248 offset:32
	ds_read_b128 v[124:127], v248 offset:64
	ds_read_b128 v[128:131], v248 offset:96
	ds_read_b64_tr_b16 v[72:73], v231
	ds_read_b64_tr_b16 v[74:75], v231 offset:512
	ds_read_b64_tr_b16 v[76:77], v231 offset:2048
	ds_read_b64_tr_b16 v[78:79], v231 offset:2560
	ds_read_b64_tr_b16 v[220:221], v231 offset:1024
	ds_read_b64_tr_b16 v[222:223], v231 offset:1536
	ds_read_b64_tr_b16 v[224:225], v231 offset:3072
	ds_read_b64_tr_b16 v[226:227], v231 offset:3584
	s_waitcnt lgkmcnt(8)
	v_mfma_f32_32x32x16_bf16 v[32:47], v[116:119], v[48:51], v[32:47]
	v_mfma_f32_32x32x16_bf16 v[32:47], v[120:123], v[52:55], v[32:47]
	v_mfma_f32_32x32x16_bf16 v[32:47], v[124:127], v[56:59], v[32:47]
	v_mfma_f32_32x32x16_bf16 v[32:47], v[128:131], v[60:63], v[32:47]
	s_nop 11
	v_exp_f32_e32 v32, v32
	v_exp_f32_e32 v33, v33
	v_exp_f32_e32 v34, v34
	v_exp_f32_e32 v35, v35
	v_exp_f32_e32 v36, v36
	v_exp_f32_e32 v37, v37
	v_exp_f32_e32 v38, v38
	v_exp_f32_e32 v39, v39
	v_exp_f32_e32 v40, v40
	v_exp_f32_e32 v41, v41
	v_exp_f32_e32 v42, v42
	v_exp_f32_e32 v43, v43
	v_exp_f32_e32 v44, v44
	v_exp_f32_e32 v45, v45
	v_exp_f32_e32 v46, v46
	v_exp_f32_e32 v47, v47
	v_cvt_pk_bf16_f32 v64, v32, v33
	v_cvt_pk_bf16_f32 v65, v34, v35
	v_cvt_pk_bf16_f32 v66, v36, v37
	v_cvt_pk_bf16_f32 v67, v38, v39
	v_cvt_pk_bf16_f32 v68, v40, v41
	v_cvt_pk_bf16_f32 v69, v42, v43
	v_cvt_pk_bf16_f32 v70, v44, v45
	v_cvt_pk_bf16_f32 v71, v46, v47
	v_pk_add_f32 v[232:233], v[232:233], v[32:33]
	v_pk_add_f32 v[232:233], v[232:233], v[34:35]
	v_pk_add_f32 v[232:233], v[232:233], v[36:37]
	v_pk_add_f32 v[232:233], v[232:233], v[38:39]
	v_pk_add_f32 v[232:233], v[232:233], v[40:41]
	v_pk_add_f32 v[232:233], v[232:233], v[42:43]
	v_pk_add_f32 v[232:233], v[232:233], v[44:45]
	v_pk_add_f32 v[232:233], v[232:233], v[46:47]
	s_waitcnt lgkmcnt(0)
	v_mfma_f32_32x32x16_bf16 v[0:15], v[64:67], v[72:75], v[0:15]
	v_mfma_f32_32x32x16_bf16 v[16:31], v[64:67], v[76:79], v[16:31]
	v_mfma_f32_32x32x16_bf16 v[0:15], v[68:71], v[220:223], v[0:15]
	v_mfma_f32_32x32x16_bf16 v[16:31], v[68:71], v[224:227], v[16:31]
	global_load_dwordx4 v[116:119], v239, s[86:87]
	global_load_dwordx4 v[120:123], v240, s[86:87]
	global_load_dwordx4 v[124:127], v241, s[86:87]
	global_load_dwordx4 v[128:131], v242, s[86:87]
	global_load_dwordx4 v[132:135], v101, s[86:87] offset:768
	global_load_dwordx4 v[136:139], v150, s[86:87] offset:768
	global_load_dwordx4 v[140:143], v101, s[86:87] offset:832
	global_load_dwordx4 v[144:147], v150, s[86:87] offset:832
	s_add_u32 s86, s86, 0xc0000
	s_addc_u32 s87, s87, 0
	s_waitcnt vmcnt(16)
	ds_write_b128 v247, v[156:159]
	ds_write_b128 v247, v[160:163] offset:1152
	ds_write_b128 v247, v[164:167] offset:2304
	ds_write_b128 v247, v[168:171] offset:3456
	ds_write_b128 v112, v[172:175]
	ds_write_b128 v112, v[176:179] offset:1024
	ds_write_b128 v112, v[180:183] offset:2048
	ds_write_b128 v112, v[184:187] offset:3072
	ds_read2_b32 v[32:33], v115 offset0:64 offset1:65
	ds_read2_b32 v[34:35], v115 offset0:66 offset1:67
	ds_read2_b32 v[36:37], v115 offset0:72 offset1:73
	ds_read2_b32 v[38:39], v115 offset0:74 offset1:75
	ds_read2_b32 v[40:41], v115 offset0:80 offset1:81
	ds_read2_b32 v[42:43], v115 offset0:82 offset1:83
	ds_read2_b32 v[44:45], v115 offset0:88 offset1:89
	ds_read2_b32 v[46:47], v115 offset0:90 offset1:91
	ds_read_b128 v[156:159], v248
	ds_read_b128 v[160:163], v248 offset:32
	ds_read_b128 v[164:167], v248 offset:64
	ds_read_b128 v[168:171], v248 offset:96
	ds_read_b64_tr_b16 v[72:73], v231
	ds_read_b64_tr_b16 v[74:75], v231 offset:512
	ds_read_b64_tr_b16 v[76:77], v231 offset:2048
	ds_read_b64_tr_b16 v[78:79], v231 offset:2560
	ds_read_b64_tr_b16 v[220:221], v231 offset:1024
	ds_read_b64_tr_b16 v[222:223], v231 offset:1536
	ds_read_b64_tr_b16 v[224:225], v231 offset:3072
	ds_read_b64_tr_b16 v[226:227], v231 offset:3584
	s_waitcnt lgkmcnt(8)
	v_mfma_f32_32x32x16_bf16 v[32:47], v[156:159], v[48:51], v[32:47]
	v_mfma_f32_32x32x16_bf16 v[32:47], v[160:163], v[52:55], v[32:47]
	v_mfma_f32_32x32x16_bf16 v[32:47], v[164:167], v[56:59], v[32:47]
	v_mfma_f32_32x32x16_bf16 v[32:47], v[168:171], v[60:63], v[32:47]
	s_nop 11
	v_exp_f32_e32 v32, v32
	v_exp_f32_e32 v33, v33
	v_exp_f32_e32 v34, v34
	v_exp_f32_e32 v35, v35
	v_exp_f32_e32 v36, v36
	v_exp_f32_e32 v37, v37
	v_exp_f32_e32 v38, v38
	v_exp_f32_e32 v39, v39
	v_exp_f32_e32 v40, v40
	v_exp_f32_e32 v41, v41
	v_exp_f32_e32 v42, v42
	v_exp_f32_e32 v43, v43
	v_exp_f32_e32 v44, v44
	v_exp_f32_e32 v45, v45
	v_exp_f32_e32 v46, v46
	v_exp_f32_e32 v47, v47
	v_cvt_pk_bf16_f32 v64, v32, v33
	v_cvt_pk_bf16_f32 v65, v34, v35
	v_cvt_pk_bf16_f32 v66, v36, v37
	v_cvt_pk_bf16_f32 v67, v38, v39
	v_cvt_pk_bf16_f32 v68, v40, v41
	v_cvt_pk_bf16_f32 v69, v42, v43
	v_cvt_pk_bf16_f32 v70, v44, v45
	v_cvt_pk_bf16_f32 v71, v46, v47
	v_pk_add_f32 v[232:233], v[232:233], v[32:33]
	v_pk_add_f32 v[232:233], v[232:233], v[34:35]
	v_pk_add_f32 v[232:233], v[232:233], v[36:37]
	v_pk_add_f32 v[232:233], v[232:233], v[38:39]
	v_pk_add_f32 v[232:233], v[232:233], v[40:41]
	v_pk_add_f32 v[232:233], v[232:233], v[42:43]
	v_pk_add_f32 v[232:233], v[232:233], v[44:45]
	v_pk_add_f32 v[232:233], v[232:233], v[46:47]
	s_waitcnt lgkmcnt(0)
	v_mfma_f32_32x32x16_bf16 v[0:15], v[64:67], v[72:75], v[0:15]
	v_mfma_f32_32x32x16_bf16 v[16:31], v[64:67], v[76:79], v[16:31]
	v_mfma_f32_32x32x16_bf16 v[0:15], v[68:71], v[220:223], v[0:15]
	v_mfma_f32_32x32x16_bf16 v[16:31], v[68:71], v[224:227], v[16:31]
	global_load_dwordx4 v[156:159], v239, s[86:87]
	global_load_dwordx4 v[160:163], v240, s[86:87]
	global_load_dwordx4 v[164:167], v241, s[86:87]
	global_load_dwordx4 v[168:171], v242, s[86:87]
	global_load_dwordx4 v[172:175], v101, s[86:87] offset:768
	global_load_dwordx4 v[176:179], v150, s[86:87] offset:768
	global_load_dwordx4 v[180:183], v101, s[86:87] offset:832
	global_load_dwordx4 v[184:187], v150, s[86:87] offset:832
	s_add_u32 s86, s86, 0xc0000
	s_addc_u32 s87, s87, 0
	s_waitcnt vmcnt(16)
	ds_write_b128 v247, v[188:191]
	ds_write_b128 v247, v[192:195] offset:1152
	ds_write_b128 v247, v[196:199] offset:2304
	ds_write_b128 v247, v[200:203] offset:3456
	ds_write_b128 v112, v[204:207]
	ds_write_b128 v112, v[208:211] offset:1024
	ds_write_b128 v112, v[212:215] offset:2048
	ds_write_b128 v112, v[216:219] offset:3072
	ds_read2_b32 v[32:33], v115 offset0:96 offset1:97
	ds_read2_b32 v[34:35], v115 offset0:98 offset1:99
	ds_read2_b32 v[36:37], v115 offset0:104 offset1:105
	ds_read2_b32 v[38:39], v115 offset0:106 offset1:107
	ds_read2_b32 v[40:41], v115 offset0:112 offset1:113
	ds_read2_b32 v[42:43], v115 offset0:114 offset1:115
	ds_read2_b32 v[44:45], v115 offset0:120 offset1:121
	ds_read2_b32 v[46:47], v115 offset0:122 offset1:123
	ds_read_b128 v[188:191], v248
	ds_read_b128 v[192:195], v248 offset:32
	ds_read_b128 v[196:199], v248 offset:64
	ds_read_b128 v[200:203], v248 offset:96
	ds_read_b64_tr_b16 v[72:73], v231
	ds_read_b64_tr_b16 v[74:75], v231 offset:512
	ds_read_b64_tr_b16 v[76:77], v231 offset:2048
	ds_read_b64_tr_b16 v[78:79], v231 offset:2560
	ds_read_b64_tr_b16 v[220:221], v231 offset:1024
	ds_read_b64_tr_b16 v[222:223], v231 offset:1536
	ds_read_b64_tr_b16 v[224:225], v231 offset:3072
	ds_read_b64_tr_b16 v[226:227], v231 offset:3584
	s_waitcnt lgkmcnt(8)
	v_mfma_f32_32x32x16_bf16 v[32:47], v[188:191], v[48:51], v[32:47]
	v_mfma_f32_32x32x16_bf16 v[32:47], v[192:195], v[52:55], v[32:47]
	v_mfma_f32_32x32x16_bf16 v[32:47], v[196:199], v[56:59], v[32:47]
	v_mfma_f32_32x32x16_bf16 v[32:47], v[200:203], v[60:63], v[32:47]
	s_nop 11
	v_exp_f32_e32 v32, v32
	v_exp_f32_e32 v33, v33
	v_exp_f32_e32 v34, v34
	v_exp_f32_e32 v35, v35
	v_exp_f32_e32 v36, v36
	v_exp_f32_e32 v37, v37
	v_exp_f32_e32 v38, v38
	v_exp_f32_e32 v39, v39
	v_exp_f32_e32 v40, v40
	v_exp_f32_e32 v41, v41
	v_exp_f32_e32 v42, v42
	v_exp_f32_e32 v43, v43
	v_exp_f32_e32 v44, v44
	v_exp_f32_e32 v45, v45
	v_exp_f32_e32 v46, v46
	v_exp_f32_e32 v47, v47
	v_cvt_pk_bf16_f32 v64, v32, v33
	v_cvt_pk_bf16_f32 v65, v34, v35
	v_cvt_pk_bf16_f32 v66, v36, v37
	v_cvt_pk_bf16_f32 v67, v38, v39
	v_cvt_pk_bf16_f32 v68, v40, v41
	v_cvt_pk_bf16_f32 v69, v42, v43
	v_cvt_pk_bf16_f32 v70, v44, v45
	v_cvt_pk_bf16_f32 v71, v46, v47
	v_pk_add_f32 v[232:233], v[232:233], v[32:33]
	v_pk_add_f32 v[232:233], v[232:233], v[34:35]
	v_pk_add_f32 v[232:233], v[232:233], v[36:37]
	v_pk_add_f32 v[232:233], v[232:233], v[38:39]
	v_pk_add_f32 v[232:233], v[232:233], v[40:41]
	v_pk_add_f32 v[232:233], v[232:233], v[42:43]
	v_pk_add_f32 v[232:233], v[232:233], v[44:45]
	v_pk_add_f32 v[232:233], v[232:233], v[46:47]
	s_waitcnt lgkmcnt(0)
	v_mfma_f32_32x32x16_bf16 v[0:15], v[64:67], v[72:75], v[0:15]
	v_mfma_f32_32x32x16_bf16 v[16:31], v[64:67], v[76:79], v[16:31]
	v_mfma_f32_32x32x16_bf16 v[0:15], v[68:71], v[220:223], v[0:15]
	v_mfma_f32_32x32x16_bf16 v[16:31], v[68:71], v[224:227], v[16:31]
	global_load_dwordx4 v[188:191], v239, s[86:87]
	global_load_dwordx4 v[192:195], v240, s[86:87]
	global_load_dwordx4 v[196:199], v241, s[86:87]
	global_load_dwordx4 v[200:203], v242, s[86:87]
	global_load_dwordx4 v[204:207], v101, s[86:87] offset:768
	global_load_dwordx4 v[208:211], v150, s[86:87] offset:768
	global_load_dwordx4 v[212:215], v101, s[86:87] offset:832
	global_load_dwordx4 v[216:219], v150, s[86:87] offset:832
	s_add_u32 s86, s86, 0xc0000
	s_addc_u32 s87, s87, 0
	s_waitcnt vmcnt(16)
	ds_write_b128 v247, v[116:119]
	ds_write_b128 v247, v[120:123] offset:1152
	ds_write_b128 v247, v[124:127] offset:2304
	ds_write_b128 v247, v[128:131] offset:3456
	ds_write_b128 v112, v[132:135]
	ds_write_b128 v112, v[136:139] offset:1024
	ds_write_b128 v112, v[140:143] offset:2048
	ds_write_b128 v112, v[144:147] offset:3072
	ds_read2_b32 v[32:33], v115 offset0:128 offset1:129
	ds_read2_b32 v[34:35], v115 offset0:130 offset1:131
	ds_read2_b32 v[36:37], v115 offset0:136 offset1:137
	ds_read2_b32 v[38:39], v115 offset0:138 offset1:139
	ds_read2_b32 v[40:41], v115 offset0:144 offset1:145
	ds_read2_b32 v[42:43], v115 offset0:146 offset1:147
	ds_read2_b32 v[44:45], v115 offset0:152 offset1:153
	ds_read2_b32 v[46:47], v115 offset0:154 offset1:155
	ds_read_b128 v[116:119], v248
	ds_read_b128 v[120:123], v248 offset:32
	ds_read_b128 v[124:127], v248 offset:64
	ds_read_b128 v[128:131], v248 offset:96
	ds_read_b64_tr_b16 v[72:73], v231
	ds_read_b64_tr_b16 v[74:75], v231 offset:512
	ds_read_b64_tr_b16 v[76:77], v231 offset:2048
	ds_read_b64_tr_b16 v[78:79], v231 offset:2560
	ds_read_b64_tr_b16 v[220:221], v231 offset:1024
	ds_read_b64_tr_b16 v[222:223], v231 offset:1536
	ds_read_b64_tr_b16 v[224:225], v231 offset:3072
	ds_read_b64_tr_b16 v[226:227], v231 offset:3584
	s_waitcnt lgkmcnt(8)
	v_mfma_f32_32x32x16_bf16 v[32:47], v[116:119], v[48:51], v[32:47]
	v_mfma_f32_32x32x16_bf16 v[32:47], v[120:123], v[52:55], v[32:47]
	v_mfma_f32_32x32x16_bf16 v[32:47], v[124:127], v[56:59], v[32:47]
	v_mfma_f32_32x32x16_bf16 v[32:47], v[128:131], v[60:63], v[32:47]
	s_nop 11
	v_exp_f32_e32 v32, v32
	v_exp_f32_e32 v33, v33
	v_exp_f32_e32 v34, v34
	v_exp_f32_e32 v35, v35
	v_exp_f32_e32 v36, v36
	v_exp_f32_e32 v37, v37
	v_exp_f32_e32 v38, v38
	v_exp_f32_e32 v39, v39
	v_exp_f32_e32 v40, v40
	v_exp_f32_e32 v41, v41
	v_exp_f32_e32 v42, v42
	v_exp_f32_e32 v43, v43
	v_exp_f32_e32 v44, v44
	v_exp_f32_e32 v45, v45
	v_exp_f32_e32 v46, v46
	v_exp_f32_e32 v47, v47
	v_cvt_pk_bf16_f32 v64, v32, v33
	v_cvt_pk_bf16_f32 v65, v34, v35
	v_cvt_pk_bf16_f32 v66, v36, v37
	v_cvt_pk_bf16_f32 v67, v38, v39
	v_cvt_pk_bf16_f32 v68, v40, v41
	v_cvt_pk_bf16_f32 v69, v42, v43
	v_cvt_pk_bf16_f32 v70, v44, v45
	v_cvt_pk_bf16_f32 v71, v46, v47
	v_pk_add_f32 v[232:233], v[232:233], v[32:33]
	v_pk_add_f32 v[232:233], v[232:233], v[34:35]
	v_pk_add_f32 v[232:233], v[232:233], v[36:37]
	v_pk_add_f32 v[232:233], v[232:233], v[38:39]
	v_pk_add_f32 v[232:233], v[232:233], v[40:41]
	v_pk_add_f32 v[232:233], v[232:233], v[42:43]
	v_pk_add_f32 v[232:233], v[232:233], v[44:45]
	v_pk_add_f32 v[232:233], v[232:233], v[46:47]
	s_waitcnt lgkmcnt(0)
	v_mfma_f32_32x32x16_bf16 v[0:15], v[64:67], v[72:75], v[0:15]
	v_mfma_f32_32x32x16_bf16 v[16:31], v[64:67], v[76:79], v[16:31]
	v_mfma_f32_32x32x16_bf16 v[0:15], v[68:71], v[220:223], v[0:15]
	v_mfma_f32_32x32x16_bf16 v[16:31], v[68:71], v[224:227], v[16:31]
	global_load_dwordx4 v[116:119], v239, s[86:87]
	global_load_dwordx4 v[120:123], v240, s[86:87]
	global_load_dwordx4 v[124:127], v241, s[86:87]
	global_load_dwordx4 v[128:131], v242, s[86:87]
	global_load_dwordx4 v[132:135], v101, s[86:87] offset:768
	global_load_dwordx4 v[136:139], v150, s[86:87] offset:768
	global_load_dwordx4 v[140:143], v101, s[86:87] offset:832
	global_load_dwordx4 v[144:147], v150, s[86:87] offset:832
	s_waitcnt vmcnt(16)
	ds_write_b128 v247, v[156:159]
	ds_write_b128 v247, v[160:163] offset:1152
	ds_write_b128 v247, v[164:167] offset:2304
	ds_write_b128 v247, v[168:171] offset:3456
	ds_write_b128 v112, v[172:175]
	ds_write_b128 v112, v[176:179] offset:1024
	ds_write_b128 v112, v[180:183] offset:2048
	ds_write_b128 v112, v[184:187] offset:3072
	ds_read2_b32 v[32:33], v115 offset0:160 offset1:161
	ds_read2_b32 v[34:35], v115 offset0:162 offset1:163
	ds_read2_b32 v[36:37], v115 offset0:168 offset1:169
	ds_read2_b32 v[38:39], v115 offset0:170 offset1:171
	ds_read2_b32 v[40:41], v115 offset0:176 offset1:177
	ds_read2_b32 v[42:43], v115 offset0:178 offset1:179
	ds_read2_b32 v[44:45], v115 offset0:184 offset1:185
	ds_read2_b32 v[46:47], v115 offset0:186 offset1:187
	ds_read_b128 v[156:159], v248
	ds_read_b128 v[160:163], v248 offset:32
	ds_read_b128 v[164:167], v248 offset:64
	ds_read_b128 v[168:171], v248 offset:96
	ds_read_b64_tr_b16 v[72:73], v231
	ds_read_b64_tr_b16 v[74:75], v231 offset:512
	ds_read_b64_tr_b16 v[76:77], v231 offset:2048
	ds_read_b64_tr_b16 v[78:79], v231 offset:2560
	ds_read_b64_tr_b16 v[220:221], v231 offset:1024
	ds_read_b64_tr_b16 v[222:223], v231 offset:1536
	ds_read_b64_tr_b16 v[224:225], v231 offset:3072
	ds_read_b64_tr_b16 v[226:227], v231 offset:3584
	s_waitcnt lgkmcnt(8)
	v_mfma_f32_32x32x16_bf16 v[32:47], v[156:159], v[48:51], v[32:47]
	v_mfma_f32_32x32x16_bf16 v[32:47], v[160:163], v[52:55], v[32:47]
	v_mfma_f32_32x32x16_bf16 v[32:47], v[164:167], v[56:59], v[32:47]
	v_mfma_f32_32x32x16_bf16 v[32:47], v[168:171], v[60:63], v[32:47]
	s_nop 11
	v_exp_f32_e32 v32, v32
	v_exp_f32_e32 v33, v33
	v_exp_f32_e32 v34, v34
	v_exp_f32_e32 v35, v35
	v_exp_f32_e32 v36, v36
	v_exp_f32_e32 v37, v37
	v_exp_f32_e32 v38, v38
	v_exp_f32_e32 v39, v39
	v_exp_f32_e32 v40, v40
	v_exp_f32_e32 v41, v41
	v_exp_f32_e32 v42, v42
	v_exp_f32_e32 v43, v43
	v_exp_f32_e32 v44, v44
	v_exp_f32_e32 v45, v45
	v_exp_f32_e32 v46, v46
	v_exp_f32_e32 v47, v47
	v_cvt_pk_bf16_f32 v64, v32, v33
	v_cvt_pk_bf16_f32 v65, v34, v35
	v_cvt_pk_bf16_f32 v66, v36, v37
	v_cvt_pk_bf16_f32 v67, v38, v39
	v_cvt_pk_bf16_f32 v68, v40, v41
	v_cvt_pk_bf16_f32 v69, v42, v43
	v_cvt_pk_bf16_f32 v70, v44, v45
	v_cvt_pk_bf16_f32 v71, v46, v47
	v_pk_add_f32 v[232:233], v[232:233], v[32:33]
	v_pk_add_f32 v[232:233], v[232:233], v[34:35]
	v_pk_add_f32 v[232:233], v[232:233], v[36:37]
	v_pk_add_f32 v[232:233], v[232:233], v[38:39]
	v_pk_add_f32 v[232:233], v[232:233], v[40:41]
	v_pk_add_f32 v[232:233], v[232:233], v[42:43]
	v_pk_add_f32 v[232:233], v[232:233], v[44:45]
	v_pk_add_f32 v[232:233], v[232:233], v[46:47]
	s_waitcnt lgkmcnt(0)
	v_mfma_f32_32x32x16_bf16 v[0:15], v[64:67], v[72:75], v[0:15]
	v_mfma_f32_32x32x16_bf16 v[16:31], v[64:67], v[76:79], v[16:31]
	v_mfma_f32_32x32x16_bf16 v[0:15], v[68:71], v[220:223], v[0:15]
	v_mfma_f32_32x32x16_bf16 v[16:31], v[68:71], v[224:227], v[16:31]
	global_load_dwordx4 v[156:159], v243, s[88:89]
	global_load_dwordx4 v[160:163], v244, s[88:89]
	global_load_dwordx4 v[164:167], v245, s[88:89]
	global_load_dwordx4 v[168:171], v246, s[88:89]
	global_load_dwordx4 v[172:175], v148, s[88:89] offset:768
	global_load_dwordx4 v[176:179], v151, s[88:89] offset:768
	global_load_dwordx4 v[180:183], v148, s[88:89] offset:832
	global_load_dwordx4 v[184:187], v151, s[88:89] offset:832
	s_add_u32 s88, s88, 0x300000
	s_addc_u32 s89, s89, 0
	s_waitcnt vmcnt(16)
	ds_write_b128 v247, v[188:191]
	ds_write_b128 v247, v[192:195] offset:1152
	ds_write_b128 v247, v[196:199] offset:2304
	ds_write_b128 v247, v[200:203] offset:3456
	ds_write_b128 v112, v[204:207]
	ds_write_b128 v112, v[208:211] offset:1024
	ds_write_b128 v112, v[212:215] offset:2048
	ds_write_b128 v112, v[216:219] offset:3072
	ds_read2_b32 v[32:33], v115 offset0:192 offset1:193
	ds_read2_b32 v[34:35], v115 offset0:194 offset1:195
	ds_read2_b32 v[36:37], v115 offset0:200 offset1:201
	ds_read2_b32 v[38:39], v115 offset0:202 offset1:203
	ds_read2_b32 v[40:41], v115 offset0:208 offset1:209
	ds_read2_b32 v[42:43], v115 offset0:210 offset1:211
	ds_read2_b32 v[44:45], v115 offset0:216 offset1:217
	ds_read2_b32 v[46:47], v115 offset0:218 offset1:219
	ds_read_b128 v[188:191], v248
	ds_read_b128 v[192:195], v248 offset:32
	ds_read_b128 v[196:199], v248 offset:64
	ds_read_b128 v[200:203], v248 offset:96
	ds_read_b64_tr_b16 v[72:73], v231
	ds_read_b64_tr_b16 v[74:75], v231 offset:512
	ds_read_b64_tr_b16 v[76:77], v231 offset:2048
	ds_read_b64_tr_b16 v[78:79], v231 offset:2560
	ds_read_b64_tr_b16 v[220:221], v231 offset:1024
	ds_read_b64_tr_b16 v[222:223], v231 offset:1536
	ds_read_b64_tr_b16 v[224:225], v231 offset:3072
	ds_read_b64_tr_b16 v[226:227], v231 offset:3584
	s_waitcnt lgkmcnt(8)
	v_mfma_f32_32x32x16_bf16 v[32:47], v[188:191], v[48:51], v[32:47]
	v_mfma_f32_32x32x16_bf16 v[32:47], v[192:195], v[52:55], v[32:47]
	v_mfma_f32_32x32x16_bf16 v[32:47], v[196:199], v[56:59], v[32:47]
	v_mfma_f32_32x32x16_bf16 v[32:47], v[200:203], v[60:63], v[32:47]
	s_nop 11
	v_exp_f32_e32 v32, v32
	v_exp_f32_e32 v33, v33
	v_exp_f32_e32 v34, v34
	v_exp_f32_e32 v35, v35
	v_exp_f32_e32 v36, v36
	v_exp_f32_e32 v37, v37
	v_exp_f32_e32 v38, v38
	v_exp_f32_e32 v39, v39
	v_exp_f32_e32 v40, v40
	v_exp_f32_e32 v41, v41
	v_exp_f32_e32 v42, v42
	v_exp_f32_e32 v43, v43
	v_exp_f32_e32 v44, v44
	v_exp_f32_e32 v45, v45
	v_exp_f32_e32 v46, v46
	v_exp_f32_e32 v47, v47
	v_cvt_pk_bf16_f32 v64, v32, v33
	v_cvt_pk_bf16_f32 v65, v34, v35
	v_cvt_pk_bf16_f32 v66, v36, v37
	v_cvt_pk_bf16_f32 v67, v38, v39
	v_cvt_pk_bf16_f32 v68, v40, v41
	v_cvt_pk_bf16_f32 v69, v42, v43
	v_cvt_pk_bf16_f32 v70, v44, v45
	v_cvt_pk_bf16_f32 v71, v46, v47
	v_pk_add_f32 v[232:233], v[232:233], v[32:33]
	v_pk_add_f32 v[232:233], v[232:233], v[34:35]
	v_pk_add_f32 v[232:233], v[232:233], v[36:37]
	v_pk_add_f32 v[232:233], v[232:233], v[38:39]
	v_pk_add_f32 v[232:233], v[232:233], v[40:41]
	v_pk_add_f32 v[232:233], v[232:233], v[42:43]
	v_pk_add_f32 v[232:233], v[232:233], v[44:45]
	v_pk_add_f32 v[232:233], v[232:233], v[46:47]
	s_waitcnt lgkmcnt(0)
	v_mfma_f32_32x32x16_bf16 v[0:15], v[64:67], v[72:75], v[0:15]
	v_mfma_f32_32x32x16_bf16 v[16:31], v[64:67], v[76:79], v[16:31]
	v_mfma_f32_32x32x16_bf16 v[0:15], v[68:71], v[220:223], v[0:15]
	v_mfma_f32_32x32x16_bf16 v[16:31], v[68:71], v[224:227], v[16:31]
	global_load_dwordx4 v[188:191], v243, s[88:89]
	global_load_dwordx4 v[192:195], v244, s[88:89]
	global_load_dwordx4 v[196:199], v245, s[88:89]
	global_load_dwordx4 v[200:203], v246, s[88:89]
	global_load_dwordx4 v[204:207], v148, s[88:89] offset:768
	global_load_dwordx4 v[208:211], v151, s[88:89] offset:768
	global_load_dwordx4 v[212:215], v148, s[88:89] offset:832
	global_load_dwordx4 v[216:219], v151, s[88:89] offset:832
	s_add_u32 s88, s88, 0x300000
	s_addc_u32 s89, s89, 0
	s_waitcnt vmcnt(16)
	ds_write_b128 v247, v[116:119]
	ds_write_b128 v247, v[120:123] offset:1152
	ds_write_b128 v247, v[124:127] offset:2304
	ds_write_b128 v247, v[128:131] offset:3456
	ds_write_b128 v112, v[132:135]
	ds_write_b128 v112, v[136:139] offset:1024
	ds_write_b128 v112, v[140:143] offset:2048
	ds_write_b128 v112, v[144:147] offset:3072
	ds_read2_b32 v[32:33], v115 offset0:224 offset1:225
	ds_read2_b32 v[34:35], v115 offset0:226 offset1:227
	ds_read2_b32 v[36:37], v115 offset0:232 offset1:233
	ds_read2_b32 v[38:39], v115 offset0:234 offset1:235
	ds_read2_b32 v[40:41], v115 offset0:240 offset1:241
	ds_read2_b32 v[42:43], v115 offset0:242 offset1:243
	ds_read2_b32 v[44:45], v115 offset0:248 offset1:249
	ds_read2_b32 v[46:47], v115 offset0:250 offset1:251
	ds_read_b128 v[116:119], v248
	ds_read_b128 v[120:123], v248 offset:32
	ds_read_b128 v[124:127], v248 offset:64
	ds_read_b128 v[128:131], v248 offset:96
	ds_read_b64_tr_b16 v[72:73], v231
	ds_read_b64_tr_b16 v[74:75], v231 offset:512
	ds_read_b64_tr_b16 v[76:77], v231 offset:2048
	ds_read_b64_tr_b16 v[78:79], v231 offset:2560
	ds_read_b64_tr_b16 v[220:221], v231 offset:1024
	ds_read_b64_tr_b16 v[222:223], v231 offset:1536
	ds_read_b64_tr_b16 v[224:225], v231 offset:3072
	ds_read_b64_tr_b16 v[226:227], v231 offset:3584
	s_waitcnt lgkmcnt(8)
	v_mfma_f32_32x32x16_bf16 v[32:47], v[116:119], v[48:51], v[32:47]
	v_mfma_f32_32x32x16_bf16 v[32:47], v[120:123], v[52:55], v[32:47]
	v_mfma_f32_32x32x16_bf16 v[32:47], v[124:127], v[56:59], v[32:47]
	v_mfma_f32_32x32x16_bf16 v[32:47], v[128:131], v[60:63], v[32:47]
	s_nop 11
	v_exp_f32_e32 v32, v32
	v_exp_f32_e32 v33, v33
	v_exp_f32_e32 v34, v34
	v_exp_f32_e32 v35, v35
	v_exp_f32_e32 v36, v36
	v_exp_f32_e32 v37, v37
	v_exp_f32_e32 v38, v38
	v_exp_f32_e32 v39, v39
	v_exp_f32_e32 v40, v40
	v_exp_f32_e32 v41, v41
	v_exp_f32_e32 v42, v42
	v_exp_f32_e32 v43, v43
	v_exp_f32_e32 v44, v44
	v_exp_f32_e32 v45, v45
	v_exp_f32_e32 v46, v46
	v_exp_f32_e32 v47, v47
	v_cvt_pk_bf16_f32 v64, v32, v33
	v_cvt_pk_bf16_f32 v65, v34, v35
	v_cvt_pk_bf16_f32 v66, v36, v37
	v_cvt_pk_bf16_f32 v67, v38, v39
	v_cvt_pk_bf16_f32 v68, v40, v41
	v_cvt_pk_bf16_f32 v69, v42, v43
	v_cvt_pk_bf16_f32 v70, v44, v45
	v_cvt_pk_bf16_f32 v71, v46, v47
	v_pk_add_f32 v[232:233], v[232:233], v[32:33]
	v_pk_add_f32 v[232:233], v[232:233], v[34:35]
	v_pk_add_f32 v[232:233], v[232:233], v[36:37]
	v_pk_add_f32 v[232:233], v[232:233], v[38:39]
	v_pk_add_f32 v[232:233], v[232:233], v[40:41]
	v_pk_add_f32 v[232:233], v[232:233], v[42:43]
	v_pk_add_f32 v[232:233], v[232:233], v[44:45]
	v_pk_add_f32 v[232:233], v[232:233], v[46:47]
	s_waitcnt lgkmcnt(0)
	v_mfma_f32_32x32x16_bf16 v[0:15], v[64:67], v[72:75], v[0:15]
	v_mfma_f32_32x32x16_bf16 v[16:31], v[64:67], v[76:79], v[16:31]
	v_mfma_f32_32x32x16_bf16 v[0:15], v[68:71], v[220:223], v[0:15]
	v_mfma_f32_32x32x16_bf16 v[16:31], v[68:71], v[224:227], v[16:31]
	global_load_dwordx4 v[116:119], v243, s[88:89]
	global_load_dwordx4 v[120:123], v244, s[88:89]
	global_load_dwordx4 v[124:127], v245, s[88:89]
	global_load_dwordx4 v[128:131], v246, s[88:89]
	global_load_dwordx4 v[132:135], v148, s[88:89] offset:768
	global_load_dwordx4 v[136:139], v151, s[88:89] offset:768
	global_load_dwordx4 v[140:143], v148, s[88:89] offset:832
	global_load_dwordx4 v[144:147], v151, s[88:89] offset:832
	s_add_u32 s88, s88, 0x300000
	s_addc_u32 s89, s89, 0
	s_waitcnt vmcnt(16)
	ds_write_b128 v247, v[156:159]
	ds_write_b128 v247, v[160:163] offset:1152
	ds_write_b128 v247, v[164:167] offset:2304
	ds_write_b128 v247, v[168:171] offset:3456
	ds_write_b128 v112, v[172:175]
	ds_write_b128 v112, v[176:179] offset:1024
	ds_write_b128 v112, v[180:183] offset:2048
	ds_write_b128 v112, v[184:187] offset:3072
	v_mov_b32_e32 v115, v230
	ds_read2_b32 v[32:33], v115 offset0:0 offset1:1
	ds_read2_b32 v[34:35], v115 offset0:2 offset1:3
	ds_read2_b32 v[36:37], v115 offset0:8 offset1:9
	ds_read2_b32 v[38:39], v115 offset0:10 offset1:11
	ds_read2_b32 v[40:41], v115 offset0:16 offset1:17
	ds_read2_b32 v[42:43], v115 offset0:18 offset1:19
	ds_read2_b32 v[44:45], v115 offset0:24 offset1:25
	ds_read2_b32 v[46:47], v115 offset0:26 offset1:27
	ds_read_b128 v[156:159], v248
	ds_read_b128 v[160:163], v248 offset:32
	ds_read_b128 v[164:167], v248 offset:64
	ds_read_b128 v[168:171], v248 offset:96
	ds_read_b64_tr_b16 v[72:73], v231
	ds_read_b64_tr_b16 v[74:75], v231 offset:512
	ds_read_b64_tr_b16 v[76:77], v231 offset:2048
	ds_read_b64_tr_b16 v[78:79], v231 offset:2560
	ds_read_b64_tr_b16 v[220:221], v231 offset:1024
	ds_read_b64_tr_b16 v[222:223], v231 offset:1536
	ds_read_b64_tr_b16 v[224:225], v231 offset:3072
	ds_read_b64_tr_b16 v[226:227], v231 offset:3584
	s_waitcnt lgkmcnt(8)
	v_mfma_f32_32x32x16_bf16 v[32:47], v[156:159], v[48:51], v[32:47]
	v_mfma_f32_32x32x16_bf16 v[32:47], v[160:163], v[52:55], v[32:47]
	v_mfma_f32_32x32x16_bf16 v[32:47], v[164:167], v[56:59], v[32:47]
	v_mfma_f32_32x32x16_bf16 v[32:47], v[168:171], v[60:63], v[32:47]
	s_nop 11
	v_exp_f32_e32 v32, v32
	v_exp_f32_e32 v33, v33
	v_exp_f32_e32 v34, v34
	v_exp_f32_e32 v35, v35
	v_exp_f32_e32 v36, v36
	v_exp_f32_e32 v37, v37
	v_exp_f32_e32 v38, v38
	v_exp_f32_e32 v39, v39
	v_exp_f32_e32 v40, v40
	v_exp_f32_e32 v41, v41
	v_exp_f32_e32 v42, v42
	v_exp_f32_e32 v43, v43
	v_exp_f32_e32 v44, v44
	v_exp_f32_e32 v45, v45
	v_exp_f32_e32 v46, v46
	v_exp_f32_e32 v47, v47
	v_cvt_pk_bf16_f32 v64, v32, v33
	v_cvt_pk_bf16_f32 v65, v34, v35
	v_cvt_pk_bf16_f32 v66, v36, v37
	v_cvt_pk_bf16_f32 v67, v38, v39
	v_cvt_pk_bf16_f32 v68, v40, v41
	v_cvt_pk_bf16_f32 v69, v42, v43
	v_cvt_pk_bf16_f32 v70, v44, v45
	v_cvt_pk_bf16_f32 v71, v46, v47
	v_pk_add_f32 v[232:233], v[232:233], v[32:33]
	v_pk_add_f32 v[232:233], v[232:233], v[34:35]
	v_pk_add_f32 v[232:233], v[232:233], v[36:37]
	v_pk_add_f32 v[232:233], v[232:233], v[38:39]
	v_pk_add_f32 v[232:233], v[232:233], v[40:41]
	v_pk_add_f32 v[232:233], v[232:233], v[42:43]
	v_pk_add_f32 v[232:233], v[232:233], v[44:45]
	v_pk_add_f32 v[232:233], v[232:233], v[46:47]
	s_waitcnt lgkmcnt(0)
	v_mfma_f32_32x32x16_bf16 v[0:15], v[64:67], v[72:75], v[0:15]
	v_mfma_f32_32x32x16_bf16 v[16:31], v[64:67], v[76:79], v[16:31]
	v_mfma_f32_32x32x16_bf16 v[0:15], v[68:71], v[220:223], v[0:15]
	v_mfma_f32_32x32x16_bf16 v[16:31], v[68:71], v[224:227], v[16:31]
	global_load_dwordx4 v[156:159], v243, s[88:89]
	global_load_dwordx4 v[160:163], v244, s[88:89]
	global_load_dwordx4 v[164:167], v245, s[88:89]
	global_load_dwordx4 v[168:171], v246, s[88:89]
	global_load_dwordx4 v[172:175], v148, s[88:89] offset:768
	global_load_dwordx4 v[176:179], v151, s[88:89] offset:768
	global_load_dwordx4 v[180:183], v148, s[88:89] offset:832
	global_load_dwordx4 v[184:187], v151, s[88:89] offset:832
	s_add_u32 s88, s88, 0x300000
	s_addc_u32 s89, s89, 0
	s_waitcnt vmcnt(16)
	ds_write_b128 v247, v[188:191]
	ds_write_b128 v247, v[192:195] offset:1152
	ds_write_b128 v247, v[196:199] offset:2304
	ds_write_b128 v247, v[200:203] offset:3456
	ds_write_b128 v112, v[204:207]
	ds_write_b128 v112, v[208:211] offset:1024
	ds_write_b128 v112, v[212:215] offset:2048
	ds_write_b128 v112, v[216:219] offset:3072
	ds_read2_b32 v[32:33], v115 offset0:32 offset1:33
	ds_read2_b32 v[34:35], v115 offset0:34 offset1:35
	ds_read2_b32 v[36:37], v115 offset0:40 offset1:41
	ds_read2_b32 v[38:39], v115 offset0:42 offset1:43
	ds_read2_b32 v[40:41], v115 offset0:48 offset1:49
	ds_read2_b32 v[42:43], v115 offset0:50 offset1:51
	ds_read2_b32 v[44:45], v115 offset0:56 offset1:57
	ds_read2_b32 v[46:47], v115 offset0:58 offset1:59
	ds_read_b128 v[188:191], v248
	ds_read_b128 v[192:195], v248 offset:32
	ds_read_b128 v[196:199], v248 offset:64
	ds_read_b128 v[200:203], v248 offset:96
	ds_read_b64_tr_b16 v[72:73], v231
	ds_read_b64_tr_b16 v[74:75], v231 offset:512
	ds_read_b64_tr_b16 v[76:77], v231 offset:2048
	ds_read_b64_tr_b16 v[78:79], v231 offset:2560
	ds_read_b64_tr_b16 v[220:221], v231 offset:1024
	ds_read_b64_tr_b16 v[222:223], v231 offset:1536
	ds_read_b64_tr_b16 v[224:225], v231 offset:3072
	ds_read_b64_tr_b16 v[226:227], v231 offset:3584
	s_waitcnt lgkmcnt(8)
	v_mfma_f32_32x32x16_bf16 v[32:47], v[188:191], v[48:51], v[32:47]
	v_mfma_f32_32x32x16_bf16 v[32:47], v[192:195], v[52:55], v[32:47]
	v_mfma_f32_32x32x16_bf16 v[32:47], v[196:199], v[56:59], v[32:47]
	v_mfma_f32_32x32x16_bf16 v[32:47], v[200:203], v[60:63], v[32:47]
	s_nop 11
	v_exp_f32_e32 v32, v32
	v_exp_f32_e32 v33, v33
	v_exp_f32_e32 v34, v34
	v_exp_f32_e32 v35, v35
	v_exp_f32_e32 v36, v36
	v_exp_f32_e32 v37, v37
	v_exp_f32_e32 v38, v38
	v_exp_f32_e32 v39, v39
	v_exp_f32_e32 v40, v40
	v_exp_f32_e32 v41, v41
	v_exp_f32_e32 v42, v42
	v_exp_f32_e32 v43, v43
	v_exp_f32_e32 v44, v44
	v_exp_f32_e32 v45, v45
	v_exp_f32_e32 v46, v46
	v_exp_f32_e32 v47, v47
	v_cvt_pk_bf16_f32 v64, v32, v33
	v_cvt_pk_bf16_f32 v65, v34, v35
	v_cvt_pk_bf16_f32 v66, v36, v37
	v_cvt_pk_bf16_f32 v67, v38, v39
	v_cvt_pk_bf16_f32 v68, v40, v41
	v_cvt_pk_bf16_f32 v69, v42, v43
	v_cvt_pk_bf16_f32 v70, v44, v45
	v_cvt_pk_bf16_f32 v71, v46, v47
	v_pk_add_f32 v[232:233], v[232:233], v[32:33]
	v_pk_add_f32 v[232:233], v[232:233], v[34:35]
	v_pk_add_f32 v[232:233], v[232:233], v[36:37]
	v_pk_add_f32 v[232:233], v[232:233], v[38:39]
	v_pk_add_f32 v[232:233], v[232:233], v[40:41]
	v_pk_add_f32 v[232:233], v[232:233], v[42:43]
	v_pk_add_f32 v[232:233], v[232:233], v[44:45]
	v_pk_add_f32 v[232:233], v[232:233], v[46:47]
	s_waitcnt lgkmcnt(0)
	v_mfma_f32_32x32x16_bf16 v[0:15], v[64:67], v[72:75], v[0:15]
	v_mfma_f32_32x32x16_bf16 v[16:31], v[64:67], v[76:79], v[16:31]
	v_mfma_f32_32x32x16_bf16 v[0:15], v[68:71], v[220:223], v[0:15]
	v_mfma_f32_32x32x16_bf16 v[16:31], v[68:71], v[224:227], v[16:31]
	global_load_dwordx4 v[188:191], v243, s[88:89]
	global_load_dwordx4 v[192:195], v244, s[88:89]
	global_load_dwordx4 v[196:199], v245, s[88:89]
	global_load_dwordx4 v[200:203], v246, s[88:89]
	global_load_dwordx4 v[204:207], v148, s[88:89] offset:768
	global_load_dwordx4 v[208:211], v151, s[88:89] offset:768
	global_load_dwordx4 v[212:215], v148, s[88:89] offset:832
	global_load_dwordx4 v[216:219], v151, s[88:89] offset:832
	s_waitcnt vmcnt(16)
	ds_write_b128 v247, v[116:119]
	ds_write_b128 v247, v[120:123] offset:1152
	ds_write_b128 v247, v[124:127] offset:2304
	ds_write_b128 v247, v[128:131] offset:3456
	ds_write_b128 v112, v[132:135]
	ds_write_b128 v112, v[136:139] offset:1024
	ds_write_b128 v112, v[140:143] offset:2048
	ds_write_b128 v112, v[144:147] offset:3072
	ds_read2_b32 v[32:33], v115 offset0:64 offset1:65
	ds_read2_b32 v[34:35], v115 offset0:66 offset1:67
	ds_read2_b32 v[36:37], v115 offset0:72 offset1:73
	ds_read2_b32 v[38:39], v115 offset0:74 offset1:75
	ds_read2_b32 v[40:41], v115 offset0:80 offset1:81
	ds_read2_b32 v[42:43], v115 offset0:82 offset1:83
	ds_read2_b32 v[44:45], v115 offset0:88 offset1:89
	ds_read2_b32 v[46:47], v115 offset0:90 offset1:91
	ds_read_b128 v[116:119], v248
	ds_read_b128 v[120:123], v248 offset:32
	ds_read_b128 v[124:127], v248 offset:64
	ds_read_b128 v[128:131], v248 offset:96
	ds_read_b64_tr_b16 v[72:73], v231
	ds_read_b64_tr_b16 v[74:75], v231 offset:512
	ds_read_b64_tr_b16 v[76:77], v231 offset:2048
	ds_read_b64_tr_b16 v[78:79], v231 offset:2560
	ds_read_b64_tr_b16 v[220:221], v231 offset:1024
	ds_read_b64_tr_b16 v[222:223], v231 offset:1536
	ds_read_b64_tr_b16 v[224:225], v231 offset:3072
	ds_read_b64_tr_b16 v[226:227], v231 offset:3584
	s_waitcnt lgkmcnt(8)
	v_mfma_f32_32x32x16_bf16 v[32:47], v[116:119], v[48:51], v[32:47]
	v_mfma_f32_32x32x16_bf16 v[32:47], v[120:123], v[52:55], v[32:47]
	v_mfma_f32_32x32x16_bf16 v[32:47], v[124:127], v[56:59], v[32:47]
	v_mfma_f32_32x32x16_bf16 v[32:47], v[128:131], v[60:63], v[32:47]
	s_nop 11
	v_exp_f32_e32 v32, v32
	v_exp_f32_e32 v33, v33
	v_exp_f32_e32 v34, v34
	v_exp_f32_e32 v35, v35
	v_exp_f32_e32 v36, v36
	v_exp_f32_e32 v37, v37
	v_exp_f32_e32 v38, v38
	v_exp_f32_e32 v39, v39
	v_exp_f32_e32 v40, v40
	v_exp_f32_e32 v41, v41
	v_exp_f32_e32 v42, v42
	v_exp_f32_e32 v43, v43
	v_exp_f32_e32 v44, v44
	v_exp_f32_e32 v45, v45
	v_exp_f32_e32 v46, v46
	v_exp_f32_e32 v47, v47
	v_cvt_pk_bf16_f32 v64, v32, v33
	v_cvt_pk_bf16_f32 v65, v34, v35
	v_cvt_pk_bf16_f32 v66, v36, v37
	v_cvt_pk_bf16_f32 v67, v38, v39
	v_cvt_pk_bf16_f32 v68, v40, v41
	v_cvt_pk_bf16_f32 v69, v42, v43
	v_cvt_pk_bf16_f32 v70, v44, v45
	v_cvt_pk_bf16_f32 v71, v46, v47
	v_pk_add_f32 v[232:233], v[232:233], v[32:33]
	v_pk_add_f32 v[232:233], v[232:233], v[34:35]
	v_pk_add_f32 v[232:233], v[232:233], v[36:37]
	v_pk_add_f32 v[232:233], v[232:233], v[38:39]
	v_pk_add_f32 v[232:233], v[232:233], v[40:41]
	v_pk_add_f32 v[232:233], v[232:233], v[42:43]
	v_pk_add_f32 v[232:233], v[232:233], v[44:45]
	v_pk_add_f32 v[232:233], v[232:233], v[46:47]
	s_waitcnt lgkmcnt(0)
	v_mfma_f32_32x32x16_bf16 v[0:15], v[64:67], v[72:75], v[0:15]
	v_mfma_f32_32x32x16_bf16 v[16:31], v[64:67], v[76:79], v[16:31]
	v_mfma_f32_32x32x16_bf16 v[0:15], v[68:71], v[220:223], v[0:15]
	v_mfma_f32_32x32x16_bf16 v[16:31], v[68:71], v[224:227], v[16:31]
	s_waitcnt vmcnt(8)
	ds_write_b128 v247, v[156:159]
	ds_write_b128 v247, v[160:163] offset:1152
	ds_write_b128 v247, v[164:167] offset:2304
	ds_write_b128 v247, v[168:171] offset:3456
	ds_write_b128 v112, v[172:175]
	ds_write_b128 v112, v[176:179] offset:1024
	ds_write_b128 v112, v[180:183] offset:2048
	ds_write_b128 v112, v[184:187] offset:3072
	ds_read2_b32 v[32:33], v115 offset0:96 offset1:97
	ds_read2_b32 v[34:35], v115 offset0:98 offset1:99
	ds_read2_b32 v[36:37], v115 offset0:104 offset1:105
	ds_read2_b32 v[38:39], v115 offset0:106 offset1:107
	ds_read2_b32 v[40:41], v115 offset0:112 offset1:113
	ds_read2_b32 v[42:43], v115 offset0:114 offset1:115
	ds_read2_b32 v[44:45], v115 offset0:120 offset1:121
	ds_read2_b32 v[46:47], v115 offset0:122 offset1:123
	ds_read_b128 v[156:159], v248
	ds_read_b128 v[160:163], v248 offset:32
	ds_read_b128 v[164:167], v248 offset:64
	ds_read_b128 v[168:171], v248 offset:96
	ds_read_b64_tr_b16 v[72:73], v231
	ds_read_b64_tr_b16 v[74:75], v231 offset:512
	ds_read_b64_tr_b16 v[76:77], v231 offset:2048
	ds_read_b64_tr_b16 v[78:79], v231 offset:2560
	ds_read_b64_tr_b16 v[220:221], v231 offset:1024
	ds_read_b64_tr_b16 v[222:223], v231 offset:1536
	ds_read_b64_tr_b16 v[224:225], v231 offset:3072
	ds_read_b64_tr_b16 v[226:227], v231 offset:3584
	s_waitcnt lgkmcnt(8)
; __device__ __forceinline__ int crow(int r, int hi) { return (r & 3) + 8 * (r >> 2) + 4 * hi; }
; __device__ __forceinline__ void dil_unit(LAS unsigned char* lds, bf16_t* proj, int seq, int hd, int T0, int rho) {
;     ...
;     l += __shfl_xor(l, 32);
; #pragma unroll
;     for (int rr = 0; rr < 16; ++rr) {
;         const int j = crow(rr, hi);
;         const float il = __builtin_amdgcn_rcpf(__shfl(l, j));
	v_mfma_f32_32x32x16_bf16 v[32:47], v[156:159], v[48:51], v[32:47]
	v_mfma_f32_32x32x16_bf16 v[32:47], v[160:163], v[52:55], v[32:47]
	v_mfma_f32_32x32x16_bf16 v[32:47], v[164:167], v[56:59], v[32:47]
	v_mfma_f32_32x32x16_bf16 v[32:47], v[168:171], v[60:63], v[32:47]
	s_nop 11
	v_exp_f32_e32 v32, v32
	v_exp_f32_e32 v33, v33
	v_exp_f32_e32 v34, v34
	v_exp_f32_e32 v35, v35
	v_exp_f32_e32 v36, v36
	v_exp_f32_e32 v37, v37
	v_exp_f32_e32 v38, v38
	v_exp_f32_e32 v39, v39
	v_exp_f32_e32 v40, v40
	v_exp_f32_e32 v41, v41
	v_exp_f32_e32 v42, v42
	v_exp_f32_e32 v43, v43
	v_exp_f32_e32 v44, v44
	v_exp_f32_e32 v45, v45
	v_exp_f32_e32 v46, v46
	v_exp_f32_e32 v47, v47
	v_cvt_pk_bf16_f32 v64, v32, v33
	v_cvt_pk_bf16_f32 v65, v34, v35
	v_cvt_pk_bf16_f32 v66, v36, v37
	v_cvt_pk_bf16_f32 v67, v38, v39
	v_cvt_pk_bf16_f32 v68, v40, v41
	v_cvt_pk_bf16_f32 v69, v42, v43
	v_cvt_pk_bf16_f32 v70, v44, v45
	v_cvt_pk_bf16_f32 v71, v46, v47
	v_pk_add_f32 v[232:233], v[232:233], v[32:33]
	v_pk_add_f32 v[232:233], v[232:233], v[34:35]
	v_pk_add_f32 v[232:233], v[232:233], v[36:37]
	v_pk_add_f32 v[232:233], v[232:233], v[38:39]
	v_pk_add_f32 v[232:233], v[232:233], v[40:41]
	v_pk_add_f32 v[232:233], v[232:233], v[42:43]
	v_pk_add_f32 v[232:233], v[232:233], v[44:45]
	v_pk_add_f32 v[232:233], v[232:233], v[46:47]
	s_waitcnt lgkmcnt(0)
	v_mfma_f32_32x32x16_bf16 v[0:15], v[64:67], v[72:75], v[0:15]
	v_mfma_f32_32x32x16_bf16 v[16:31], v[64:67], v[76:79], v[16:31]
	v_mfma_f32_32x32x16_bf16 v[0:15], v[68:71], v[220:223], v[0:15]
	v_mfma_f32_32x32x16_bf16 v[16:31], v[68:71], v[224:227], v[16:31]
	s_waitcnt vmcnt(0)
	ds_write_b128 v247, v[188:191]
	ds_write_b128 v247, v[192:195] offset:1152
	ds_write_b128 v247, v[196:199] offset:2304
	ds_write_b128 v247, v[200:203] offset:3456
	ds_write_b128 v112, v[204:207]
	ds_write_b128 v112, v[208:211] offset:1024
	ds_write_b128 v112, v[212:215] offset:2048
	ds_write_b128 v112, v[216:219] offset:3072
	ds_read2_b32 v[32:33], v115 offset0:128 offset1:129
	ds_read2_b32 v[34:35], v115 offset0:130 offset1:131
	ds_read2_b32 v[36:37], v115 offset0:136 offset1:137
	ds_read2_b32 v[38:39], v115 offset0:138 offset1:139
	ds_read2_b32 v[40:41], v115 offset0:144 offset1:145
	ds_read2_b32 v[42:43], v115 offset0:146 offset1:147
	ds_read2_b32 v[44:45], v115 offset0:152 offset1:153
	ds_read2_b32 v[46:47], v115 offset0:154 offset1:155
	ds_read_b128 v[188:191], v248
	ds_read_b128 v[192:195], v248 offset:32
	ds_read_b128 v[196:199], v248 offset:64
	ds_read_b128 v[200:203], v248 offset:96
	ds_read_b64_tr_b16 v[72:73], v231
	ds_read_b64_tr_b16 v[74:75], v231 offset:512
	ds_read_b64_tr_b16 v[76:77], v231 offset:2048
	ds_read_b64_tr_b16 v[78:79], v231 offset:2560
	ds_read_b64_tr_b16 v[220:221], v231 offset:1024
	ds_read_b64_tr_b16 v[222:223], v231 offset:1536
	ds_read_b64_tr_b16 v[224:225], v231 offset:3072
	ds_read_b64_tr_b16 v[226:227], v231 offset:3584
	s_waitcnt lgkmcnt(8)
	v_mfma_f32_32x32x16_bf16 v[32:47], v[188:191], v[48:51], v[32:47]
	v_mfma_f32_32x32x16_bf16 v[32:47], v[192:195], v[52:55], v[32:47]
	v_mfma_f32_32x32x16_bf16 v[32:47], v[196:199], v[56:59], v[32:47]
	v_mfma_f32_32x32x16_bf16 v[32:47], v[200:203], v[60:63], v[32:47]
	s_nop 11
	v_exp_f32_e32 v32, v32
	v_exp_f32_e32 v33, v33
	v_exp_f32_e32 v34, v34
	v_exp_f32_e32 v35, v35
	v_exp_f32_e32 v36, v36
	v_exp_f32_e32 v37, v37
	v_exp_f32_e32 v38, v38
	v_exp_f32_e32 v39, v39
	v_exp_f32_e32 v40, v40
	v_exp_f32_e32 v41, v41
	v_exp_f32_e32 v42, v42
	v_exp_f32_e32 v43, v43
	v_exp_f32_e32 v44, v44
	v_exp_f32_e32 v45, v45
	v_exp_f32_e32 v46, v46
	v_exp_f32_e32 v47, v47
	v_cvt_pk_bf16_f32 v64, v32, v33
	v_cvt_pk_bf16_f32 v65, v34, v35
	v_cvt_pk_bf16_f32 v66, v36, v37
	v_cvt_pk_bf16_f32 v67, v38, v39
	v_cvt_pk_bf16_f32 v68, v40, v41
	v_cvt_pk_bf16_f32 v69, v42, v43
	v_cvt_pk_bf16_f32 v70, v44, v45
	v_cvt_pk_bf16_f32 v71, v46, v47
	v_pk_add_f32 v[232:233], v[232:233], v[32:33]
	v_pk_add_f32 v[232:233], v[232:233], v[34:35]
	v_pk_add_f32 v[232:233], v[232:233], v[36:37]
	v_pk_add_f32 v[232:233], v[232:233], v[38:39]
	v_pk_add_f32 v[232:233], v[232:233], v[40:41]
	v_pk_add_f32 v[232:233], v[232:233], v[42:43]
	v_pk_add_f32 v[232:233], v[232:233], v[44:45]
	v_pk_add_f32 v[232:233], v[232:233], v[46:47]
	s_waitcnt lgkmcnt(0)
	v_mfma_f32_32x32x16_bf16 v[0:15], v[64:67], v[72:75], v[0:15]
	v_mfma_f32_32x32x16_bf16 v[16:31], v[64:67], v[76:79], v[16:31]
	v_mfma_f32_32x32x16_bf16 v[0:15], v[68:71], v[220:223], v[0:15]
	v_mfma_f32_32x32x16_bf16 v[16:31], v[68:71], v[224:227], v[16:31]
	v_add_f32_e32 v113, v232, v233
	v_or_b32_e32 v114, 1, v107
	v_or_b32_e32 v97, 2, v107
	v_or_b32_e32 v96, 3, v107
	v_or_b32_e32 v95, 8, v107
	v_or_b32_e32 v94, 9, v107
	v_or_b32_e32 v93, 10, v107
	v_or_b32_e32 v92, 11, v107
	v_or_b32_e32 v91, 16, v107
	v_or_b32_e32 v90, 17, v107
	v_or_b32_e32 v89, 18, v107
	v_or_b32_e32 v88, 19, v107
	v_or_b32_e32 v87, 24, v107
	v_or_b32_e32 v86, 25, v107
	v_or_b32_e32 v85, 26, v107
	v_or_b32_e32 v84, 27, v107
	s_nop 11
	s_branch .LBB0_553

; #define LAS __attribute__((address_space(3)))
; #define GAS __attribute__((address_space(1)))
; __device__ __forceinline__ void dil_unit(LAS unsigned char* lds, bf16_t* proj, int seq, int hd, int T0, int rho) {
;     int tid_ = threadIdx.x; asm volatile("" : "+v"(tid_));
;     const int tid = tid_, lane = tid & 63, r32 = lane & 31, hi = lane >> 5, wid = __builtin_amdgcn_readfirstlane(tid >> 6);
;     bf16_t* base = proj + (size_t)seq * SEQ * NIN;
;     LAS unsigned char* wbuf = lds + wid * 4096;
;     const LAS unsigned char* vp = wbuf + ((lane >> 4) & 1) * 32 + (lane & 3) * 8 + (4 * hi + ((lane & 15) >> 2)) * 64;
;     const int P0 = T0 + rho;
;     bf16x8 qr[4];
; #pragma unroll
;     for (int ks = 0; ks < 4; ++ks) qr[ks] = *(const GAS bf16x8*)(base + (size_t)(P0 + 16 * r32) * NIN + PC_LQ + hd * 64 + 16 * ks + 8 * hi);
;     f32x16 o0 = {}, o1 = {}; float l = 0.f;
;     const bool bound = (T0 < 1024) || (T0 >= 15360);
.LBB0_1266:
	s_lshr_b32 s82, s60, 8
	s_mul_i32 s82, s82, 13
	s_add_i32 s82, s82, s60
	s_ashr_i32 s4, s60, 6
	s_mul_hi_i32 s9, s4, 0x2aaaaaab
	s_lshl_b32 s5, s82, 8
	s_lshr_b32 s10, s9, 31
	s_and_b32 s8, s5, 0x3e00
	s_lshl_b32 s5, s82, 3
	s_add_i32 s9, s9, s10
	s_and_b32 s5, s5, 8
	s_mul_i32 s10, s9, 6
	s_add_i32 s5, s5, s61
	s_sub_i32 s10, s4, s10
	s_mul_hi_i32 s4, s9, 0x6000000
	s_mul_i32 s9, s9, 0x6000000
	v_mov_b32_e32 v2, v154
	s_add_u32 s52, s44, s9
	s_addc_u32 s53, s45, s4
	v_and_b32_e32 v105, 31, v2
	s_add_i32 s67, s5, s8
	v_lshl_add_u32 v3, v105, 4, s67
	v_mov_b64_e32 v[0:1], s[52:53]
	s_lshl_b32 s54, s10, 6
	v_bfe_u32 v106, v2, 5, 1
	v_mad_u64_u32 v[0:1], s[4:5], v3, s62, v[0:1]
	s_ashr_i32 s55, s54, 31
	v_lshl_add_u64 v[0:1], s[54:55], 1, v[0:1]
	v_lshlrev_b32_e32 v80, 4, v106
	v_lshl_add_u64 v[0:1], v[0:1], 0, v[80:81]
	global_load_dwordx4 v[48:51], v[0:1], off offset:1280
	global_load_dwordx4 v[52:55], v[0:1], off offset:1312
	global_load_dwordx4 v[56:59], v[0:1], off offset:1344
	global_load_dwordx4 v[60:63], v[0:1], off offset:1376
	v_readfirstlane_b32 s4, v2
	s_lshl_b32 s4, s4, 6
	s_and_b32 s4, s4, 0xfffff000
	v_lshlrev_b32_e32 v0, 1, v2
	v_lshlrev_b32_e32 v104, 3, v2
	v_lshlrev_b32_e32 v107, 2, v106
	v_lshrrev_b32_e32 v1, 2, v2
	v_and_b32_e32 v103, 63, v2
	v_and_b32_e32 v0, 32, v0
	v_and_b32_e32 v98, 24, v104
	v_and_or_b32 v1, v1, 3, v107
	s_add_i32 s69, s4, 0
	v_lshlrev_b32_e32 v108, 6, v1
	v_lshlrev_b32_e32 v1, 3, v106
	v_add3_u32 v109, s69, v0, v98
	s_addk_i32 s8, 0xc400
	v_lshrrev_b32_e32 v110, 2, v103
	v_lshlrev_b32_e32 v0, 4, v103
	s_mov_b64 s[4:5], -1
	s_cmp_gt_u32 s8, 0xffffc7ff
	v_lshlrev_b32_e32 v100, 1, v98
	s_mul_i32 s8, s10, 0x1c00
	v_lshlrev_b32_e32 v82, 1, v1
	v_or_b32_e32 v111, 16, v110
	v_add_u32_e32 v112, s69, v0
	s_cbranch_scc0 .LBB0_1270
	s_movk_i32 s100, 0x1800
	s_add_i32 s101, s8, 0x15c00
	s_lshl_b32 s90, s54, 1
	s_add_u32 s82, s52, s90
	s_addc_u32 s83, s53, 0
	s_add_u32 s82, s82, 0x1200
	s_addc_u32 s83, s83, 0
	s_sub_i32 s90, s67, 64
	s_mul_i32 s90, s90, 0x1800
	s_add_u32 s84, s82, s90
	s_addc_u32 s85, s83, 0
	s_sub_i32 s90, s67, 256
	s_mul_i32 s90, s90, 0x1800
	s_add_u32 s86, s82, s90
	s_addc_u32 s87, s83, 0
	s_sub_i32 s90, s67, 1024
	s_mul_i32 s90, s90, 0x1800
	s_add_u32 s88, s82, s90
	s_addc_u32 s89, s83, 0
	v_lshlrev_b32_e32 v153, 1, v98
	v_mad_u32_u24 v80, v105, s100, v82
	v_mad_u32_u24 v100, v110, s100, v153
	v_add_u32_e32 v149, 0x18000, v100
	v_lshlrev_b32_e32 v83, 2, v105
	v_mad_u32_u24 v83, v83, s100, v82
	v_lshlrev_b32_e32 v101, 2, v110
	v_mad_u32_u24 v101, v101, s100, v153
	v_add_u32_e32 v150, 0x60000, v101
	v_lshlrev_b32_e32 v99, 4, v105
	v_mad_u32_u24 v99, v99, s100, v82
	v_lshlrev_b32_e32 v148, 4, v110
	v_mad_u32_u24 v148, v148, s100, v153
	v_add_u32_e32 v151, 0x180000, v148
	s_lshr_b32 s90, s69, 12
	s_mul_i32 s90, s90, 4608
	s_add_i32 s91, s90, 0x8000
	s_movk_i32 s35, 144
	v_lshrrev_b32_e32 v249, 3, v103
	v_and_b32_e32 v250, 7, v103
	v_lshlrev_b32_e32 v250, 4, v250
	v_mad_u32_u24 v247, v249, s35, v250
	v_add_u32_e32 v247, s91, v247
	v_mad_u32_u24 v248, v105, s35, v82
	v_add_u32_e32 v248, s91, v248
	v_add_u32_e32 v235, 0, v249
	v_mad_u32_u24 v235, v235, s100, v250
	v_add_u32_e32 v236, 8, v249
	v_mad_u32_u24 v236, v236, s100, v250
	v_add_u32_e32 v237, 16, v249
	v_mad_u32_u24 v237, v237, s100, v250
	v_add_u32_e32 v238, 24, v249
	v_mad_u32_u24 v238, v238, s100, v250
	v_add_u32_e32 v239, 0, v249
	v_lshlrev_b32_e32 v239, 2, v239
	v_mad_u32_u24 v239, v239, s100, v250
	v_add_u32_e32 v240, 8, v249
	v_lshlrev_b32_e32 v240, 2, v240
	v_mad_u32_u24 v240, v240, s100, v250
	v_add_u32_e32 v241, 16, v249
	v_lshlrev_b32_e32 v241, 2, v241
	v_mad_u32_u24 v241, v241, s100, v250
	v_add_u32_e32 v242, 24, v249
	v_lshlrev_b32_e32 v242, 2, v242
	v_mad_u32_u24 v242, v242, s100, v250
	v_add_u32_e32 v243, 0, v249
	v_lshlrev_b32_e32 v243, 4, v243
	v_mad_u32_u24 v243, v243, s100, v250
	v_add_u32_e32 v244, 8, v249
	v_lshlrev_b32_e32 v244, 4, v244
	v_mad_u32_u24 v244, v244, s100, v250
	v_add_u32_e32 v245, 16, v249
	v_lshlrev_b32_e32 v245, 4, v245
	v_mad_u32_u24 v245, v245, s100, v250
	v_add_u32_e32 v246, 24, v249
	v_lshlrev_b32_e32 v246, 4, v246
	v_mad_u32_u24 v246, v246, s100, v250
	v_lshlrev_b32_e32 v228, 4, v105
	v_sub_u32_e32 v228, v107, v228
	s_add_i32 s90, s101, 1984
	v_lshl_add_u32 v228, v228, 2, s90
	v_lshlrev_b32_e32 v229, 2, v105
	v_sub_u32_e32 v229, v107, v229
	s_add_i32 s90, s101, 5104
	v_lshl_add_u32 v229, v229, 2, s90
	v_sub_u32_e32 v230, v107, v105
	s_add_i32 s90, s101, 6364
	v_lshl_add_u32 v230, v230, 2, s90
	v_add_u32_e32 v231, v109, v108
	v_mov_b64_e32 v[232:233], 0
	v_mov_b64_e32 v[0:1], 0
	v_mov_b64_e32 v[2:3], 0
	v_mov_b64_e32 v[4:5], 0
	v_mov_b64_e32 v[6:7], 0
	v_mov_b64_e32 v[8:9], 0
	v_mov_b64_e32 v[10:11], 0
	v_mov_b64_e32 v[12:13], 0
	v_mov_b64_e32 v[14:15], 0
	v_mov_b64_e32 v[16:17], 0
	v_mov_b64_e32 v[18:19], 0
	v_mov_b64_e32 v[20:21], 0
	v_mov_b64_e32 v[22:23], 0
	v_mov_b64_e32 v[24:25], 0
	v_mov_b64_e32 v[26:27], 0
	v_mov_b64_e32 v[28:29], 0
	v_mov_b64_e32 v[30:31], 0
	global_load_dwordx4 v[116:119], v235, s[84:85]
	global_load_dwordx4 v[120:123], v236, s[84:85]
	global_load_dwordx4 v[124:127], v237, s[84:85]
	global_load_dwordx4 v[128:131], v238, s[84:85]
	global_load_dwordx4 v[132:135], v100, s[84:85] offset:768
	global_load_dwordx4 v[136:139], v149, s[84:85] offset:768
	global_load_dwordx4 v[140:143], v100, s[84:85] offset:832
	global_load_dwordx4 v[144:147], v149, s[84:85] offset:832
	s_add_u32 s84, s84, 0x30000
	s_addc_u32 s85, s85, 0
	global_load_dwordx4 v[156:159], v235, s[84:85]
	global_load_dwordx4 v[160:163], v236, s[84:85]
	global_load_dwordx4 v[164:167], v237, s[84:85]
	global_load_dwordx4 v[168:171], v238, s[84:85]
	global_load_dwordx4 v[172:175], v100, s[84:85] offset:768
	global_load_dwordx4 v[176:179], v149, s[84:85] offset:768
	global_load_dwordx4 v[180:183], v100, s[84:85] offset:832
	global_load_dwordx4 v[184:187], v149, s[84:85] offset:832
	s_add_u32 s84, s84, 0x30000
	s_addc_u32 s85, s85, 0
	global_load_dwordx4 v[188:191], v235, s[84:85]
	global_load_dwordx4 v[192:195], v236, s[84:85]
	global_load_dwordx4 v[196:199], v237, s[84:85]
	global_load_dwordx4 v[200:203], v238, s[84:85]
	global_load_dwordx4 v[204:207], v100, s[84:85] offset:768
	global_load_dwordx4 v[208:211], v149, s[84:85] offset:768
	global_load_dwordx4 v[212:215], v100, s[84:85] offset:832
	global_load_dwordx4 v[216:219], v149, s[84:85] offset:832
	s_add_u32 s84, s84, 0x30000
	s_addc_u32 s85, s85, 0
	s_waitcnt vmcnt(16)
	ds_write_b128 v247, v[116:119]
	ds_write_b128 v247, v[120:123] offset:1152
	ds_write_b128 v247, v[124:127] offset:2304
	ds_write_b128 v247, v[128:131] offset:3456
	ds_write_b128 v112, v[132:135]
	ds_write_b128 v112, v[136:139] offset:1024
	ds_write_b128 v112, v[140:143] offset:2048
	ds_write_b128 v112, v[144:147] offset:3072
	v_mov_b32_e32 v115, v228
	ds_read2_b32 v[32:33], v115 offset0:0 offset1:1
	ds_read2_b32 v[34:35], v115 offset0:2 offset1:3
	ds_read2_b32 v[36:37], v115 offset0:8 offset1:9
	ds_read2_b32 v[38:39], v115 offset0:10 offset1:11
	ds_read2_b32 v[40:41], v115 offset0:16 offset1:17
	ds_read2_b32 v[42:43], v115 offset0:18 offset1:19
	ds_read2_b32 v[44:45], v115 offset0:24 offset1:25
	ds_read2_b32 v[46:47], v115 offset0:26 offset1:27
	ds_read_b128 v[116:119], v248
	ds_read_b128 v[120:123], v248 offset:32
	ds_read_b128 v[124:127], v248 offset:64
	ds_read_b128 v[128:131], v248 offset:96
	ds_read_b64_tr_b16 v[72:73], v231
	ds_read_b64_tr_b16 v[74:75], v231 offset:512
	ds_read_b64_tr_b16 v[76:77], v231 offset:2048
	ds_read_b64_tr_b16 v[78:79], v231 offset:2560
	ds_read_b64_tr_b16 v[220:221], v231 offset:1024
	ds_read_b64_tr_b16 v[222:223], v231 offset:1536
	ds_read_b64_tr_b16 v[224:225], v231 offset:3072
	ds_read_b64_tr_b16 v[226:227], v231 offset:3584
	s_waitcnt lgkmcnt(8)
	v_mfma_f32_32x32x16_bf16 v[32:47], v[116:119], v[48:51], v[32:47]
	v_mfma_f32_32x32x16_bf16 v[32:47], v[120:123], v[52:55], v[32:47]
	v_mfma_f32_32x32x16_bf16 v[32:47], v[124:127], v[56:59], v[32:47]
	v_mfma_f32_32x32x16_bf16 v[32:47], v[128:131], v[60:63], v[32:47]
	s_nop 11
	v_exp_f32_e32 v32, v32
	v_exp_f32_e32 v33, v33
	v_exp_f32_e32 v34, v34
	v_exp_f32_e32 v35, v35
	v_exp_f32_e32 v36, v36
	v_exp_f32_e32 v37, v37
	v_exp_f32_e32 v38, v38
	v_exp_f32_e32 v39, v39
	v_exp_f32_e32 v40, v40
	v_exp_f32_e32 v41, v41
	v_exp_f32_e32 v42, v42
	v_exp_f32_e32 v43, v43
	v_exp_f32_e32 v44, v44
	v_exp_f32_e32 v45, v45
	v_exp_f32_e32 v46, v46
	v_exp_f32_e32 v47, v47
	v_cvt_pk_bf16_f32 v64, v32, v33
	v_cvt_pk_bf16_f32 v65, v34, v35
	v_cvt_pk_bf16_f32 v66, v36, v37
	v_cvt_pk_bf16_f32 v67, v38, v39
	v_cvt_pk_bf16_f32 v68, v40, v41
	v_cvt_pk_bf16_f32 v69, v42, v43
	v_cvt_pk_bf16_f32 v70, v44, v45
	v_cvt_pk_bf16_f32 v71, v46, v47
	v_pk_add_f32 v[232:233], v[232:233], v[32:33]
	v_pk_add_f32 v[232:233], v[232:233], v[34:35]
	v_pk_add_f32 v[232:233], v[232:233], v[36:37]
	v_pk_add_f32 v[232:233], v[232:233], v[38:39]
	v_pk_add_f32 v[232:233], v[232:233], v[40:41]
	v_pk_add_f32 v[232:233], v[232:233], v[42:43]
	v_pk_add_f32 v[232:233], v[232:233], v[44:45]
	v_pk_add_f32 v[232:233], v[232:233], v[46:47]
	s_waitcnt lgkmcnt(0)
	v_mfma_f32_32x32x16_bf16 v[0:15], v[64:67], v[72:75], v[0:15]
	v_mfma_f32_32x32x16_bf16 v[16:31], v[64:67], v[76:79], v[16:31]
	v_mfma_f32_32x32x16_bf16 v[0:15], v[68:71], v[220:223], v[0:15]
	v_mfma_f32_32x32x16_bf16 v[16:31], v[68:71], v[224:227], v[16:31]
	global_load_dwordx4 v[116:119], v235, s[84:85]
	global_load_dwordx4 v[120:123], v236, s[84:85]
	global_load_dwordx4 v[124:127], v237, s[84:85]
	global_load_dwordx4 v[128:131], v238, s[84:85]
	global_load_dwordx4 v[132:135], v100, s[84:85] offset:768
	global_load_dwordx4 v[136:139], v149, s[84:85] offset:768
	global_load_dwordx4 v[140:143], v100, s[84:85] offset:832
	global_load_dwordx4 v[144:147], v149, s[84:85] offset:832
	s_add_u32 s84, s84, 0x30000
	s_addc_u32 s85, s85, 0
	s_waitcnt vmcnt(16)
	ds_write_b128 v247, v[156:159]
	ds_write_b128 v247, v[160:163] offset:1152
	ds_write_b128 v247, v[164:167] offset:2304
	ds_write_b128 v247, v[168:171] offset:3456
	ds_write_b128 v112, v[172:175]
	ds_write_b128 v112, v[176:179] offset:1024
	ds_write_b128 v112, v[180:183] offset:2048
	ds_write_b128 v112, v[184:187] offset:3072
	ds_read2_b32 v[32:33], v115 offset0:32 offset1:33
	ds_read2_b32 v[34:35], v115 offset0:34 offset1:35
	ds_read2_b32 v[36:37], v115 offset0:40 offset1:41
	ds_read2_b32 v[38:39], v115 offset0:42 offset1:43
	ds_read2_b32 v[40:41], v115 offset0:48 offset1:49
	ds_read2_b32 v[42:43], v115 offset0:50 offset1:51
	ds_read2_b32 v[44:45], v115 offset0:56 offset1:57
	ds_read2_b32 v[46:47], v115 offset0:58 offset1:59
	ds_read_b128 v[156:159], v248
	ds_read_b128 v[160:163], v248 offset:32
	ds_read_b128 v[164:167], v248 offset:64
	ds_read_b128 v[168:171], v248 offset:96
	ds_read_b64_tr_b16 v[72:73], v231
	ds_read_b64_tr_b16 v[74:75], v231 offset:512
	ds_read_b64_tr_b16 v[76:77], v231 offset:2048
	ds_read_b64_tr_b16 v[78:79], v231 offset:2560
	ds_read_b64_tr_b16 v[220:221], v231 offset:1024
	ds_read_b64_tr_b16 v[222:223], v231 offset:1536
	ds_read_b64_tr_b16 v[224:225], v231 offset:3072
	ds_read_b64_tr_b16 v[226:227], v231 offset:3584
	s_waitcnt lgkmcnt(8)
	v_mfma_f32_32x32x16_bf16 v[32:47], v[156:159], v[48:51], v[32:47]
	v_mfma_f32_32x32x16_bf16 v[32:47], v[160:163], v[52:55], v[32:47]
	v_mfma_f32_32x32x16_bf16 v[32:47], v[164:167], v[56:59], v[32:47]
	v_mfma_f32_32x32x16_bf16 v[32:47], v[168:171], v[60:63], v[32:47]
	s_nop 11
	v_exp_f32_e32 v32, v32
	v_exp_f32_e32 v33, v33
	v_exp_f32_e32 v34, v34
	v_exp_f32_e32 v35, v35
	v_exp_f32_e32 v36, v36
	v_exp_f32_e32 v37, v37
	v_exp_f32_e32 v38, v38
	v_exp_f32_e32 v39, v39
	v_exp_f32_e32 v40, v40
	v_exp_f32_e32 v41, v41
	v_exp_f32_e32 v42, v42
	v_exp_f32_e32 v43, v43
	v_exp_f32_e32 v44, v44
	v_exp_f32_e32 v45, v45
	v_exp_f32_e32 v46, v46
	v_exp_f32_e32 v47, v47
	v_cvt_pk_bf16_f32 v64, v32, v33
	v_cvt_pk_bf16_f32 v65, v34, v35
	v_cvt_pk_bf16_f32 v66, v36, v37
	v_cvt_pk_bf16_f32 v67, v38, v39
	v_cvt_pk_bf16_f32 v68, v40, v41
	v_cvt_pk_bf16_f32 v69, v42, v43
	v_cvt_pk_bf16_f32 v70, v44, v45
	v_cvt_pk_bf16_f32 v71, v46, v47
	v_pk_add_f32 v[232:233], v[232:233], v[32:33]
	v_pk_add_f32 v[232:233], v[232:233], v[34:35]
	v_pk_add_f32 v[232:233], v[232:233], v[36:37]
	v_pk_add_f32 v[232:233], v[232:233], v[38:39]
	v_pk_add_f32 v[232:233], v[232:233], v[40:41]
	v_pk_add_f32 v[232:233], v[232:233], v[42:43]
	v_pk_add_f32 v[232:233], v[232:233], v[44:45]
	v_pk_add_f32 v[232:233], v[232:233], v[46:47]
	s_waitcnt lgkmcnt(0)
	v_mfma_f32_32x32x16_bf16 v[0:15], v[64:67], v[72:75], v[0:15]
	v_mfma_f32_32x32x16_bf16 v[16:31], v[64:67], v[76:79], v[16:31]
	v_mfma_f32_32x32x16_bf16 v[0:15], v[68:71], v[220:223], v[0:15]
	v_mfma_f32_32x32x16_bf16 v[16:31], v[68:71], v[224:227], v[16:31]
	global_load_dwordx4 v[156:159], v235, s[84:85]
	global_load_dwordx4 v[160:163], v236, s[84:85]
	global_load_dwordx4 v[164:167], v237, s[84:85]
	global_load_dwordx4 v[168:171], v238, s[84:85]
	global_load_dwordx4 v[172:175], v100, s[84:85] offset:768
	global_load_dwordx4 v[176:179], v149, s[84:85] offset:768
	global_load_dwordx4 v[180:183], v100, s[84:85] offset:832
	global_load_dwordx4 v[184:187], v149, s[84:85] offset:832
	s_add_u32 s84, s84, 0x30000
	s_addc_u32 s85, s85, 0
	s_waitcnt vmcnt(16)
	ds_write_b128 v247, v[188:191]
	ds_write_b128 v247, v[192:195] offset:1152
	ds_write_b128 v247, v[196:199] offset:2304
	ds_write_b128 v247, v[200:203] offset:3456
	ds_write_b128 v112, v[204:207]
	ds_write_b128 v112, v[208:211] offset:1024
	ds_write_b128 v112, v[212:215] offset:2048
	ds_write_b128 v112, v[216:219] offset:3072
	ds_read2_b32 v[32:33], v115 offset0:64 offset1:65
	ds_read2_b32 v[34:35], v115 offset0:66 offset1:67
	ds_read2_b32 v[36:37], v115 offset0:72 offset1:73
	ds_read2_b32 v[38:39], v115 offset0:74 offset1:75
	ds_read2_b32 v[40:41], v115 offset0:80 offset1:81
	ds_read2_b32 v[42:43], v115 offset0:82 offset1:83
	ds_read2_b32 v[44:45], v115 offset0:88 offset1:89
	ds_read2_b32 v[46:47], v115 offset0:90 offset1:91
	ds_read_b128 v[188:191], v248
	ds_read_b128 v[192:195], v248 offset:32
	ds_read_b128 v[196:199], v248 offset:64
	ds_read_b128 v[200:203], v248 offset:96
	ds_read_b64_tr_b16 v[72:73], v231
	ds_read_b64_tr_b16 v[74:75], v231 offset:512
	ds_read_b64_tr_b16 v[76:77], v231 offset:2048
	ds_read_b64_tr_b16 v[78:79], v231 offset:2560
	ds_read_b64_tr_b16 v[220:221], v231 offset:1024
	ds_read_b64_tr_b16 v[222:223], v231 offset:1536
	ds_read_b64_tr_b16 v[224:225], v231 offset:3072
	ds_read_b64_tr_b16 v[226:227], v231 offset:3584
	s_waitcnt lgkmcnt(8)
	v_mfma_f32_32x32x16_bf16 v[32:47], v[188:191], v[48:51], v[32:47]
	v_mfma_f32_32x32x16_bf16 v[32:47], v[192:195], v[52:55], v[32:47]
	v_mfma_f32_32x32x16_bf16 v[32:47], v[196:199], v[56:59], v[32:47]
	v_mfma_f32_32x32x16_bf16 v[32:47], v[200:203], v[60:63], v[32:47]
	s_nop 11
	v_exp_f32_e32 v32, v32
	v_exp_f32_e32 v33, v33
	v_exp_f32_e32 v34, v34
	v_exp_f32_e32 v35, v35
	v_exp_f32_e32 v36, v36
	v_exp_f32_e32 v37, v37
	v_exp_f32_e32 v38, v38
	v_exp_f32_e32 v39, v39
	v_exp_f32_e32 v40, v40
	v_exp_f32_e32 v41, v41
	v_exp_f32_e32 v42, v42
	v_exp_f32_e32 v43, v43
	v_exp_f32_e32 v44, v44
	v_exp_f32_e32 v45, v45
	v_exp_f32_e32 v46, v46
	v_exp_f32_e32 v47, v47
	v_cvt_pk_bf16_f32 v64, v32, v33
	v_cvt_pk_bf16_f32 v65, v34, v35
	v_cvt_pk_bf16_f32 v66, v36, v37
	v_cvt_pk_bf16_f32 v67, v38, v39
	v_cvt_pk_bf16_f32 v68, v40, v41
	v_cvt_pk_bf16_f32 v69, v42, v43
	v_cvt_pk_bf16_f32 v70, v44, v45
	v_cvt_pk_bf16_f32 v71, v46, v47
	v_pk_add_f32 v[232:233], v[232:233], v[32:33]
	v_pk_add_f32 v[232:233], v[232:233], v[34:35]
	v_pk_add_f32 v[232:233], v[232:233], v[36:37]
	v_pk_add_f32 v[232:233], v[232:233], v[38:39]
	v_pk_add_f32 v[232:233], v[232:233], v[40:41]
	v_pk_add_f32 v[232:233], v[232:233], v[42:43]
	v_pk_add_f32 v[232:233], v[232:233], v[44:45]
	v_pk_add_f32 v[232:233], v[232:233], v[46:47]
	s_waitcnt lgkmcnt(0)
	v_mfma_f32_32x32x16_bf16 v[0:15], v[64:67], v[72:75], v[0:15]
	v_mfma_f32_32x32x16_bf16 v[16:31], v[64:67], v[76:79], v[16:31]
	v_mfma_f32_32x32x16_bf16 v[0:15], v[68:71], v[220:223], v[0:15]
	v_mfma_f32_32x32x16_bf16 v[16:31], v[68:71], v[224:227], v[16:31]
	global_load_dwordx4 v[188:191], v235, s[84:85]
	global_load_dwordx4 v[192:195], v236, s[84:85]
	global_load_dwordx4 v[196:199], v237, s[84:85]
	global_load_dwordx4 v[200:203], v238, s[84:85]
	global_load_dwordx4 v[204:207], v100, s[84:85] offset:768
	global_load_dwordx4 v[208:211], v149, s[84:85] offset:768
	global_load_dwordx4 v[212:215], v100, s[84:85] offset:832
	global_load_dwordx4 v[216:219], v149, s[84:85] offset:832
	s_add_u32 s84, s84, 0x30000
	s_addc_u32 s85, s85, 0
	s_waitcnt vmcnt(16)
	ds_write_b128 v247, v[116:119]
	ds_write_b128 v247, v[120:123] offset:1152
	ds_write_b128 v247, v[124:127] offset:2304
	ds_write_b128 v247, v[128:131] offset:3456
	ds_write_b128 v112, v[132:135]
	ds_write_b128 v112, v[136:139] offset:1024
	ds_write_b128 v112, v[140:143] offset:2048
	ds_write_b128 v112, v[144:147] offset:3072
	ds_read2_b32 v[32:33], v115 offset0:96 offset1:97
	ds_read2_b32 v[34:35], v115 offset0:98 offset1:99
	ds_read2_b32 v[36:37], v115 offset0:104 offset1:105
	ds_read2_b32 v[38:39], v115 offset0:106 offset1:107
	ds_read2_b32 v[40:41], v115 offset0:112 offset1:113
	ds_read2_b32 v[42:43], v115 offset0:114 offset1:115
	ds_read2_b32 v[44:45], v115 offset0:120 offset1:121
	ds_read2_b32 v[46:47], v115 offset0:122 offset1:123
	ds_read_b128 v[116:119], v248
	ds_read_b128 v[120:123], v248 offset:32
	ds_read_b128 v[124:127], v248 offset:64
	ds_read_b128 v[128:131], v248 offset:96
	ds_read_b64_tr_b16 v[72:73], v231
	ds_read_b64_tr_b16 v[74:75], v231 offset:512
	ds_read_b64_tr_b16 v[76:77], v231 offset:2048
	ds_read_b64_tr_b16 v[78:79], v231 offset:2560
	ds_read_b64_tr_b16 v[220:221], v231 offset:1024
	ds_read_b64_tr_b16 v[222:223], v231 offset:1536
	ds_read_b64_tr_b16 v[224:225], v231 offset:3072
	ds_read_b64_tr_b16 v[226:227], v231 offset:3584
	s_waitcnt lgkmcnt(8)
	v_mfma_f32_32x32x16_bf16 v[32:47], v[116:119], v[48:51], v[32:47]
	v_mfma_f32_32x32x16_bf16 v[32:47], v[120:123], v[52:55], v[32:47]
	v_mfma_f32_32x32x16_bf16 v[32:47], v[124:127], v[56:59], v[32:47]
	v_mfma_f32_32x32x16_bf16 v[32:47], v[128:131], v[60:63], v[32:47]
	s_nop 11
	v_exp_f32_e32 v32, v32
	v_exp_f32_e32 v33, v33
	v_exp_f32_e32 v34, v34
	v_exp_f32_e32 v35, v35
	v_exp_f32_e32 v36, v36
	v_exp_f32_e32 v37, v37
	v_exp_f32_e32 v38, v38
	v_exp_f32_e32 v39, v39
	v_exp_f32_e32 v40, v40
	v_exp_f32_e32 v41, v41
	v_exp_f32_e32 v42, v42
	v_exp_f32_e32 v43, v43
	v_exp_f32_e32 v44, v44
	v_exp_f32_e32 v45, v45
	v_exp_f32_e32 v46, v46
	v_exp_f32_e32 v47, v47
	v_cvt_pk_bf16_f32 v64, v32, v33
	v_cvt_pk_bf16_f32 v65, v34, v35
	v_cvt_pk_bf16_f32 v66, v36, v37
	v_cvt_pk_bf16_f32 v67, v38, v39
	v_cvt_pk_bf16_f32 v68, v40, v41
	v_cvt_pk_bf16_f32 v69, v42, v43
	v_cvt_pk_bf16_f32 v70, v44, v45
	v_cvt_pk_bf16_f32 v71, v46, v47
	v_pk_add_f32 v[232:233], v[232:233], v[32:33]
	v_pk_add_f32 v[232:233], v[232:233], v[34:35]
	v_pk_add_f32 v[232:233], v[232:233], v[36:37]
	v_pk_add_f32 v[232:233], v[232:233], v[38:39]
	v_pk_add_f32 v[232:233], v[232:233], v[40:41]
	v_pk_add_f32 v[232:233], v[232:233], v[42:43]
	v_pk_add_f32 v[232:233], v[232:233], v[44:45]
	v_pk_add_f32 v[232:233], v[232:233], v[46:47]
	s_waitcnt lgkmcnt(0)
	v_mfma_f32_32x32x16_bf16 v[0:15], v[64:67], v[72:75], v[0:15]
	v_mfma_f32_32x32x16_bf16 v[16:31], v[64:67], v[76:79], v[16:31]
	v_mfma_f32_32x32x16_bf16 v[0:15], v[68:71], v[220:223], v[0:15]
	v_mfma_f32_32x32x16_bf16 v[16:31], v[68:71], v[224:227], v[16:31]
	global_load_dwordx4 v[116:119], v235, s[84:85]
	global_load_dwordx4 v[120:123], v236, s[84:85]
	global_load_dwordx4 v[124:127], v237, s[84:85]
	global_load_dwordx4 v[128:131], v238, s[84:85]
	global_load_dwordx4 v[132:135], v100, s[84:85] offset:768
	global_load_dwordx4 v[136:139], v149, s[84:85] offset:768
	global_load_dwordx4 v[140:143], v100, s[84:85] offset:832
	global_load_dwordx4 v[144:147], v149, s[84:85] offset:832
	s_add_u32 s84, s84, 0x30000
	s_addc_u32 s85, s85, 0
	s_waitcnt vmcnt(16)
	ds_write_b128 v247, v[156:159]
	ds_write_b128 v247, v[160:163] offset:1152
	ds_write_b128 v247, v[164:167] offset:2304
	ds_write_b128 v247, v[168:171] offset:3456
	ds_write_b128 v112, v[172:175]
	ds_write_b128 v112, v[176:179] offset:1024
	ds_write_b128 v112, v[180:183] offset:2048
	ds_write_b128 v112, v[184:187] offset:3072
	ds_read2_b32 v[32:33], v115 offset0:128 offset1:129
	ds_read2_b32 v[34:35], v115 offset0:130 offset1:131
	ds_read2_b32 v[36:37], v115 offset0:136 offset1:137
	ds_read2_b32 v[38:39], v115 offset0:138 offset1:139
	ds_read2_b32 v[40:41], v115 offset0:144 offset1:145
	ds_read2_b32 v[42:43], v115 offset0:146 offset1:147
	ds_read2_b32 v[44:45], v115 offset0:152 offset1:153
	ds_read2_b32 v[46:47], v115 offset0:154 offset1:155
	ds_read_b128 v[156:159], v248
	ds_read_b128 v[160:163], v248 offset:32
	ds_read_b128 v[164:167], v248 offset:64
	ds_read_b128 v[168:171], v248 offset:96
	ds_read_b64_tr_b16 v[72:73], v231
	ds_read_b64_tr_b16 v[74:75], v231 offset:512
	ds_read_b64_tr_b16 v[76:77], v231 offset:2048
	ds_read_b64_tr_b16 v[78:79], v231 offset:2560
	ds_read_b64_tr_b16 v[220:221], v231 offset:1024
	ds_read_b64_tr_b16 v[222:223], v231 offset:1536
	ds_read_b64_tr_b16 v[224:225], v231 offset:3072
	ds_read_b64_tr_b16 v[226:227], v231 offset:3584
	s_waitcnt lgkmcnt(8)
	v_mfma_f32_32x32x16_bf16 v[32:47], v[156:159], v[48:51], v[32:47]
	v_mfma_f32_32x32x16_bf16 v[32:47], v[160:163], v[52:55], v[32:47]
	v_mfma_f32_32x32x16_bf16 v[32:47], v[164:167], v[56:59], v[32:47]
	v_mfma_f32_32x32x16_bf16 v[32:47], v[168:171], v[60:63], v[32:47]
	s_nop 11
	v_exp_f32_e32 v32, v32
	v_exp_f32_e32 v33, v33
	v_exp_f32_e32 v34, v34
	v_exp_f32_e32 v35, v35
	v_exp_f32_e32 v36, v36
	v_exp_f32_e32 v37, v37
	v_exp_f32_e32 v38, v38
	v_exp_f32_e32 v39, v39
	v_exp_f32_e32 v40, v40
	v_exp_f32_e32 v41, v41
	v_exp_f32_e32 v42, v42
	v_exp_f32_e32 v43, v43
	v_exp_f32_e32 v44, v44
	v_exp_f32_e32 v45, v45
	v_exp_f32_e32 v46, v46
	v_exp_f32_e32 v47, v47
	v_cvt_pk_bf16_f32 v64, v32, v33
	v_cvt_pk_bf16_f32 v65, v34, v35
	v_cvt_pk_bf16_f32 v66, v36, v37
	v_cvt_pk_bf16_f32 v67, v38, v39
	v_cvt_pk_bf16_f32 v68, v40, v41
	v_cvt_pk_bf16_f32 v69, v42, v43
	v_cvt_pk_bf16_f32 v70, v44, v45
	v_cvt_pk_bf16_f32 v71, v46, v47
	v_pk_add_f32 v[232:233], v[232:233], v[32:33]
	v_pk_add_f32 v[232:233], v[232:233], v[34:35]
	v_pk_add_f32 v[232:233], v[232:233], v[36:37]
	v_pk_add_f32 v[232:233], v[232:233], v[38:39]
	v_pk_add_f32 v[232:233], v[232:233], v[40:41]
	v_pk_add_f32 v[232:233], v[232:233], v[42:43]
	v_pk_add_f32 v[232:233], v[232:233], v[44:45]
	v_pk_add_f32 v[232:233], v[232:233], v[46:47]
	s_waitcnt lgkmcnt(0)
	v_mfma_f32_32x32x16_bf16 v[0:15], v[64:67], v[72:75], v[0:15]
	v_mfma_f32_32x32x16_bf16 v[16:31], v[64:67], v[76:79], v[16:31]
	v_mfma_f32_32x32x16_bf16 v[0:15], v[68:71], v[220:223], v[0:15]
	v_mfma_f32_32x32x16_bf16 v[16:31], v[68:71], v[224:227], v[16:31]
	global_load_dwordx4 v[156:159], v235, s[84:85]
	global_load_dwordx4 v[160:163], v236, s[84:85]
	global_load_dwordx4 v[164:167], v237, s[84:85]
	global_load_dwordx4 v[168:171], v238, s[84:85]
	global_load_dwordx4 v[172:175], v100, s[84:85] offset:768
	global_load_dwordx4 v[176:179], v149, s[84:85] offset:768
	global_load_dwordx4 v[180:183], v100, s[84:85] offset:832
	global_load_dwordx4 v[184:187], v149, s[84:85] offset:832
	s_add_u32 s84, s84, 0x30000
	s_addc_u32 s85, s85, 0
	s_waitcnt vmcnt(16)
	ds_write_b128 v247, v[188:191]
	ds_write_b128 v247, v[192:195] offset:1152
	ds_write_b128 v247, v[196:199] offset:2304
	ds_write_b128 v247, v[200:203] offset:3456
	ds_write_b128 v112, v[204:207]
	ds_write_b128 v112, v[208:211] offset:1024
	ds_write_b128 v112, v[212:215] offset:2048
	ds_write_b128 v112, v[216:219] offset:3072
	ds_read2_b32 v[32:33], v115 offset0:160 offset1:161
	ds_read2_b32 v[34:35], v115 offset0:162 offset1:163
	ds_read2_b32 v[36:37], v115 offset0:168 offset1:169
	ds_read2_b32 v[38:39], v115 offset0:170 offset1:171
	ds_read2_b32 v[40:41], v115 offset0:176 offset1:177
	ds_read2_b32 v[42:43], v115 offset0:178 offset1:179
	ds_read2_b32 v[44:45], v115 offset0:184 offset1:185
	ds_read2_b32 v[46:47], v115 offset0:186 offset1:187
	ds_read_b128 v[188:191], v248
	ds_read_b128 v[192:195], v248 offset:32
	ds_read_b128 v[196:199], v248 offset:64
	ds_read_b128 v[200:203], v248 offset:96
	ds_read_b64_tr_b16 v[72:73], v231
	ds_read_b64_tr_b16 v[74:75], v231 offset:512
	ds_read_b64_tr_b16 v[76:77], v231 offset:2048
	ds_read_b64_tr_b16 v[78:79], v231 offset:2560
	ds_read_b64_tr_b16 v[220:221], v231 offset:1024
	ds_read_b64_tr_b16 v[222:223], v231 offset:1536
	ds_read_b64_tr_b16 v[224:225], v231 offset:3072
	ds_read_b64_tr_b16 v[226:227], v231 offset:3584
	s_waitcnt lgkmcnt(8)
	v_mfma_f32_32x32x16_bf16 v[32:47], v[188:191], v[48:51], v[32:47]
	v_mfma_f32_32x32x16_bf16 v[32:47], v[192:195], v[52:55], v[32:47]
	v_mfma_f32_32x32x16_bf16 v[32:47], v[196:199], v[56:59], v[32:47]
	v_mfma_f32_32x32x16_bf16 v[32:47], v[200:203], v[60:63], v[32:47]
	s_nop 11
	v_exp_f32_e32 v32, v32
	v_exp_f32_e32 v33, v33
	v_exp_f32_e32 v34, v34
	v_exp_f32_e32 v35, v35
	v_exp_f32_e32 v36, v36
	v_exp_f32_e32 v37, v37
	v_exp_f32_e32 v38, v38
	v_exp_f32_e32 v39, v39
	v_exp_f32_e32 v40, v40
	v_exp_f32_e32 v41, v41
	v_exp_f32_e32 v42, v42
	v_exp_f32_e32 v43, v43
	v_exp_f32_e32 v44, v44
	v_exp_f32_e32 v45, v45
	v_exp_f32_e32 v46, v46
	v_exp_f32_e32 v47, v47
	v_cvt_pk_bf16_f32 v64, v32, v33
	v_cvt_pk_bf16_f32 v65, v34, v35
	v_cvt_pk_bf16_f32 v66, v36, v37
	v_cvt_pk_bf16_f32 v67, v38, v39
	v_cvt_pk_bf16_f32 v68, v40, v41
	v_cvt_pk_bf16_f32 v69, v42, v43
	v_cvt_pk_bf16_f32 v70, v44, v45
	v_cvt_pk_bf16_f32 v71, v46, v47
	v_pk_add_f32 v[232:233], v[232:233], v[32:33]
	v_pk_add_f32 v[232:233], v[232:233], v[34:35]
	v_pk_add_f32 v[232:233], v[232:233], v[36:37]
	v_pk_add_f32 v[232:233], v[232:233], v[38:39]
	v_pk_add_f32 v[232:233], v[232:233], v[40:41]
	v_pk_add_f32 v[232:233], v[232:233], v[42:43]
	v_pk_add_f32 v[232:233], v[232:233], v[44:45]
	v_pk_add_f32 v[232:233], v[232:233], v[46:47]
	s_waitcnt lgkmcnt(0)
	v_mfma_f32_32x32x16_bf16 v[0:15], v[64:67], v[72:75], v[0:15]
	v_mfma_f32_32x32x16_bf16 v[16:31], v[64:67], v[76:79], v[16:31]
	v_mfma_f32_32x32x16_bf16 v[0:15], v[68:71], v[220:223], v[0:15]
	v_mfma_f32_32x32x16_bf16 v[16:31], v[68:71], v[224:227], v[16:31]
	global_load_dwordx4 v[188:191], v235, s[84:85]
	global_load_dwordx4 v[192:195], v236, s[84:85]
	global_load_dwordx4 v[196:199], v237, s[84:85]
	global_load_dwordx4 v[200:203], v238, s[84:85]
	global_load_dwordx4 v[204:207], v100, s[84:85] offset:768
	global_load_dwordx4 v[208:211], v149, s[84:85] offset:768
	global_load_dwordx4 v[212:215], v100, s[84:85] offset:832
	global_load_dwordx4 v[216:219], v149, s[84:85] offset:832
	s_add_u32 s84, s84, 0x30000
	s_addc_u32 s85, s85, 0
	s_waitcnt vmcnt(16)
	ds_write_b128 v247, v[116:119]
	ds_write_b128 v247, v[120:123] offset:1152
	ds_write_b128 v247, v[124:127] offset:2304
	ds_write_b128 v247, v[128:131] offset:3456
	ds_write_b128 v112, v[132:135]
	ds_write_b128 v112, v[136:139] offset:1024
	ds_write_b128 v112, v[140:143] offset:2048
	ds_write_b128 v112, v[144:147] offset:3072
	ds_read2_b32 v[32:33], v115 offset0:192 offset1:193
	ds_read2_b32 v[34:35], v115 offset0:194 offset1:195
	ds_read2_b32 v[36:37], v115 offset0:200 offset1:201
	ds_read2_b32 v[38:39], v115 offset0:202 offset1:203
	ds_read2_b32 v[40:41], v115 offset0:208 offset1:209
	ds_read2_b32 v[42:43], v115 offset0:210 offset1:211
	ds_read2_b32 v[44:45], v115 offset0:216 offset1:217
	ds_read2_b32 v[46:47], v115 offset0:218 offset1:219
	ds_read_b128 v[116:119], v248
	ds_read_b128 v[120:123], v248 offset:32
	ds_read_b128 v[124:127], v248 offset:64
	ds_read_b128 v[128:131], v248 offset:96
	ds_read_b64_tr_b16 v[72:73], v231
	ds_read_b64_tr_b16 v[74:75], v231 offset:512
	ds_read_b64_tr_b16 v[76:77], v231 offset:2048
	ds_read_b64_tr_b16 v[78:79], v231 offset:2560
	ds_read_b64_tr_b16 v[220:221], v231 offset:1024
	ds_read_b64_tr_b16 v[222:223], v231 offset:1536
	ds_read_b64_tr_b16 v[224:225], v231 offset:3072
	ds_read_b64_tr_b16 v[226:227], v231 offset:3584
	s_waitcnt lgkmcnt(8)
	v_mfma_f32_32x32x16_bf16 v[32:47], v[116:119], v[48:51], v[32:47]
	v_mfma_f32_32x32x16_bf16 v[32:47], v[120:123], v[52:55], v[32:47]
	v_mfma_f32_32x32x16_bf16 v[32:47], v[124:127], v[56:59], v[32:47]
	v_mfma_f32_32x32x16_bf16 v[32:47], v[128:131], v[60:63], v[32:47]
	s_nop 11
	v_exp_f32_e32 v32, v32
	v_exp_f32_e32 v33, v33
	v_exp_f32_e32 v34, v34
	v_exp_f32_e32 v35, v35
	v_exp_f32_e32 v36, v36
	v_exp_f32_e32 v37, v37
	v_exp_f32_e32 v38, v38
	v_exp_f32_e32 v39, v39
	v_exp_f32_e32 v40, v40
	v_exp_f32_e32 v41, v41
	v_exp_f32_e32 v42, v42
	v_exp_f32_e32 v43, v43
	v_exp_f32_e32 v44, v44
	v_exp_f32_e32 v45, v45
	v_exp_f32_e32 v46, v46
	v_exp_f32_e32 v47, v47
	v_cvt_pk_bf16_f32 v64, v32, v33
	v_cvt_pk_bf16_f32 v65, v34, v35
	v_cvt_pk_bf16_f32 v66, v36, v37
	v_cvt_pk_bf16_f32 v67, v38, v39
	v_cvt_pk_bf16_f32 v68, v40, v41
	v_cvt_pk_bf16_f32 v69, v42, v43
	v_cvt_pk_bf16_f32 v70, v44, v45
	v_cvt_pk_bf16_f32 v71, v46, v47
	v_pk_add_f32 v[232:233], v[232:233], v[32:33]
	v_pk_add_f32 v[232:233], v[232:233], v[34:35]
	v_pk_add_f32 v[232:233], v[232:233], v[36:37]
	v_pk_add_f32 v[232:233], v[232:233], v[38:39]
	v_pk_add_f32 v[232:233], v[232:233], v[40:41]
	v_pk_add_f32 v[232:233], v[232:233], v[42:43]
	v_pk_add_f32 v[232:233], v[232:233], v[44:45]
	v_pk_add_f32 v[232:233], v[232:233], v[46:47]
	s_waitcnt lgkmcnt(0)
	v_mfma_f32_32x32x16_bf16 v[0:15], v[64:67], v[72:75], v[0:15]
	v_mfma_f32_32x32x16_bf16 v[16:31], v[64:67], v[76:79], v[16:31]
	v_mfma_f32_32x32x16_bf16 v[0:15], v[68:71], v[220:223], v[0:15]
	v_mfma_f32_32x32x16_bf16 v[16:31], v[68:71], v[224:227], v[16:31]
	global_load_dwordx4 v[116:119], v235, s[84:85]
	global_load_dwordx4 v[120:123], v236, s[84:85]
	global_load_dwordx4 v[124:127], v237, s[84:85]
	global_load_dwordx4 v[128:131], v238, s[84:85]
	global_load_dwordx4 v[132:135], v100, s[84:85] offset:768
	global_load_dwordx4 v[136:139], v149, s[84:85] offset:768
	global_load_dwordx4 v[140:143], v100, s[84:85] offset:832
	global_load_dwordx4 v[144:147], v149, s[84:85] offset:832
	s_add_u32 s84, s84, 0x30000
	s_addc_u32 s85, s85, 0
	s_waitcnt vmcnt(16)
	ds_write_b128 v247, v[156:159]
	ds_write_b128 v247, v[160:163] offset:1152
	ds_write_b128 v247, v[164:167] offset:2304
	ds_write_b128 v247, v[168:171] offset:3456
	ds_write_b128 v112, v[172:175]
	ds_write_b128 v112, v[176:179] offset:1024
	ds_write_b128 v112, v[180:183] offset:2048
	ds_write_b128 v112, v[184:187] offset:3072
	ds_read2_b32 v[32:33], v115 offset0:224 offset1:225
	ds_read2_b32 v[34:35], v115 offset0:226 offset1:227
	ds_read2_b32 v[36:37], v115 offset0:232 offset1:233
	ds_read2_b32 v[38:39], v115 offset0:234 offset1:235
	ds_read2_b32 v[40:41], v115 offset0:240 offset1:241
	ds_read2_b32 v[42:43], v115 offset0:242 offset1:243
	ds_read2_b32 v[44:45], v115 offset0:248 offset1:249
	ds_read2_b32 v[46:47], v115 offset0:250 offset1:251
	ds_read_b128 v[156:159], v248
	ds_read_b128 v[160:163], v248 offset:32
	ds_read_b128 v[164:167], v248 offset:64
	ds_read_b128 v[168:171], v248 offset:96
	ds_read_b64_tr_b16 v[72:73], v231
	ds_read_b64_tr_b16 v[74:75], v231 offset:512
	ds_read_b64_tr_b16 v[76:77], v231 offset:2048
	ds_read_b64_tr_b16 v[78:79], v231 offset:2560
	ds_read_b64_tr_b16 v[220:221], v231 offset:1024
	ds_read_b64_tr_b16 v[222:223], v231 offset:1536
	ds_read_b64_tr_b16 v[224:225], v231 offset:3072
	ds_read_b64_tr_b16 v[226:227], v231 offset:3584
	s_waitcnt lgkmcnt(8)
	v_mfma_f32_32x32x16_bf16 v[32:47], v[156:159], v[48:51], v[32:47]
	v_mfma_f32_32x32x16_bf16 v[32:47], v[160:163], v[52:55], v[32:47]
	v_mfma_f32_32x32x16_bf16 v[32:47], v[164:167], v[56:59], v[32:47]
	v_mfma_f32_32x32x16_bf16 v[32:47], v[168:171], v[60:63], v[32:47]
	s_nop 11
	v_exp_f32_e32 v32, v32
	v_exp_f32_e32 v33, v33
	v_exp_f32_e32 v34, v34
	v_exp_f32_e32 v35, v35
	v_exp_f32_e32 v36, v36
	v_exp_f32_e32 v37, v37
	v_exp_f32_e32 v38, v38
	v_exp_f32_e32 v39, v39
	v_exp_f32_e32 v40, v40
	v_exp_f32_e32 v41, v41
	v_exp_f32_e32 v42, v42
	v_exp_f32_e32 v43, v43
	v_exp_f32_e32 v44, v44
	v_exp_f32_e32 v45, v45
	v_exp_f32_e32 v46, v46
	v_exp_f32_e32 v47, v47
	v_cvt_pk_bf16_f32 v64, v32, v33
	v_cvt_pk_bf16_f32 v65, v34, v35
	v_cvt_pk_bf16_f32 v66, v36, v37
	v_cvt_pk_bf16_f32 v67, v38, v39
	v_cvt_pk_bf16_f32 v68, v40, v41
	v_cvt_pk_bf16_f32 v69, v42, v43
	v_cvt_pk_bf16_f32 v70, v44, v45
	v_cvt_pk_bf16_f32 v71, v46, v47
	v_pk_add_f32 v[232:233], v[232:233], v[32:33]
	v_pk_add_f32 v[232:233], v[232:233], v[34:35]
	v_pk_add_f32 v[232:233], v[232:233], v[36:37]
	v_pk_add_f32 v[232:233], v[232:233], v[38:39]
	v_pk_add_f32 v[232:233], v[232:233], v[40:41]
	v_pk_add_f32 v[232:233], v[232:233], v[42:43]
	v_pk_add_f32 v[232:233], v[232:233], v[44:45]
	v_pk_add_f32 v[232:233], v[232:233], v[46:47]
	s_waitcnt lgkmcnt(0)
	v_mfma_f32_32x32x16_bf16 v[0:15], v[64:67], v[72:75], v[0:15]
	v_mfma_f32_32x32x16_bf16 v[16:31], v[64:67], v[76:79], v[16:31]
	v_mfma_f32_32x32x16_bf16 v[0:15], v[68:71], v[220:223], v[0:15]
	v_mfma_f32_32x32x16_bf16 v[16:31], v[68:71], v[224:227], v[16:31]
	global_load_dwordx4 v[156:159], v235, s[84:85]
	global_load_dwordx4 v[160:163], v236, s[84:85]
	global_load_dwordx4 v[164:167], v237, s[84:85]
	global_load_dwordx4 v[168:171], v238, s[84:85]
	global_load_dwordx4 v[172:175], v100, s[84:85] offset:768
	global_load_dwordx4 v[176:179], v149, s[84:85] offset:768
	global_load_dwordx4 v[180:183], v100, s[84:85] offset:832
	global_load_dwordx4 v[184:187], v149, s[84:85] offset:832
	s_add_u32 s84, s84, 0x30000
	s_addc_u32 s85, s85, 0
	s_waitcnt vmcnt(16)
	ds_write_b128 v247, v[188:191]
	ds_write_b128 v247, v[192:195] offset:1152
	ds_write_b128 v247, v[196:199] offset:2304
	ds_write_b128 v247, v[200:203] offset:3456
	ds_write_b128 v112, v[204:207]
	ds_write_b128 v112, v[208:211] offset:1024
	ds_write_b128 v112, v[212:215] offset:2048
	ds_write_b128 v112, v[216:219] offset:3072
	v_add_u32_e32 v115, 0x400, v115
	ds_read2_b32 v[32:33], v115 offset0:0 offset1:1
	ds_read2_b32 v[34:35], v115 offset0:2 offset1:3
	ds_read2_b32 v[36:37], v115 offset0:8 offset1:9
	ds_read2_b32 v[38:39], v115 offset0:10 offset1:11
	ds_read2_b32 v[40:41], v115 offset0:16 offset1:17
	ds_read2_b32 v[42:43], v115 offset0:18 offset1:19
	ds_read2_b32 v[44:45], v115 offset0:24 offset1:25
	ds_read2_b32 v[46:47], v115 offset0:26 offset1:27
	ds_read_b128 v[188:191], v248
	ds_read_b128 v[192:195], v248 offset:32
	ds_read_b128 v[196:199], v248 offset:64
	ds_read_b128 v[200:203], v248 offset:96
	ds_read_b64_tr_b16 v[72:73], v231
	ds_read_b64_tr_b16 v[74:75], v231 offset:512
	ds_read_b64_tr_b16 v[76:77], v231 offset:2048
	ds_read_b64_tr_b16 v[78:79], v231 offset:2560
	ds_read_b64_tr_b16 v[220:221], v231 offset:1024
	ds_read_b64_tr_b16 v[222:223], v231 offset:1536
	ds_read_b64_tr_b16 v[224:225], v231 offset:3072
	ds_read_b64_tr_b16 v[226:227], v231 offset:3584
	s_waitcnt lgkmcnt(8)
	v_mfma_f32_32x32x16_bf16 v[32:47], v[188:191], v[48:51], v[32:47]
	v_mfma_f32_32x32x16_bf16 v[32:47], v[192:195], v[52:55], v[32:47]
	v_mfma_f32_32x32x16_bf16 v[32:47], v[196:199], v[56:59], v[32:47]
	v_mfma_f32_32x32x16_bf16 v[32:47], v[200:203], v[60:63], v[32:47]
	s_nop 11
	v_exp_f32_e32 v32, v32
	v_exp_f32_e32 v33, v33
	v_exp_f32_e32 v34, v34
	v_exp_f32_e32 v35, v35
	v_exp_f32_e32 v36, v36
	v_exp_f32_e32 v37, v37
	v_exp_f32_e32 v38, v38
	v_exp_f32_e32 v39, v39
	v_exp_f32_e32 v40, v40
	v_exp_f32_e32 v41, v41
	v_exp_f32_e32 v42, v42
	v_exp_f32_e32 v43, v43
	v_exp_f32_e32 v44, v44
	v_exp_f32_e32 v45, v45
	v_exp_f32_e32 v46, v46
	v_exp_f32_e32 v47, v47
	v_cvt_pk_bf16_f32 v64, v32, v33
	v_cvt_pk_bf16_f32 v65, v34, v35
	v_cvt_pk_bf16_f32 v66, v36, v37
	v_cvt_pk_bf16_f32 v67, v38, v39
	v_cvt_pk_bf16_f32 v68, v40, v41
	v_cvt_pk_bf16_f32 v69, v42, v43
	v_cvt_pk_bf16_f32 v70, v44, v45
	v_cvt_pk_bf16_f32 v71, v46, v47
	v_pk_add_f32 v[232:233], v[232:233], v[32:33]
	v_pk_add_f32 v[232:233], v[232:233], v[34:35]
	v_pk_add_f32 v[232:233], v[232:233], v[36:37]
	v_pk_add_f32 v[232:233], v[232:233], v[38:39]
	v_pk_add_f32 v[232:233], v[232:233], v[40:41]
	v_pk_add_f32 v[232:233], v[232:233], v[42:43]
	v_pk_add_f32 v[232:233], v[232:233], v[44:45]
	v_pk_add_f32 v[232:233], v[232:233], v[46:47]
	s_waitcnt lgkmcnt(0)
	v_mfma_f32_32x32x16_bf16 v[0:15], v[64:67], v[72:75], v[0:15]
	v_mfma_f32_32x32x16_bf16 v[16:31], v[64:67], v[76:79], v[16:31]
	v_mfma_f32_32x32x16_bf16 v[0:15], v[68:71], v[220:223], v[0:15]
	v_mfma_f32_32x32x16_bf16 v[16:31], v[68:71], v[224:227], v[16:31]
	global_load_dwordx4 v[188:191], v235, s[84:85]
	global_load_dwordx4 v[192:195], v236, s[84:85]
	global_load_dwordx4 v[196:199], v237, s[84:85]
	global_load_dwordx4 v[200:203], v238, s[84:85]
	global_load_dwordx4 v[204:207], v100, s[84:85] offset:768
	global_load_dwordx4 v[208:211], v149, s[84:85] offset:768
	global_load_dwordx4 v[212:215], v100, s[84:85] offset:832
	global_load_dwordx4 v[216:219], v149, s[84:85] offset:832
	s_add_u32 s84, s84, 0x30000
	s_addc_u32 s85, s85, 0
	s_waitcnt vmcnt(16)
	ds_write_b128 v247, v[116:119]
	ds_write_b128 v247, v[120:123] offset:1152
	ds_write_b128 v247, v[124:127] offset:2304
	ds_write_b128 v247, v[128:131] offset:3456
	ds_write_b128 v112, v[132:135]
	ds_write_b128 v112, v[136:139] offset:1024
	ds_write_b128 v112, v[140:143] offset:2048
	ds_write_b128 v112, v[144:147] offset:3072
	ds_read2_b32 v[32:33], v115 offset0:32 offset1:33
	ds_read2_b32 v[34:35], v115 offset0:34 offset1:35
	ds_read2_b32 v[36:37], v115 offset0:40 offset1:41
	ds_read2_b32 v[38:39], v115 offset0:42 offset1:43
	ds_read2_b32 v[40:41], v115 offset0:48 offset1:49
	ds_read2_b32 v[42:43], v115 offset0:50 offset1:51
	ds_read2_b32 v[44:45], v115 offset0:56 offset1:57
	ds_read2_b32 v[46:47], v115 offset0:58 offset1:59
	ds_read_b128 v[116:119], v248
	ds_read_b128 v[120:123], v248 offset:32
	ds_read_b128 v[124:127], v248 offset:64
	ds_read_b128 v[128:131], v248 offset:96
	ds_read_b64_tr_b16 v[72:73], v231
	ds_read_b64_tr_b16 v[74:75], v231 offset:512
	ds_read_b64_tr_b16 v[76:77], v231 offset:2048
	ds_read_b64_tr_b16 v[78:79], v231 offset:2560
	ds_read_b64_tr_b16 v[220:221], v231 offset:1024
	ds_read_b64_tr_b16 v[222:223], v231 offset:1536
	ds_read_b64_tr_b16 v[224:225], v231 offset:3072
	ds_read_b64_tr_b16 v[226:227], v231 offset:3584
	s_waitcnt lgkmcnt(8)
	v_mfma_f32_32x32x16_bf16 v[32:47], v[116:119], v[48:51], v[32:47]
	v_mfma_f32_32x32x16_bf16 v[32:47], v[120:123], v[52:55], v[32:47]
	v_mfma_f32_32x32x16_bf16 v[32:47], v[124:127], v[56:59], v[32:47]
	v_mfma_f32_32x32x16_bf16 v[32:47], v[128:131], v[60:63], v[32:47]
	s_nop 11
	v_exp_f32_e32 v32, v32
	v_exp_f32_e32 v33, v33
	v_exp_f32_e32 v34, v34
	v_exp_f32_e32 v35, v35
	v_exp_f32_e32 v36, v36
	v_exp_f32_e32 v37, v37
	v_exp_f32_e32 v38, v38
	v_exp_f32_e32 v39, v39
	v_exp_f32_e32 v40, v40
	v_exp_f32_e32 v41, v41
	v_exp_f32_e32 v42, v42
	v_exp_f32_e32 v43, v43
	v_exp_f32_e32 v44, v44
	v_exp_f32_e32 v45, v45
	v_exp_f32_e32 v46, v46
	v_exp_f32_e32 v47, v47
	v_cvt_pk_bf16_f32 v64, v32, v33
	v_cvt_pk_bf16_f32 v65, v34, v35
	v_cvt_pk_bf16_f32 v66, v36, v37
	v_cvt_pk_bf16_f32 v67, v38, v39
	v_cvt_pk_bf16_f32 v68, v40, v41
	v_cvt_pk_bf16_f32 v69, v42, v43
	v_cvt_pk_bf16_f32 v70, v44, v45
	v_cvt_pk_bf16_f32 v71, v46, v47
	v_pk_add_f32 v[232:233], v[232:233], v[32:33]
	v_pk_add_f32 v[232:233], v[232:233], v[34:35]
	v_pk_add_f32 v[232:233], v[232:233], v[36:37]
	v_pk_add_f32 v[232:233], v[232:233], v[38:39]
	v_pk_add_f32 v[232:233], v[232:233], v[40:41]
	v_pk_add_f32 v[232:233], v[232:233], v[42:43]
	v_pk_add_f32 v[232:233], v[232:233], v[44:45]
	v_pk_add_f32 v[232:233], v[232:233], v[46:47]
	s_waitcnt lgkmcnt(0)
	v_mfma_f32_32x32x16_bf16 v[0:15], v[64:67], v[72:75], v[0:15]
	v_mfma_f32_32x32x16_bf16 v[16:31], v[64:67], v[76:79], v[16:31]
	v_mfma_f32_32x32x16_bf16 v[0:15], v[68:71], v[220:223], v[0:15]
	v_mfma_f32_32x32x16_bf16 v[16:31], v[68:71], v[224:227], v[16:31]
	global_load_dwordx4 v[116:119], v235, s[84:85]
	global_load_dwordx4 v[120:123], v236, s[84:85]
	global_load_dwordx4 v[124:127], v237, s[84:85]
	global_load_dwordx4 v[128:131], v238, s[84:85]
	global_load_dwordx4 v[132:135], v100, s[84:85] offset:768
	global_load_dwordx4 v[136:139], v149, s[84:85] offset:768
	global_load_dwordx4 v[140:143], v100, s[84:85] offset:832
	global_load_dwordx4 v[144:147], v149, s[84:85] offset:832
	s_add_u32 s84, s84, 0x30000
	s_addc_u32 s85, s85, 0
	s_waitcnt vmcnt(16)
	ds_write_b128 v247, v[156:159]
	ds_write_b128 v247, v[160:163] offset:1152
	ds_write_b128 v247, v[164:167] offset:2304
	ds_write_b128 v247, v[168:171] offset:3456
	ds_write_b128 v112, v[172:175]
	ds_write_b128 v112, v[176:179] offset:1024
	ds_write_b128 v112, v[180:183] offset:2048
	ds_write_b128 v112, v[184:187] offset:3072
	ds_read2_b32 v[32:33], v115 offset0:64 offset1:65
	ds_read2_b32 v[34:35], v115 offset0:66 offset1:67
	ds_read2_b32 v[36:37], v115 offset0:72 offset1:73
	ds_read2_b32 v[38:39], v115 offset0:74 offset1:75
	ds_read2_b32 v[40:41], v115 offset0:80 offset1:81
	ds_read2_b32 v[42:43], v115 offset0:82 offset1:83
	ds_read2_b32 v[44:45], v115 offset0:88 offset1:89
	ds_read2_b32 v[46:47], v115 offset0:90 offset1:91
	ds_read_b128 v[156:159], v248
	ds_read_b128 v[160:163], v248 offset:32
	ds_read_b128 v[164:167], v248 offset:64
	ds_read_b128 v[168:171], v248 offset:96
	ds_read_b64_tr_b16 v[72:73], v231
	ds_read_b64_tr_b16 v[74:75], v231 offset:512
	ds_read_b64_tr_b16 v[76:77], v231 offset:2048
	ds_read_b64_tr_b16 v[78:79], v231 offset:2560
	ds_read_b64_tr_b16 v[220:221], v231 offset:1024
	ds_read_b64_tr_b16 v[222:223], v231 offset:1536
	ds_read_b64_tr_b16 v[224:225], v231 offset:3072
	ds_read_b64_tr_b16 v[226:227], v231 offset:3584
	s_waitcnt lgkmcnt(8)
	v_mfma_f32_32x32x16_bf16 v[32:47], v[156:159], v[48:51], v[32:47]
	v_mfma_f32_32x32x16_bf16 v[32:47], v[160:163], v[52:55], v[32:47]
	v_mfma_f32_32x32x16_bf16 v[32:47], v[164:167], v[56:59], v[32:47]
	v_mfma_f32_32x32x16_bf16 v[32:47], v[168:171], v[60:63], v[32:47]
	s_nop 11
	v_exp_f32_e32 v32, v32
	v_exp_f32_e32 v33, v33
	v_exp_f32_e32 v34, v34
	v_exp_f32_e32 v35, v35
	v_exp_f32_e32 v36, v36
	v_exp_f32_e32 v37, v37
	v_exp_f32_e32 v38, v38
	v_exp_f32_e32 v39, v39
	v_exp_f32_e32 v40, v40
	v_exp_f32_e32 v41, v41
	v_exp_f32_e32 v42, v42
	v_exp_f32_e32 v43, v43
	v_exp_f32_e32 v44, v44
	v_exp_f32_e32 v45, v45
	v_exp_f32_e32 v46, v46
	v_exp_f32_e32 v47, v47
	v_cvt_pk_bf16_f32 v64, v32, v33
	v_cvt_pk_bf16_f32 v65, v34, v35
	v_cvt_pk_bf16_f32 v66, v36, v37
	v_cvt_pk_bf16_f32 v67, v38, v39
	v_cvt_pk_bf16_f32 v68, v40, v41
	v_cvt_pk_bf16_f32 v69, v42, v43
	v_cvt_pk_bf16_f32 v70, v44, v45
	v_cvt_pk_bf16_f32 v71, v46, v47
	v_pk_add_f32 v[232:233], v[232:233], v[32:33]
	v_pk_add_f32 v[232:233], v[232:233], v[34:35]
	v_pk_add_f32 v[232:233], v[232:233], v[36:37]
	v_pk_add_f32 v[232:233], v[232:233], v[38:39]
	v_pk_add_f32 v[232:233], v[232:233], v[40:41]
	v_pk_add_f32 v[232:233], v[232:233], v[42:43]
	v_pk_add_f32 v[232:233], v[232:233], v[44:45]
	v_pk_add_f32 v[232:233], v[232:233], v[46:47]
	s_waitcnt lgkmcnt(0)
	v_mfma_f32_32x32x16_bf16 v[0:15], v[64:67], v[72:75], v[0:15]
	v_mfma_f32_32x32x16_bf16 v[16:31], v[64:67], v[76:79], v[16:31]
	v_mfma_f32_32x32x16_bf16 v[0:15], v[68:71], v[220:223], v[0:15]
	v_mfma_f32_32x32x16_bf16 v[16:31], v[68:71], v[224:227], v[16:31]
	global_load_dwordx4 v[156:159], v235, s[84:85]
	global_load_dwordx4 v[160:163], v236, s[84:85]
	global_load_dwordx4 v[164:167], v237, s[84:85]
	global_load_dwordx4 v[168:171], v238, s[84:85]
	global_load_dwordx4 v[172:175], v100, s[84:85] offset:768
	global_load_dwordx4 v[176:179], v149, s[84:85] offset:768
	global_load_dwordx4 v[180:183], v100, s[84:85] offset:832
	global_load_dwordx4 v[184:187], v149, s[84:85] offset:832
	s_add_u32 s84, s84, 0x30000
	s_addc_u32 s85, s85, 0
	s_waitcnt vmcnt(16)
	ds_write_b128 v247, v[188:191]
	ds_write_b128 v247, v[192:195] offset:1152
	ds_write_b128 v247, v[196:199] offset:2304
	ds_write_b128 v247, v[200:203] offset:3456
	ds_write_b128 v112, v[204:207]
	ds_write_b128 v112, v[208:211] offset:1024
	ds_write_b128 v112, v[212:215] offset:2048
	ds_write_b128 v112, v[216:219] offset:3072
	ds_read2_b32 v[32:33], v115 offset0:96 offset1:97
	ds_read2_b32 v[34:35], v115 offset0:98 offset1:99
	ds_read2_b32 v[36:37], v115 offset0:104 offset1:105
	ds_read2_b32 v[38:39], v115 offset0:106 offset1:107
	ds_read2_b32 v[40:41], v115 offset0:112 offset1:113
	ds_read2_b32 v[42:43], v115 offset0:114 offset1:115
	ds_read2_b32 v[44:45], v115 offset0:120 offset1:121
	ds_read2_b32 v[46:47], v115 offset0:122 offset1:123
	ds_read_b128 v[188:191], v248
	ds_read_b128 v[192:195], v248 offset:32
	ds_read_b128 v[196:199], v248 offset:64
	ds_read_b128 v[200:203], v248 offset:96
	ds_read_b64_tr_b16 v[72:73], v231
	ds_read_b64_tr_b16 v[74:75], v231 offset:512
	ds_read_b64_tr_b16 v[76:77], v231 offset:2048
	ds_read_b64_tr_b16 v[78:79], v231 offset:2560
	ds_read_b64_tr_b16 v[220:221], v231 offset:1024
	ds_read_b64_tr_b16 v[222:223], v231 offset:1536
	ds_read_b64_tr_b16 v[224:225], v231 offset:3072
	ds_read_b64_tr_b16 v[226:227], v231 offset:3584
	s_waitcnt lgkmcnt(8)
	v_mfma_f32_32x32x16_bf16 v[32:47], v[188:191], v[48:51], v[32:47]
	v_mfma_f32_32x32x16_bf16 v[32:47], v[192:195], v[52:55], v[32:47]
	v_mfma_f32_32x32x16_bf16 v[32:47], v[196:199], v[56:59], v[32:47]
	v_mfma_f32_32x32x16_bf16 v[32:47], v[200:203], v[60:63], v[32:47]
	s_nop 11
	v_exp_f32_e32 v32, v32
	v_exp_f32_e32 v33, v33
	v_exp_f32_e32 v34, v34
	v_exp_f32_e32 v35, v35
	v_exp_f32_e32 v36, v36
	v_exp_f32_e32 v37, v37
	v_exp_f32_e32 v38, v38
	v_exp_f32_e32 v39, v39
	v_exp_f32_e32 v40, v40
	v_exp_f32_e32 v41, v41
	v_exp_f32_e32 v42, v42
	v_exp_f32_e32 v43, v43
	v_exp_f32_e32 v44, v44
	v_exp_f32_e32 v45, v45
	v_exp_f32_e32 v46, v46
	v_exp_f32_e32 v47, v47
	v_cvt_pk_bf16_f32 v64, v32, v33
	v_cvt_pk_bf16_f32 v65, v34, v35
	v_cvt_pk_bf16_f32 v66, v36, v37
	v_cvt_pk_bf16_f32 v67, v38, v39
	v_cvt_pk_bf16_f32 v68, v40, v41
	v_cvt_pk_bf16_f32 v69, v42, v43
	v_cvt_pk_bf16_f32 v70, v44, v45
	v_cvt_pk_bf16_f32 v71, v46, v47
	v_pk_add_f32 v[232:233], v[232:233], v[32:33]
	v_pk_add_f32 v[232:233], v[232:233], v[34:35]
	v_pk_add_f32 v[232:233], v[232:233], v[36:37]
	v_pk_add_f32 v[232:233], v[232:233], v[38:39]
	v_pk_add_f32 v[232:233], v[232:233], v[40:41]
	v_pk_add_f32 v[232:233], v[232:233], v[42:43]
	v_pk_add_f32 v[232:233], v[232:233], v[44:45]
	v_pk_add_f32 v[232:233], v[232:233], v[46:47]
	s_waitcnt lgkmcnt(0)
	v_mfma_f32_32x32x16_bf16 v[0:15], v[64:67], v[72:75], v[0:15]
	v_mfma_f32_32x32x16_bf16 v[16:31], v[64:67], v[76:79], v[16:31]
	v_mfma_f32_32x32x16_bf16 v[0:15], v[68:71], v[220:223], v[0:15]
	v_mfma_f32_32x32x16_bf16 v[16:31], v[68:71], v[224:227], v[16:31]
	global_load_dwordx4 v[188:191], v235, s[84:85]
	global_load_dwordx4 v[192:195], v236, s[84:85]
	global_load_dwordx4 v[196:199], v237, s[84:85]
	global_load_dwordx4 v[200:203], v238, s[84:85]
	global_load_dwordx4 v[204:207], v100, s[84:85] offset:768
	global_load_dwordx4 v[208:211], v149, s[84:85] offset:768
	global_load_dwordx4 v[212:215], v100, s[84:85] offset:832
	global_load_dwordx4 v[216:219], v149, s[84:85] offset:832
	s_add_u32 s84, s84, 0x30000
	s_addc_u32 s85, s85, 0
	s_waitcnt vmcnt(16)
	ds_write_b128 v247, v[116:119]
	ds_write_b128 v247, v[120:123] offset:1152
	ds_write_b128 v247, v[124:127] offset:2304
	ds_write_b128 v247, v[128:131] offset:3456
	ds_write_b128 v112, v[132:135]
	ds_write_b128 v112, v[136:139] offset:1024
	ds_write_b128 v112, v[140:143] offset:2048
	ds_write_b128 v112, v[144:147] offset:3072
	ds_read2_b32 v[32:33], v115 offset0:128 offset1:129
	ds_read2_b32 v[34:35], v115 offset0:130 offset1:131
	ds_read2_b32 v[36:37], v115 offset0:136 offset1:137
	ds_read2_b32 v[38:39], v115 offset0:138 offset1:139
	ds_read2_b32 v[40:41], v115 offset0:144 offset1:145
	ds_read2_b32 v[42:43], v115 offset0:146 offset1:147
	ds_read2_b32 v[44:45], v115 offset0:152 offset1:153
	ds_read2_b32 v[46:47], v115 offset0:154 offset1:155
	ds_read_b128 v[116:119], v248
	ds_read_b128 v[120:123], v248 offset:32
	ds_read_b128 v[124:127], v248 offset:64
	ds_read_b128 v[128:131], v248 offset:96
	ds_read_b64_tr_b16 v[72:73], v231
	ds_read_b64_tr_b16 v[74:75], v231 offset:512
	ds_read_b64_tr_b16 v[76:77], v231 offset:2048
	ds_read_b64_tr_b16 v[78:79], v231 offset:2560
	ds_read_b64_tr_b16 v[220:221], v231 offset:1024
	ds_read_b64_tr_b16 v[222:223], v231 offset:1536
	ds_read_b64_tr_b16 v[224:225], v231 offset:3072
	ds_read_b64_tr_b16 v[226:227], v231 offset:3584
	s_waitcnt lgkmcnt(8)
	v_mfma_f32_32x32x16_bf16 v[32:47], v[116:119], v[48:51], v[32:47]
	v_mfma_f32_32x32x16_bf16 v[32:47], v[120:123], v[52:55], v[32:47]
	v_mfma_f32_32x32x16_bf16 v[32:47], v[124:127], v[56:59], v[32:47]
	v_mfma_f32_32x32x16_bf16 v[32:47], v[128:131], v[60:63], v[32:47]
	s_nop 11
	v_exp_f32_e32 v32, v32
	v_exp_f32_e32 v33, v33
	v_exp_f32_e32 v34, v34
	v_exp_f32_e32 v35, v35
	v_exp_f32_e32 v36, v36
	v_exp_f32_e32 v37, v37
	v_exp_f32_e32 v38, v38
	v_exp_f32_e32 v39, v39
	v_exp_f32_e32 v40, v40
	v_exp_f32_e32 v41, v41
	v_exp_f32_e32 v42, v42
	v_exp_f32_e32 v43, v43
	v_exp_f32_e32 v44, v44
	v_exp_f32_e32 v45, v45
	v_exp_f32_e32 v46, v46
	v_exp_f32_e32 v47, v47
	v_cvt_pk_bf16_f32 v64, v32, v33
	v_cvt_pk_bf16_f32 v65, v34, v35
	v_cvt_pk_bf16_f32 v66, v36, v37
	v_cvt_pk_bf16_f32 v67, v38, v39
	v_cvt_pk_bf16_f32 v68, v40, v41
	v_cvt_pk_bf16_f32 v69, v42, v43
	v_cvt_pk_bf16_f32 v70, v44, v45
	v_cvt_pk_bf16_f32 v71, v46, v47
	v_pk_add_f32 v[232:233], v[232:233], v[32:33]
	v_pk_add_f32 v[232:233], v[232:233], v[34:35]
	v_pk_add_f32 v[232:233], v[232:233], v[36:37]
	v_pk_add_f32 v[232:233], v[232:233], v[38:39]
	v_pk_add_f32 v[232:233], v[232:233], v[40:41]
	v_pk_add_f32 v[232:233], v[232:233], v[42:43]
	v_pk_add_f32 v[232:233], v[232:233], v[44:45]
	v_pk_add_f32 v[232:233], v[232:233], v[46:47]
	s_waitcnt lgkmcnt(0)
	v_mfma_f32_32x32x16_bf16 v[0:15], v[64:67], v[72:75], v[0:15]
	v_mfma_f32_32x32x16_bf16 v[16:31], v[64:67], v[76:79], v[16:31]
	v_mfma_f32_32x32x16_bf16 v[0:15], v[68:71], v[220:223], v[0:15]
	v_mfma_f32_32x32x16_bf16 v[16:31], v[68:71], v[224:227], v[16:31]
	global_load_dwordx4 v[116:119], v235, s[84:85]
	global_load_dwordx4 v[120:123], v236, s[84:85]
	global_load_dwordx4 v[124:127], v237, s[84:85]
	global_load_dwordx4 v[128:131], v238, s[84:85]
	global_load_dwordx4 v[132:135], v100, s[84:85] offset:768
	global_load_dwordx4 v[136:139], v149, s[84:85] offset:768
	global_load_dwordx4 v[140:143], v100, s[84:85] offset:832
	global_load_dwordx4 v[144:147], v149, s[84:85] offset:832
	s_add_u32 s84, s84, 0x30000
	s_addc_u32 s85, s85, 0
	s_waitcnt vmcnt(16)
	ds_write_b128 v247, v[156:159]
	ds_write_b128 v247, v[160:163] offset:1152
	ds_write_b128 v247, v[164:167] offset:2304
	ds_write_b128 v247, v[168:171] offset:3456
	ds_write_b128 v112, v[172:175]
	ds_write_b128 v112, v[176:179] offset:1024
	ds_write_b128 v112, v[180:183] offset:2048
	ds_write_b128 v112, v[184:187] offset:3072
	ds_read2_b32 v[32:33], v115 offset0:160 offset1:161
	ds_read2_b32 v[34:35], v115 offset0:162 offset1:163
	ds_read2_b32 v[36:37], v115 offset0:168 offset1:169
	ds_read2_b32 v[38:39], v115 offset0:170 offset1:171
	ds_read2_b32 v[40:41], v115 offset0:176 offset1:177
	ds_read2_b32 v[42:43], v115 offset0:178 offset1:179
	ds_read2_b32 v[44:45], v115 offset0:184 offset1:185
	ds_read2_b32 v[46:47], v115 offset0:186 offset1:187
	ds_read_b128 v[156:159], v248
	ds_read_b128 v[160:163], v248 offset:32
	ds_read_b128 v[164:167], v248 offset:64
	ds_read_b128 v[168:171], v248 offset:96
	ds_read_b64_tr_b16 v[72:73], v231
	ds_read_b64_tr_b16 v[74:75], v231 offset:512
	ds_read_b64_tr_b16 v[76:77], v231 offset:2048
	ds_read_b64_tr_b16 v[78:79], v231 offset:2560
	ds_read_b64_tr_b16 v[220:221], v231 offset:1024
	ds_read_b64_tr_b16 v[222:223], v231 offset:1536
	ds_read_b64_tr_b16 v[224:225], v231 offset:3072
	ds_read_b64_tr_b16 v[226:227], v231 offset:3584
	s_waitcnt lgkmcnt(8)
	v_mfma_f32_32x32x16_bf16 v[32:47], v[156:159], v[48:51], v[32:47]
	v_mfma_f32_32x32x16_bf16 v[32:47], v[160:163], v[52:55], v[32:47]
	v_mfma_f32_32x32x16_bf16 v[32:47], v[164:167], v[56:59], v[32:47]
	v_mfma_f32_32x32x16_bf16 v[32:47], v[168:171], v[60:63], v[32:47]
	s_nop 11
	v_exp_f32_e32 v32, v32
	v_exp_f32_e32 v33, v33
	v_exp_f32_e32 v34, v34
	v_exp_f32_e32 v35, v35
	v_exp_f32_e32 v36, v36
	v_exp_f32_e32 v37, v37
	v_exp_f32_e32 v38, v38
	v_exp_f32_e32 v39, v39
	v_exp_f32_e32 v40, v40
	v_exp_f32_e32 v41, v41
	v_exp_f32_e32 v42, v42
	v_exp_f32_e32 v43, v43
	v_exp_f32_e32 v44, v44
	v_exp_f32_e32 v45, v45
	v_exp_f32_e32 v46, v46
	v_exp_f32_e32 v47, v47
	v_cvt_pk_bf16_f32 v64, v32, v33
	v_cvt_pk_bf16_f32 v65, v34, v35
	v_cvt_pk_bf16_f32 v66, v36, v37
	v_cvt_pk_bf16_f32 v67, v38, v39
	v_cvt_pk_bf16_f32 v68, v40, v41
	v_cvt_pk_bf16_f32 v69, v42, v43
	v_cvt_pk_bf16_f32 v70, v44, v45
	v_cvt_pk_bf16_f32 v71, v46, v47
	v_pk_add_f32 v[232:233], v[232:233], v[32:33]
	v_pk_add_f32 v[232:233], v[232:233], v[34:35]
	v_pk_add_f32 v[232:233], v[232:233], v[36:37]
	v_pk_add_f32 v[232:233], v[232:233], v[38:39]
	v_pk_add_f32 v[232:233], v[232:233], v[40:41]
	v_pk_add_f32 v[232:233], v[232:233], v[42:43]
	v_pk_add_f32 v[232:233], v[232:233], v[44:45]
	v_pk_add_f32 v[232:233], v[232:233], v[46:47]
	s_waitcnt lgkmcnt(0)
	v_mfma_f32_32x32x16_bf16 v[0:15], v[64:67], v[72:75], v[0:15]
	v_mfma_f32_32x32x16_bf16 v[16:31], v[64:67], v[76:79], v[16:31]
	v_mfma_f32_32x32x16_bf16 v[0:15], v[68:71], v[220:223], v[0:15]
	v_mfma_f32_32x32x16_bf16 v[16:31], v[68:71], v[224:227], v[16:31]
	global_load_dwordx4 v[156:159], v235, s[84:85]
	global_load_dwordx4 v[160:163], v236, s[84:85]
	global_load_dwordx4 v[164:167], v237, s[84:85]
	global_load_dwordx4 v[168:171], v238, s[84:85]
	global_load_dwordx4 v[172:175], v100, s[84:85] offset:768
	global_load_dwordx4 v[176:179], v149, s[84:85] offset:768
	global_load_dwordx4 v[180:183], v100, s[84:85] offset:832
	global_load_dwordx4 v[184:187], v149, s[84:85] offset:832
	s_add_u32 s84, s84, 0x30000
	s_addc_u32 s85, s85, 0
	s_waitcnt vmcnt(16)
	ds_write_b128 v247, v[188:191]
	ds_write_b128 v247, v[192:195] offset:1152
	ds_write_b128 v247, v[196:199] offset:2304
	ds_write_b128 v247, v[200:203] offset:3456
	ds_write_b128 v112, v[204:207]
	ds_write_b128 v112, v[208:211] offset:1024
	ds_write_b128 v112, v[212:215] offset:2048
	ds_write_b128 v112, v[216:219] offset:3072
	ds_read2_b32 v[32:33], v115 offset0:192 offset1:193
	ds_read2_b32 v[34:35], v115 offset0:194 offset1:195
	ds_read2_b32 v[36:37], v115 offset0:200 offset1:201
	ds_read2_b32 v[38:39], v115 offset0:202 offset1:203
	ds_read2_b32 v[40:41], v115 offset0:208 offset1:209
	ds_read2_b32 v[42:43], v115 offset0:210 offset1:211
	ds_read2_b32 v[44:45], v115 offset0:216 offset1:217
	ds_read2_b32 v[46:47], v115 offset0:218 offset1:219
	ds_read_b128 v[188:191], v248
	ds_read_b128 v[192:195], v248 offset:32
	ds_read_b128 v[196:199], v248 offset:64
	ds_read_b128 v[200:203], v248 offset:96
	ds_read_b64_tr_b16 v[72:73], v231
	ds_read_b64_tr_b16 v[74:75], v231 offset:512
	ds_read_b64_tr_b16 v[76:77], v231 offset:2048
	ds_read_b64_tr_b16 v[78:79], v231 offset:2560
	ds_read_b64_tr_b16 v[220:221], v231 offset:1024
	ds_read_b64_tr_b16 v[222:223], v231 offset:1536
	ds_read_b64_tr_b16 v[224:225], v231 offset:3072
	ds_read_b64_tr_b16 v[226:227], v231 offset:3584
	s_waitcnt lgkmcnt(8)
	v_mfma_f32_32x32x16_bf16 v[32:47], v[188:191], v[48:51], v[32:47]
	v_mfma_f32_32x32x16_bf16 v[32:47], v[192:195], v[52:55], v[32:47]
	v_mfma_f32_32x32x16_bf16 v[32:47], v[196:199], v[56:59], v[32:47]
	v_mfma_f32_32x32x16_bf16 v[32:47], v[200:203], v[60:63], v[32:47]
	s_nop 11
	v_exp_f32_e32 v32, v32
	v_exp_f32_e32 v33, v33
	v_exp_f32_e32 v34, v34
	v_exp_f32_e32 v35, v35
	v_exp_f32_e32 v36, v36
	v_exp_f32_e32 v37, v37
	v_exp_f32_e32 v38, v38
	v_exp_f32_e32 v39, v39
	v_exp_f32_e32 v40, v40
	v_exp_f32_e32 v41, v41
	v_exp_f32_e32 v42, v42
	v_exp_f32_e32 v43, v43
	v_exp_f32_e32 v44, v44
	v_exp_f32_e32 v45, v45
	v_exp_f32_e32 v46, v46
	v_exp_f32_e32 v47, v47
	v_cvt_pk_bf16_f32 v64, v32, v33
	v_cvt_pk_bf16_f32 v65, v34, v35
	v_cvt_pk_bf16_f32 v66, v36, v37
	v_cvt_pk_bf16_f32 v67, v38, v39
	v_cvt_pk_bf16_f32 v68, v40, v41
	v_cvt_pk_bf16_f32 v69, v42, v43
	v_cvt_pk_bf16_f32 v70, v44, v45
	v_cvt_pk_bf16_f32 v71, v46, v47
	v_pk_add_f32 v[232:233], v[232:233], v[32:33]
	v_pk_add_f32 v[232:233], v[232:233], v[34:35]
	v_pk_add_f32 v[232:233], v[232:233], v[36:37]
	v_pk_add_f32 v[232:233], v[232:233], v[38:39]
	v_pk_add_f32 v[232:233], v[232:233], v[40:41]
	v_pk_add_f32 v[232:233], v[232:233], v[42:43]
	v_pk_add_f32 v[232:233], v[232:233], v[44:45]
	v_pk_add_f32 v[232:233], v[232:233], v[46:47]
	s_waitcnt lgkmcnt(0)
	v_mfma_f32_32x32x16_bf16 v[0:15], v[64:67], v[72:75], v[0:15]
	v_mfma_f32_32x32x16_bf16 v[16:31], v[64:67], v[76:79], v[16:31]
	v_mfma_f32_32x32x16_bf16 v[0:15], v[68:71], v[220:223], v[0:15]
	v_mfma_f32_32x32x16_bf16 v[16:31], v[68:71], v[224:227], v[16:31]
	global_load_dwordx4 v[188:191], v235, s[84:85]
	global_load_dwordx4 v[192:195], v236, s[84:85]
	global_load_dwordx4 v[196:199], v237, s[84:85]
	global_load_dwordx4 v[200:203], v238, s[84:85]
	global_load_dwordx4 v[204:207], v100, s[84:85] offset:768
	global_load_dwordx4 v[208:211], v149, s[84:85] offset:768
	global_load_dwordx4 v[212:215], v100, s[84:85] offset:832
	global_load_dwordx4 v[216:219], v149, s[84:85] offset:832
	s_add_u32 s84, s84, 0x30000
	s_addc_u32 s85, s85, 0
	s_waitcnt vmcnt(16)
	ds_write_b128 v247, v[116:119]
	ds_write_b128 v247, v[120:123] offset:1152
	ds_write_b128 v247, v[124:127] offset:2304
	ds_write_b128 v247, v[128:131] offset:3456
	ds_write_b128 v112, v[132:135]
	ds_write_b128 v112, v[136:139] offset:1024
	ds_write_b128 v112, v[140:143] offset:2048
	ds_write_b128 v112, v[144:147] offset:3072
	ds_read2_b32 v[32:33], v115 offset0:224 offset1:225
	ds_read2_b32 v[34:35], v115 offset0:226 offset1:227
	ds_read2_b32 v[36:37], v115 offset0:232 offset1:233
	ds_read2_b32 v[38:39], v115 offset0:234 offset1:235
	ds_read2_b32 v[40:41], v115 offset0:240 offset1:241
	ds_read2_b32 v[42:43], v115 offset0:242 offset1:243
	ds_read2_b32 v[44:45], v115 offset0:248 offset1:249
	ds_read2_b32 v[46:47], v115 offset0:250 offset1:251
	ds_read_b128 v[116:119], v248
	ds_read_b128 v[120:123], v248 offset:32
	ds_read_b128 v[124:127], v248 offset:64
	ds_read_b128 v[128:131], v248 offset:96
	ds_read_b64_tr_b16 v[72:73], v231
	ds_read_b64_tr_b16 v[74:75], v231 offset:512
	ds_read_b64_tr_b16 v[76:77], v231 offset:2048
	ds_read_b64_tr_b16 v[78:79], v231 offset:2560
	ds_read_b64_tr_b16 v[220:221], v231 offset:1024
	ds_read_b64_tr_b16 v[222:223], v231 offset:1536
	ds_read_b64_tr_b16 v[224:225], v231 offset:3072
	ds_read_b64_tr_b16 v[226:227], v231 offset:3584
	s_waitcnt lgkmcnt(8)
	v_mfma_f32_32x32x16_bf16 v[32:47], v[116:119], v[48:51], v[32:47]
	v_mfma_f32_32x32x16_bf16 v[32:47], v[120:123], v[52:55], v[32:47]
	v_mfma_f32_32x32x16_bf16 v[32:47], v[124:127], v[56:59], v[32:47]
	v_mfma_f32_32x32x16_bf16 v[32:47], v[128:131], v[60:63], v[32:47]
	s_nop 11
	v_exp_f32_e32 v32, v32
	v_exp_f32_e32 v33, v33
	v_exp_f32_e32 v34, v34
	v_exp_f32_e32 v35, v35
	v_exp_f32_e32 v36, v36
	v_exp_f32_e32 v37, v37
	v_exp_f32_e32 v38, v38
	v_exp_f32_e32 v39, v39
	v_exp_f32_e32 v40, v40
	v_exp_f32_e32 v41, v41
	v_exp_f32_e32 v42, v42
	v_exp_f32_e32 v43, v43
	v_exp_f32_e32 v44, v44
	v_exp_f32_e32 v45, v45
	v_exp_f32_e32 v46, v46
	v_exp_f32_e32 v47, v47
	v_cvt_pk_bf16_f32 v64, v32, v33
	v_cvt_pk_bf16_f32 v65, v34, v35
	v_cvt_pk_bf16_f32 v66, v36, v37
	v_cvt_pk_bf16_f32 v67, v38, v39
	v_cvt_pk_bf16_f32 v68, v40, v41
	v_cvt_pk_bf16_f32 v69, v42, v43
	v_cvt_pk_bf16_f32 v70, v44, v45
	v_cvt_pk_bf16_f32 v71, v46, v47
	v_pk_add_f32 v[232:233], v[232:233], v[32:33]
	v_pk_add_f32 v[232:233], v[232:233], v[34:35]
	v_pk_add_f32 v[232:233], v[232:233], v[36:37]
	v_pk_add_f32 v[232:233], v[232:233], v[38:39]
	v_pk_add_f32 v[232:233], v[232:233], v[40:41]
	v_pk_add_f32 v[232:233], v[232:233], v[42:43]
	v_pk_add_f32 v[232:233], v[232:233], v[44:45]
	v_pk_add_f32 v[232:233], v[232:233], v[46:47]
	s_waitcnt lgkmcnt(0)
	v_mfma_f32_32x32x16_bf16 v[0:15], v[64:67], v[72:75], v[0:15]
	v_mfma_f32_32x32x16_bf16 v[16:31], v[64:67], v[76:79], v[16:31]
	v_mfma_f32_32x32x16_bf16 v[0:15], v[68:71], v[220:223], v[0:15]
	v_mfma_f32_32x32x16_bf16 v[16:31], v[68:71], v[224:227], v[16:31]
	global_load_dwordx4 v[116:119], v235, s[84:85]
	global_load_dwordx4 v[120:123], v236, s[84:85]
	global_load_dwordx4 v[124:127], v237, s[84:85]
	global_load_dwordx4 v[128:131], v238, s[84:85]
	global_load_dwordx4 v[132:135], v100, s[84:85] offset:768
	global_load_dwordx4 v[136:139], v149, s[84:85] offset:768
	global_load_dwordx4 v[140:143], v100, s[84:85] offset:832
	global_load_dwordx4 v[144:147], v149, s[84:85] offset:832
	s_add_u32 s84, s84, 0x30000
	s_addc_u32 s85, s85, 0
	s_waitcnt vmcnt(16)
	ds_write_b128 v247, v[156:159]
	ds_write_b128 v247, v[160:163] offset:1152
	ds_write_b128 v247, v[164:167] offset:2304
	ds_write_b128 v247, v[168:171] offset:3456
	ds_write_b128 v112, v[172:175]
	ds_write_b128 v112, v[176:179] offset:1024
	ds_write_b128 v112, v[180:183] offset:2048
	ds_write_b128 v112, v[184:187] offset:3072
	v_add_u32_e32 v115, 0x400, v115
	ds_read2_b32 v[32:33], v115 offset0:0 offset1:1
	ds_read2_b32 v[34:35], v115 offset0:2 offset1:3
	ds_read2_b32 v[36:37], v115 offset0:8 offset1:9
	ds_read2_b32 v[38:39], v115 offset0:10 offset1:11
	ds_read2_b32 v[40:41], v115 offset0:16 offset1:17
	ds_read2_b32 v[42:43], v115 offset0:18 offset1:19
	ds_read2_b32 v[44:45], v115 offset0:24 offset1:25
	ds_read2_b32 v[46:47], v115 offset0:26 offset1:27
	ds_read_b128 v[156:159], v248
	ds_read_b128 v[160:163], v248 offset:32
	ds_read_b128 v[164:167], v248 offset:64
	ds_read_b128 v[168:171], v248 offset:96
	ds_read_b64_tr_b16 v[72:73], v231
	ds_read_b64_tr_b16 v[74:75], v231 offset:512
	ds_read_b64_tr_b16 v[76:77], v231 offset:2048
	ds_read_b64_tr_b16 v[78:79], v231 offset:2560
	ds_read_b64_tr_b16 v[220:221], v231 offset:1024
	ds_read_b64_tr_b16 v[222:223], v231 offset:1536
	ds_read_b64_tr_b16 v[224:225], v231 offset:3072
	ds_read_b64_tr_b16 v[226:227], v231 offset:3584
	s_waitcnt lgkmcnt(8)
	v_mfma_f32_32x32x16_bf16 v[32:47], v[156:159], v[48:51], v[32:47]
	v_mfma_f32_32x32x16_bf16 v[32:47], v[160:163], v[52:55], v[32:47]
	v_mfma_f32_32x32x16_bf16 v[32:47], v[164:167], v[56:59], v[32:47]
	v_mfma_f32_32x32x16_bf16 v[32:47], v[168:171], v[60:63], v[32:47]
	s_nop 11
	v_exp_f32_e32 v32, v32
	v_exp_f32_e32 v33, v33
	v_exp_f32_e32 v34, v34
	v_exp_f32_e32 v35, v35
	v_exp_f32_e32 v36, v36
	v_exp_f32_e32 v37, v37
	v_exp_f32_e32 v38, v38
	v_exp_f32_e32 v39, v39
	v_exp_f32_e32 v40, v40
	v_exp_f32_e32 v41, v41
	v_exp_f32_e32 v42, v42
	v_exp_f32_e32 v43, v43
	v_exp_f32_e32 v44, v44
	v_exp_f32_e32 v45, v45
	v_exp_f32_e32 v46, v46
	v_exp_f32_e32 v47, v47
	v_cvt_pk_bf16_f32 v64, v32, v33
	v_cvt_pk_bf16_f32 v65, v34, v35
	v_cvt_pk_bf16_f32 v66, v36, v37
	v_cvt_pk_bf16_f32 v67, v38, v39
	v_cvt_pk_bf16_f32 v68, v40, v41
	v_cvt_pk_bf16_f32 v69, v42, v43
	v_cvt_pk_bf16_f32 v70, v44, v45
	v_cvt_pk_bf16_f32 v71, v46, v47
	v_pk_add_f32 v[232:233], v[232:233], v[32:33]
	v_pk_add_f32 v[232:233], v[232:233], v[34:35]
	v_pk_add_f32 v[232:233], v[232:233], v[36:37]
	v_pk_add_f32 v[232:233], v[232:233], v[38:39]
	v_pk_add_f32 v[232:233], v[232:233], v[40:41]
	v_pk_add_f32 v[232:233], v[232:233], v[42:43]
	v_pk_add_f32 v[232:233], v[232:233], v[44:45]
	v_pk_add_f32 v[232:233], v[232:233], v[46:47]
	s_waitcnt lgkmcnt(0)
	v_mfma_f32_32x32x16_bf16 v[0:15], v[64:67], v[72:75], v[0:15]
	v_mfma_f32_32x32x16_bf16 v[16:31], v[64:67], v[76:79], v[16:31]
	v_mfma_f32_32x32x16_bf16 v[0:15], v[68:71], v[220:223], v[0:15]
	v_mfma_f32_32x32x16_bf16 v[16:31], v[68:71], v[224:227], v[16:31]
	global_load_dwordx4 v[156:159], v235, s[84:85]
	global_load_dwordx4 v[160:163], v236, s[84:85]
	global_load_dwordx4 v[164:167], v237, s[84:85]
	global_load_dwordx4 v[168:171], v238, s[84:85]
	global_load_dwordx4 v[172:175], v100, s[84:85] offset:768
	global_load_dwordx4 v[176:179], v149, s[84:85] offset:768
	global_load_dwordx4 v[180:183], v100, s[84:85] offset:832
	global_load_dwordx4 v[184:187], v149, s[84:85] offset:832
	s_waitcnt vmcnt(16)
	ds_write_b128 v247, v[188:191]
	ds_write_b128 v247, v[192:195] offset:1152
	ds_write_b128 v247, v[196:199] offset:2304
	ds_write_b128 v247, v[200:203] offset:3456
	ds_write_b128 v112, v[204:207]
	ds_write_b128 v112, v[208:211] offset:1024
	ds_write_b128 v112, v[212:215] offset:2048
	ds_write_b128 v112, v[216:219] offset:3072
	ds_read2_b32 v[32:33], v115 offset0:32 offset1:33
	ds_read2_b32 v[34:35], v115 offset0:34 offset1:35
	ds_read2_b32 v[36:37], v115 offset0:40 offset1:41
	ds_read2_b32 v[38:39], v115 offset0:42 offset1:43
	ds_read2_b32 v[40:41], v115 offset0:48 offset1:49
	ds_read2_b32 v[42:43], v115 offset0:50 offset1:51
	ds_read2_b32 v[44:45], v115 offset0:56 offset1:57
	ds_read2_b32 v[46:47], v115 offset0:58 offset1:59
	ds_read_b128 v[188:191], v248
	ds_read_b128 v[192:195], v248 offset:32
	ds_read_b128 v[196:199], v248 offset:64
	ds_read_b128 v[200:203], v248 offset:96
	ds_read_b64_tr_b16 v[72:73], v231
	ds_read_b64_tr_b16 v[74:75], v231 offset:512
	ds_read_b64_tr_b16 v[76:77], v231 offset:2048
	ds_read_b64_tr_b16 v[78:79], v231 offset:2560
	ds_read_b64_tr_b16 v[220:221], v231 offset:1024
	ds_read_b64_tr_b16 v[222:223], v231 offset:1536
	ds_read_b64_tr_b16 v[224:225], v231 offset:3072
	ds_read_b64_tr_b16 v[226:227], v231 offset:3584
	s_waitcnt lgkmcnt(8)
	v_mfma_f32_32x32x16_bf16 v[32:47], v[188:191], v[48:51], v[32:47]
	v_mfma_f32_32x32x16_bf16 v[32:47], v[192:195], v[52:55], v[32:47]
	v_mfma_f32_32x32x16_bf16 v[32:47], v[196:199], v[56:59], v[32:47]
	v_mfma_f32_32x32x16_bf16 v[32:47], v[200:203], v[60:63], v[32:47]
	s_nop 11
	v_exp_f32_e32 v32, v32
	v_exp_f32_e32 v33, v33
	v_exp_f32_e32 v34, v34
	v_exp_f32_e32 v35, v35
	v_exp_f32_e32 v36, v36
	v_exp_f32_e32 v37, v37
	v_exp_f32_e32 v38, v38
	v_exp_f32_e32 v39, v39
	v_exp_f32_e32 v40, v40
	v_exp_f32_e32 v41, v41
	v_exp_f32_e32 v42, v42
	v_exp_f32_e32 v43, v43
	v_exp_f32_e32 v44, v44
	v_exp_f32_e32 v45, v45
	v_exp_f32_e32 v46, v46
	v_exp_f32_e32 v47, v47
	v_cvt_pk_bf16_f32 v64, v32, v33
	v_cvt_pk_bf16_f32 v65, v34, v35
	v_cvt_pk_bf16_f32 v66, v36, v37
	v_cvt_pk_bf16_f32 v67, v38, v39
	v_cvt_pk_bf16_f32 v68, v40, v41
	v_cvt_pk_bf16_f32 v69, v42, v43
	v_cvt_pk_bf16_f32 v70, v44, v45
	v_cvt_pk_bf16_f32 v71, v46, v47
	v_pk_add_f32 v[232:233], v[232:233], v[32:33]
	v_pk_add_f32 v[232:233], v[232:233], v[34:35]
	v_pk_add_f32 v[232:233], v[232:233], v[36:37]
	v_pk_add_f32 v[232:233], v[232:233], v[38:39]
	v_pk_add_f32 v[232:233], v[232:233], v[40:41]
	v_pk_add_f32 v[232:233], v[232:233], v[42:43]
	v_pk_add_f32 v[232:233], v[232:233], v[44:45]
	v_pk_add_f32 v[232:233], v[232:233], v[46:47]
	s_waitcnt lgkmcnt(0)
	v_mfma_f32_32x32x16_bf16 v[0:15], v[64:67], v[72:75], v[0:15]
	v_mfma_f32_32x32x16_bf16 v[16:31], v[64:67], v[76:79], v[16:31]
	v_mfma_f32_32x32x16_bf16 v[0:15], v[68:71], v[220:223], v[0:15]
	v_mfma_f32_32x32x16_bf16 v[16:31], v[68:71], v[224:227], v[16:31]
	global_load_dwordx4 v[188:191], v239, s[86:87]
	global_load_dwordx4 v[192:195], v240, s[86:87]
	global_load_dwordx4 v[196:199], v241, s[86:87]
	global_load_dwordx4 v[200:203], v242, s[86:87]
	global_load_dwordx4 v[204:207], v101, s[86:87] offset:768
	global_load_dwordx4 v[208:211], v150, s[86:87] offset:768
	global_load_dwordx4 v[212:215], v101, s[86:87] offset:832
	global_load_dwordx4 v[216:219], v150, s[86:87] offset:832
	s_add_u32 s86, s86, 0xc0000
	s_addc_u32 s87, s87, 0
	s_waitcnt vmcnt(16)
	ds_write_b128 v247, v[116:119]
	ds_write_b128 v247, v[120:123] offset:1152
	ds_write_b128 v247, v[124:127] offset:2304
	ds_write_b128 v247, v[128:131] offset:3456
	ds_write_b128 v112, v[132:135]
	ds_write_b128 v112, v[136:139] offset:1024
	ds_write_b128 v112, v[140:143] offset:2048
	ds_write_b128 v112, v[144:147] offset:3072
	ds_read2_b32 v[32:33], v115 offset0:64 offset1:65
	ds_read2_b32 v[34:35], v115 offset0:66 offset1:67
	ds_read2_b32 v[36:37], v115 offset0:72 offset1:73
	ds_read2_b32 v[38:39], v115 offset0:74 offset1:75
	ds_read2_b32 v[40:41], v115 offset0:80 offset1:81
	ds_read2_b32 v[42:43], v115 offset0:82 offset1:83
	ds_read2_b32 v[44:45], v115 offset0:88 offset1:89
	ds_read2_b32 v[46:47], v115 offset0:90 offset1:91
	ds_read_b128 v[116:119], v248
	ds_read_b128 v[120:123], v248 offset:32
	ds_read_b128 v[124:127], v248 offset:64
	ds_read_b128 v[128:131], v248 offset:96
	ds_read_b64_tr_b16 v[72:73], v231
	ds_read_b64_tr_b16 v[74:75], v231 offset:512
	ds_read_b64_tr_b16 v[76:77], v231 offset:2048
	ds_read_b64_tr_b16 v[78:79], v231 offset:2560
	ds_read_b64_tr_b16 v[220:221], v231 offset:1024
	ds_read_b64_tr_b16 v[222:223], v231 offset:1536
	ds_read_b64_tr_b16 v[224:225], v231 offset:3072
	ds_read_b64_tr_b16 v[226:227], v231 offset:3584
	s_waitcnt lgkmcnt(8)
	v_mfma_f32_32x32x16_bf16 v[32:47], v[116:119], v[48:51], v[32:47]
	v_mfma_f32_32x32x16_bf16 v[32:47], v[120:123], v[52:55], v[32:47]
	v_mfma_f32_32x32x16_bf16 v[32:47], v[124:127], v[56:59], v[32:47]
	v_mfma_f32_32x32x16_bf16 v[32:47], v[128:131], v[60:63], v[32:47]
	s_nop 11
	v_exp_f32_e32 v32, v32
	v_exp_f32_e32 v33, v33
	v_exp_f32_e32 v34, v34
	v_exp_f32_e32 v35, v35
	v_exp_f32_e32 v36, v36
	v_exp_f32_e32 v37, v37
	v_exp_f32_e32 v38, v38
	v_exp_f32_e32 v39, v39
	v_exp_f32_e32 v40, v40
	v_exp_f32_e32 v41, v41
	v_exp_f32_e32 v42, v42
	v_exp_f32_e32 v43, v43
	v_exp_f32_e32 v44, v44
	v_exp_f32_e32 v45, v45
	v_exp_f32_e32 v46, v46
	v_exp_f32_e32 v47, v47
	v_cvt_pk_bf16_f32 v64, v32, v33
	v_cvt_pk_bf16_f32 v65, v34, v35
	v_cvt_pk_bf16_f32 v66, v36, v37
	v_cvt_pk_bf16_f32 v67, v38, v39
	v_cvt_pk_bf16_f32 v68, v40, v41
	v_cvt_pk_bf16_f32 v69, v42, v43
	v_cvt_pk_bf16_f32 v70, v44, v45
	v_cvt_pk_bf16_f32 v71, v46, v47
	v_pk_add_f32 v[232:233], v[232:233], v[32:33]
	v_pk_add_f32 v[232:233], v[232:233], v[34:35]
	v_pk_add_f32 v[232:233], v[232:233], v[36:37]
	v_pk_add_f32 v[232:233], v[232:233], v[38:39]
	v_pk_add_f32 v[232:233], v[232:233], v[40:41]
	v_pk_add_f32 v[232:233], v[232:233], v[42:43]
	v_pk_add_f32 v[232:233], v[232:233], v[44:45]
	v_pk_add_f32 v[232:233], v[232:233], v[46:47]
	s_waitcnt lgkmcnt(0)
	v_mfma_f32_32x32x16_bf16 v[0:15], v[64:67], v[72:75], v[0:15]
	v_mfma_f32_32x32x16_bf16 v[16:31], v[64:67], v[76:79], v[16:31]
	v_mfma_f32_32x32x16_bf16 v[0:15], v[68:71], v[220:223], v[0:15]
	v_mfma_f32_32x32x16_bf16 v[16:31], v[68:71], v[224:227], v[16:31]
	global_load_dwordx4 v[116:119], v239, s[86:87]
	global_load_dwordx4 v[120:123], v240, s[86:87]
	global_load_dwordx4 v[124:127], v241, s[86:87]
	global_load_dwordx4 v[128:131], v242, s[86:87]
	global_load_dwordx4 v[132:135], v101, s[86:87] offset:768
	global_load_dwordx4 v[136:139], v150, s[86:87] offset:768
	global_load_dwordx4 v[140:143], v101, s[86:87] offset:832
	global_load_dwordx4 v[144:147], v150, s[86:87] offset:832
	s_add_u32 s86, s86, 0xc0000
	s_addc_u32 s87, s87, 0
	s_waitcnt vmcnt(16)
	ds_write_b128 v247, v[156:159]
	ds_write_b128 v247, v[160:163] offset:1152
	ds_write_b128 v247, v[164:167] offset:2304
	ds_write_b128 v247, v[168:171] offset:3456
	ds_write_b128 v112, v[172:175]
	ds_write_b128 v112, v[176:179] offset:1024
	ds_write_b128 v112, v[180:183] offset:2048
	ds_write_b128 v112, v[184:187] offset:3072
	ds_read2_b32 v[32:33], v115 offset0:96 offset1:97
	ds_read2_b32 v[34:35], v115 offset0:98 offset1:99
	ds_read2_b32 v[36:37], v115 offset0:104 offset1:105
	ds_read2_b32 v[38:39], v115 offset0:106 offset1:107
	ds_read2_b32 v[40:41], v115 offset0:112 offset1:113
	ds_read2_b32 v[42:43], v115 offset0:114 offset1:115
	ds_read2_b32 v[44:45], v115 offset0:120 offset1:121
	ds_read2_b32 v[46:47], v115 offset0:122 offset1:123
	ds_read_b128 v[156:159], v248
	ds_read_b128 v[160:163], v248 offset:32
	ds_read_b128 v[164:167], v248 offset:64
	ds_read_b128 v[168:171], v248 offset:96
	ds_read_b64_tr_b16 v[72:73], v231
	ds_read_b64_tr_b16 v[74:75], v231 offset:512
	ds_read_b64_tr_b16 v[76:77], v231 offset:2048
	ds_read_b64_tr_b16 v[78:79], v231 offset:2560
	ds_read_b64_tr_b16 v[220:221], v231 offset:1024
	ds_read_b64_tr_b16 v[222:223], v231 offset:1536
	ds_read_b64_tr_b16 v[224:225], v231 offset:3072
	ds_read_b64_tr_b16 v[226:227], v231 offset:3584
	s_waitcnt lgkmcnt(8)
	v_mfma_f32_32x32x16_bf16 v[32:47], v[156:159], v[48:51], v[32:47]
	v_mfma_f32_32x32x16_bf16 v[32:47], v[160:163], v[52:55], v[32:47]
	v_mfma_f32_32x32x16_bf16 v[32:47], v[164:167], v[56:59], v[32:47]
	v_mfma_f32_32x32x16_bf16 v[32:47], v[168:171], v[60:63], v[32:47]
	s_nop 11
	v_exp_f32_e32 v32, v32
	v_exp_f32_e32 v33, v33
	v_exp_f32_e32 v34, v34
	v_exp_f32_e32 v35, v35
	v_exp_f32_e32 v36, v36
	v_exp_f32_e32 v37, v37
	v_exp_f32_e32 v38, v38
	v_exp_f32_e32 v39, v39
	v_exp_f32_e32 v40, v40
	v_exp_f32_e32 v41, v41
	v_exp_f32_e32 v42, v42
	v_exp_f32_e32 v43, v43
	v_exp_f32_e32 v44, v44
	v_exp_f32_e32 v45, v45
	v_exp_f32_e32 v46, v46
	v_exp_f32_e32 v47, v47
	v_cvt_pk_bf16_f32 v64, v32, v33
	v_cvt_pk_bf16_f32 v65, v34, v35
	v_cvt_pk_bf16_f32 v66, v36, v37
	v_cvt_pk_bf16_f32 v67, v38, v39
	v_cvt_pk_bf16_f32 v68, v40, v41
	v_cvt_pk_bf16_f32 v69, v42, v43
	v_cvt_pk_bf16_f32 v70, v44, v45
	v_cvt_pk_bf16_f32 v71, v46, v47
	v_pk_add_f32 v[232:233], v[232:233], v[32:33]
	v_pk_add_f32 v[232:233], v[232:233], v[34:35]
	v_pk_add_f32 v[232:233], v[232:233], v[36:37]
	v_pk_add_f32 v[232:233], v[232:233], v[38:39]
	v_pk_add_f32 v[232:233], v[232:233], v[40:41]
	v_pk_add_f32 v[232:233], v[232:233], v[42:43]
	v_pk_add_f32 v[232:233], v[232:233], v[44:45]
	v_pk_add_f32 v[232:233], v[232:233], v[46:47]
	s_waitcnt lgkmcnt(0)
	v_mfma_f32_32x32x16_bf16 v[0:15], v[64:67], v[72:75], v[0:15]
	v_mfma_f32_32x32x16_bf16 v[16:31], v[64:67], v[76:79], v[16:31]
	v_mfma_f32_32x32x16_bf16 v[0:15], v[68:71], v[220:223], v[0:15]
	v_mfma_f32_32x32x16_bf16 v[16:31], v[68:71], v[224:227], v[16:31]
	global_load_dwordx4 v[156:159], v239, s[86:87]
	global_load_dwordx4 v[160:163], v240, s[86:87]
	global_load_dwordx4 v[164:167], v241, s[86:87]
	global_load_dwordx4 v[168:171], v242, s[86:87]
	global_load_dwordx4 v[172:175], v101, s[86:87] offset:768
	global_load_dwordx4 v[176:179], v150, s[86:87] offset:768
	global_load_dwordx4 v[180:183], v101, s[86:87] offset:832
	global_load_dwordx4 v[184:187], v150, s[86:87] offset:832
	s_add_u32 s86, s86, 0xc0000
	s_addc_u32 s87, s87, 0
	s_waitcnt vmcnt(16)
	ds_write_b128 v247, v[188:191]
	ds_write_b128 v247, v[192:195] offset:1152
	ds_write_b128 v247, v[196:199] offset:2304
	ds_write_b128 v247, v[200:203] offset:3456
	ds_write_b128 v112, v[204:207]
	ds_write_b128 v112, v[208:211] offset:1024
	ds_write_b128 v112, v[212:215] offset:2048
	ds_write_b128 v112, v[216:219] offset:3072
	v_mov_b32_e32 v115, v229
	ds_read2_b32 v[32:33], v115 offset0:0 offset1:1
	ds_read2_b32 v[34:35], v115 offset0:2 offset1:3
	ds_read2_b32 v[36:37], v115 offset0:8 offset1:9
	ds_read2_b32 v[38:39], v115 offset0:10 offset1:11
	ds_read2_b32 v[40:41], v115 offset0:16 offset1:17
	ds_read2_b32 v[42:43], v115 offset0:18 offset1:19
	ds_read2_b32 v[44:45], v115 offset0:24 offset1:25
	ds_read2_b32 v[46:47], v115 offset0:26 offset1:27
	ds_read_b128 v[188:191], v248
	ds_read_b128 v[192:195], v248 offset:32
	ds_read_b128 v[196:199], v248 offset:64
	ds_read_b128 v[200:203], v248 offset:96
	ds_read_b64_tr_b16 v[72:73], v231
	ds_read_b64_tr_b16 v[74:75], v231 offset:512
	ds_read_b64_tr_b16 v[76:77], v231 offset:2048
	ds_read_b64_tr_b16 v[78:79], v231 offset:2560
	ds_read_b64_tr_b16 v[220:221], v231 offset:1024
	ds_read_b64_tr_b16 v[222:223], v231 offset:1536
	ds_read_b64_tr_b16 v[224:225], v231 offset:3072
	ds_read_b64_tr_b16 v[226:227], v231 offset:3584
	s_waitcnt lgkmcnt(8)
	v_mfma_f32_32x32x16_bf16 v[32:47], v[188:191], v[48:51], v[32:47]
	v_mfma_f32_32x32x16_bf16 v[32:47], v[192:195], v[52:55], v[32:47]
	v_mfma_f32_32x32x16_bf16 v[32:47], v[196:199], v[56:59], v[32:47]
	v_mfma_f32_32x32x16_bf16 v[32:47], v[200:203], v[60:63], v[32:47]
	s_nop 11
	v_exp_f32_e32 v32, v32
	v_exp_f32_e32 v33, v33
	v_exp_f32_e32 v34, v34
	v_exp_f32_e32 v35, v35
	v_exp_f32_e32 v36, v36
	v_exp_f32_e32 v37, v37
	v_exp_f32_e32 v38, v38
	v_exp_f32_e32 v39, v39
	v_exp_f32_e32 v40, v40
	v_exp_f32_e32 v41, v41
	v_exp_f32_e32 v42, v42
	v_exp_f32_e32 v43, v43
	v_exp_f32_e32 v44, v44
	v_exp_f32_e32 v45, v45
	v_exp_f32_e32 v46, v46
	v_exp_f32_e32 v47, v47
	v_cvt_pk_bf16_f32 v64, v32, v33
	v_cvt_pk_bf16_f32 v65, v34, v35
	v_cvt_pk_bf16_f32 v66, v36, v37
	v_cvt_pk_bf16_f32 v67, v38, v39
	v_cvt_pk_bf16_f32 v68, v40, v41
	v_cvt_pk_bf16_f32 v69, v42, v43
	v_cvt_pk_bf16_f32 v70, v44, v45
	v_cvt_pk_bf16_f32 v71, v46, v47
	v_pk_add_f32 v[232:233], v[232:233], v[32:33]
	v_pk_add_f32 v[232:233], v[232:233], v[34:35]
	v_pk_add_f32 v[232:233], v[232:233], v[36:37]
	v_pk_add_f32 v[232:233], v[232:233], v[38:39]
	v_pk_add_f32 v[232:233], v[232:233], v[40:41]
	v_pk_add_f32 v[232:233], v[232:233], v[42:43]
	v_pk_add_f32 v[232:233], v[232:233], v[44:45]
	v_pk_add_f32 v[232:233], v[232:233], v[46:47]
	s_waitcnt lgkmcnt(0)
	v_mfma_f32_32x32x16_bf16 v[0:15], v[64:67], v[72:75], v[0:15]
	v_mfma_f32_32x32x16_bf16 v[16:31], v[64:67], v[76:79], v[16:31]
	v_mfma_f32_32x32x16_bf16 v[0:15], v[68:71], v[220:223], v[0:15]
	v_mfma_f32_32x32x16_bf16 v[16:31], v[68:71], v[224:227], v[16:31]
	global_load_dwordx4 v[188:191], v239, s[86:87]
	global_load_dwordx4 v[192:195], v240, s[86:87]
	global_load_dwordx4 v[196:199], v241, s[86:87]
	global_load_dwordx4 v[200:203], v242, s[86:87]
	global_load_dwordx4 v[204:207], v101, s[86:87] offset:768
	global_load_dwordx4 v[208:211], v150, s[86:87] offset:768
	global_load_dwordx4 v[212:215], v101, s[86:87] offset:832
	global_load_dwordx4 v[216:219], v150, s[86:87] offset:832
	s_add_u32 s86, s86, 0xc0000
	s_addc_u32 s87, s87, 0
	s_waitcnt vmcnt(16)
	ds_write_b128 v247, v[116:119]
	ds_write_b128 v247, v[120:123] offset:1152
	ds_write_b128 v247, v[124:127] offset:2304
	ds_write_b128 v247, v[128:131] offset:3456
	ds_write_b128 v112, v[132:135]
	ds_write_b128 v112, v[136:139] offset:1024
	ds_write_b128 v112, v[140:143] offset:2048
	ds_write_b128 v112, v[144:147] offset:3072
	ds_read2_b32 v[32:33], v115 offset0:32 offset1:33
	ds_read2_b32 v[34:35], v115 offset0:34 offset1:35
	ds_read2_b32 v[36:37], v115 offset0:40 offset1:41
	ds_read2_b32 v[38:39], v115 offset0:42 offset1:43
	ds_read2_b32 v[40:41], v115 offset0:48 offset1:49
	ds_read2_b32 v[42:43], v115 offset0:50 offset1:51
	ds_read2_b32 v[44:45], v115 offset0:56 offset1:57
	ds_read2_b32 v[46:47], v115 offset0:58 offset1:59
	ds_read_b128 v[116:119], v248
	ds_read_b128 v[120:123], v248 offset:32
	ds_read_b128 v[124:127], v248 offset:64
	ds_read_b128 v[128:131], v248 offset:96
	ds_read_b64_tr_b16 v[72:73], v231
	ds_read_b64_tr_b16 v[74:75], v231 offset:512
	ds_read_b64_tr_b16 v[76:77], v231 offset:2048
	ds_read_b64_tr_b16 v[78:79], v231 offset:2560
	ds_read_b64_tr_b16 v[220:221], v231 offset:1024
	ds_read_b64_tr_b16 v[222:223], v231 offset:1536
	ds_read_b64_tr_b16 v[224:225], v231 offset:3072
	ds_read_b64_tr_b16 v[226:227], v231 offset:3584
	s_waitcnt lgkmcnt(8)
	v_mfma_f32_32x32x16_bf16 v[32:47], v[116:119], v[48:51], v[32:47]
	v_mfma_f32_32x32x16_bf16 v[32:47], v[120:123], v[52:55], v[32:47]
	v_mfma_f32_32x32x16_bf16 v[32:47], v[124:127], v[56:59], v[32:47]
	v_mfma_f32_32x32x16_bf16 v[32:47], v[128:131], v[60:63], v[32:47]
	s_nop 11
	v_exp_f32_e32 v32, v32
	v_exp_f32_e32 v33, v33
	v_exp_f32_e32 v34, v34
	v_exp_f32_e32 v35, v35
	v_exp_f32_e32 v36, v36
	v_exp_f32_e32 v37, v37
	v_exp_f32_e32 v38, v38
	v_exp_f32_e32 v39, v39
	v_exp_f32_e32 v40, v40
	v_exp_f32_e32 v41, v41
	v_exp_f32_e32 v42, v42
	v_exp_f32_e32 v43, v43
	v_exp_f32_e32 v44, v44
	v_exp_f32_e32 v45, v45
	v_exp_f32_e32 v46, v46
	v_exp_f32_e32 v47, v47
	v_cvt_pk_bf16_f32 v64, v32, v33
	v_cvt_pk_bf16_f32 v65, v34, v35
	v_cvt_pk_bf16_f32 v66, v36, v37
	v_cvt_pk_bf16_f32 v67, v38, v39
	v_cvt_pk_bf16_f32 v68, v40, v41
	v_cvt_pk_bf16_f32 v69, v42, v43
	v_cvt_pk_bf16_f32 v70, v44, v45
	v_cvt_pk_bf16_f32 v71, v46, v47
	v_pk_add_f32 v[232:233], v[232:233], v[32:33]
	v_pk_add_f32 v[232:233], v[232:233], v[34:35]
	v_pk_add_f32 v[232:233], v[232:233], v[36:37]
	v_pk_add_f32 v[232:233], v[232:233], v[38:39]
	v_pk_add_f32 v[232:233], v[232:233], v[40:41]
	v_pk_add_f32 v[232:233], v[232:233], v[42:43]
	v_pk_add_f32 v[232:233], v[232:233], v[44:45]
	v_pk_add_f32 v[232:233], v[232:233], v[46:47]
	s_waitcnt lgkmcnt(0)
	v_mfma_f32_32x32x16_bf16 v[0:15], v[64:67], v[72:75], v[0:15]
	v_mfma_f32_32x32x16_bf16 v[16:31], v[64:67], v[76:79], v[16:31]
	v_mfma_f32_32x32x16_bf16 v[0:15], v[68:71], v[220:223], v[0:15]
	v_mfma_f32_32x32x16_bf16 v[16:31], v[68:71], v[224:227], v[16:31]
	global_load_dwordx4 v[116:119], v239, s[86:87]
	global_load_dwordx4 v[120:123], v240, s[86:87]
	global_load_dwordx4 v[124:127], v241, s[86:87]
	global_load_dwordx4 v[128:131], v242, s[86:87]
	global_load_dwordx4 v[132:135], v101, s[86:87] offset:768
	global_load_dwordx4 v[136:139], v150, s[86:87] offset:768
	global_load_dwordx4 v[140:143], v101, s[86:87] offset:832
	global_load_dwordx4 v[144:147], v150, s[86:87] offset:832
	s_add_u32 s86, s86, 0xc0000
	s_addc_u32 s87, s87, 0
	s_waitcnt vmcnt(16)
	ds_write_b128 v247, v[156:159]
	ds_write_b128 v247, v[160:163] offset:1152
	ds_write_b128 v247, v[164:167] offset:2304
	ds_write_b128 v247, v[168:171] offset:3456
	ds_write_b128 v112, v[172:175]
	ds_write_b128 v112, v[176:179] offset:1024
	ds_write_b128 v112, v[180:183] offset:2048
	ds_write_b128 v112, v[184:187] offset:3072
	ds_read2_b32 v[32:33], v115 offset0:64 offset1:65
	ds_read2_b32 v[34:35], v115 offset0:66 offset1:67
	ds_read2_b32 v[36:37], v115 offset0:72 offset1:73
	ds_read2_b32 v[38:39], v115 offset0:74 offset1:75
	ds_read2_b32 v[40:41], v115 offset0:80 offset1:81
	ds_read2_b32 v[42:43], v115 offset0:82 offset1:83
	ds_read2_b32 v[44:45], v115 offset0:88 offset1:89
	ds_read2_b32 v[46:47], v115 offset0:90 offset1:91
	ds_read_b128 v[156:159], v248
	ds_read_b128 v[160:163], v248 offset:32
	ds_read_b128 v[164:167], v248 offset:64
	ds_read_b128 v[168:171], v248 offset:96
	ds_read_b64_tr_b16 v[72:73], v231
	ds_read_b64_tr_b16 v[74:75], v231 offset:512
	ds_read_b64_tr_b16 v[76:77], v231 offset:2048
	ds_read_b64_tr_b16 v[78:79], v231 offset:2560
	ds_read_b64_tr_b16 v[220:221], v231 offset:1024
	ds_read_b64_tr_b16 v[222:223], v231 offset:1536
	ds_read_b64_tr_b16 v[224:225], v231 offset:3072
	ds_read_b64_tr_b16 v[226:227], v231 offset:3584
	s_waitcnt lgkmcnt(8)
	v_mfma_f32_32x32x16_bf16 v[32:47], v[156:159], v[48:51], v[32:47]
	v_mfma_f32_32x32x16_bf16 v[32:47], v[160:163], v[52:55], v[32:47]
	v_mfma_f32_32x32x16_bf16 v[32:47], v[164:167], v[56:59], v[32:47]
	v_mfma_f32_32x32x16_bf16 v[32:47], v[168:171], v[60:63], v[32:47]
	s_nop 11
	v_exp_f32_e32 v32, v32
	v_exp_f32_e32 v33, v33
	v_exp_f32_e32 v34, v34
	v_exp_f32_e32 v35, v35
	v_exp_f32_e32 v36, v36
	v_exp_f32_e32 v37, v37
	v_exp_f32_e32 v38, v38
	v_exp_f32_e32 v39, v39
	v_exp_f32_e32 v40, v40
	v_exp_f32_e32 v41, v41
	v_exp_f32_e32 v42, v42
	v_exp_f32_e32 v43, v43
	v_exp_f32_e32 v44, v44
	v_exp_f32_e32 v45, v45
	v_exp_f32_e32 v46, v46
	v_exp_f32_e32 v47, v47
	v_cvt_pk_bf16_f32 v64, v32, v33
	v_cvt_pk_bf16_f32 v65, v34, v35
	v_cvt_pk_bf16_f32 v66, v36, v37
	v_cvt_pk_bf16_f32 v67, v38, v39
	v_cvt_pk_bf16_f32 v68, v40, v41
	v_cvt_pk_bf16_f32 v69, v42, v43
	v_cvt_pk_bf16_f32 v70, v44, v45
	v_cvt_pk_bf16_f32 v71, v46, v47
	v_pk_add_f32 v[232:233], v[232:233], v[32:33]
	v_pk_add_f32 v[232:233], v[232:233], v[34:35]
	v_pk_add_f32 v[232:233], v[232:233], v[36:37]
	v_pk_add_f32 v[232:233], v[232:233], v[38:39]
	v_pk_add_f32 v[232:233], v[232:233], v[40:41]
	v_pk_add_f32 v[232:233], v[232:233], v[42:43]
	v_pk_add_f32 v[232:233], v[232:233], v[44:45]
	v_pk_add_f32 v[232:233], v[232:233], v[46:47]
	s_waitcnt lgkmcnt(0)
	v_mfma_f32_32x32x16_bf16 v[0:15], v[64:67], v[72:75], v[0:15]
	v_mfma_f32_32x32x16_bf16 v[16:31], v[64:67], v[76:79], v[16:31]
	v_mfma_f32_32x32x16_bf16 v[0:15], v[68:71], v[220:223], v[0:15]
	v_mfma_f32_32x32x16_bf16 v[16:31], v[68:71], v[224:227], v[16:31]
	global_load_dwordx4 v[156:159], v239, s[86:87]
	global_load_dwordx4 v[160:163], v240, s[86:87]
	global_load_dwordx4 v[164:167], v241, s[86:87]
	global_load_dwordx4 v[168:171], v242, s[86:87]
	global_load_dwordx4 v[172:175], v101, s[86:87] offset:768
	global_load_dwordx4 v[176:179], v150, s[86:87] offset:768
	global_load_dwordx4 v[180:183], v101, s[86:87] offset:832
	global_load_dwordx4 v[184:187], v150, s[86:87] offset:832
	s_add_u32 s86, s86, 0xc0000
	s_addc_u32 s87, s87, 0
	s_waitcnt vmcnt(16)
	ds_write_b128 v247, v[188:191]
	ds_write_b128 v247, v[192:195] offset:1152
	ds_write_b128 v247, v[196:199] offset:2304
	ds_write_b128 v247, v[200:203] offset:3456
	ds_write_b128 v112, v[204:207]
	ds_write_b128 v112, v[208:211] offset:1024
	ds_write_b128 v112, v[212:215] offset:2048
	ds_write_b128 v112, v[216:219] offset:3072
	ds_read2_b32 v[32:33], v115 offset0:96 offset1:97
	ds_read2_b32 v[34:35], v115 offset0:98 offset1:99
	ds_read2_b32 v[36:37], v115 offset0:104 offset1:105
	ds_read2_b32 v[38:39], v115 offset0:106 offset1:107
	ds_read2_b32 v[40:41], v115 offset0:112 offset1:113
	ds_read2_b32 v[42:43], v115 offset0:114 offset1:115
	ds_read2_b32 v[44:45], v115 offset0:120 offset1:121
	ds_read2_b32 v[46:47], v115 offset0:122 offset1:123
	ds_read_b128 v[188:191], v248
	ds_read_b128 v[192:195], v248 offset:32
	ds_read_b128 v[196:199], v248 offset:64
	ds_read_b128 v[200:203], v248 offset:96
	ds_read_b64_tr_b16 v[72:73], v231
	ds_read_b64_tr_b16 v[74:75], v231 offset:512
	ds_read_b64_tr_b16 v[76:77], v231 offset:2048
	ds_read_b64_tr_b16 v[78:79], v231 offset:2560
	ds_read_b64_tr_b16 v[220:221], v231 offset:1024
	ds_read_b64_tr_b16 v[222:223], v231 offset:1536
	ds_read_b64_tr_b16 v[224:225], v231 offset:3072
	ds_read_b64_tr_b16 v[226:227], v231 offset:3584
	s_waitcnt lgkmcnt(8)
	v_mfma_f32_32x32x16_bf16 v[32:47], v[188:191], v[48:51], v[32:47]
	v_mfma_f32_32x32x16_bf16 v[32:47], v[192:195], v[52:55], v[32:47]
	v_mfma_f32_32x32x16_bf16 v[32:47], v[196:199], v[56:59], v[32:47]
	v_mfma_f32_32x32x16_bf16 v[32:47], v[200:203], v[60:63], v[32:47]
	s_nop 11
	v_exp_f32_e32 v32, v32
	v_exp_f32_e32 v33, v33
	v_exp_f32_e32 v34, v34
	v_exp_f32_e32 v35, v35
	v_exp_f32_e32 v36, v36
	v_exp_f32_e32 v37, v37
	v_exp_f32_e32 v38, v38
	v_exp_f32_e32 v39, v39
	v_exp_f32_e32 v40, v40
	v_exp_f32_e32 v41, v41
	v_exp_f32_e32 v42, v42
	v_exp_f32_e32 v43, v43
	v_exp_f32_e32 v44, v44
	v_exp_f32_e32 v45, v45
	v_exp_f32_e32 v46, v46
	v_exp_f32_e32 v47, v47
	v_cvt_pk_bf16_f32 v64, v32, v33
	v_cvt_pk_bf16_f32 v65, v34, v35
	v_cvt_pk_bf16_f32 v66, v36, v37
	v_cvt_pk_bf16_f32 v67, v38, v39
	v_cvt_pk_bf16_f32 v68, v40, v41
	v_cvt_pk_bf16_f32 v69, v42, v43
	v_cvt_pk_bf16_f32 v70, v44, v45
	v_cvt_pk_bf16_f32 v71, v46, v47
	v_pk_add_f32 v[232:233], v[232:233], v[32:33]
	v_pk_add_f32 v[232:233], v[232:233], v[34:35]
	v_pk_add_f32 v[232:233], v[232:233], v[36:37]
	v_pk_add_f32 v[232:233], v[232:233], v[38:39]
	v_pk_add_f32 v[232:233], v[232:233], v[40:41]
	v_pk_add_f32 v[232:233], v[232:233], v[42:43]
	v_pk_add_f32 v[232:233], v[232:233], v[44:45]
	v_pk_add_f32 v[232:233], v[232:233], v[46:47]
	s_waitcnt lgkmcnt(0)
	v_mfma_f32_32x32x16_bf16 v[0:15], v[64:67], v[72:75], v[0:15]
	v_mfma_f32_32x32x16_bf16 v[16:31], v[64:67], v[76:79], v[16:31]
	v_mfma_f32_32x32x16_bf16 v[0:15], v[68:71], v[220:223], v[0:15]
	v_mfma_f32_32x32x16_bf16 v[16:31], v[68:71], v[224:227], v[16:31]
	global_load_dwordx4 v[188:191], v239, s[86:87]
	global_load_dwordx4 v[192:195], v240, s[86:87]
	global_load_dwordx4 v[196:199], v241, s[86:87]
	global_load_dwordx4 v[200:203], v242, s[86:87]
	global_load_dwordx4 v[204:207], v101, s[86:87] offset:768
	global_load_dwordx4 v[208:211], v150, s[86:87] offset:768
	global_load_dwordx4 v[212:215], v101, s[86:87] offset:832
	global_load_dwordx4 v[216:219], v150, s[86:87] offset:832
	s_add_u32 s86, s86, 0xc0000
	s_addc_u32 s87, s87, 0
	s_waitcnt vmcnt(16)
	ds_write_b128 v247, v[116:119]
	ds_write_b128 v247, v[120:123] offset:1152
	ds_write_b128 v247, v[124:127] offset:2304
	ds_write_b128 v247, v[128:131] offset:3456
	ds_write_b128 v112, v[132:135]
	ds_write_b128 v112, v[136:139] offset:1024
	ds_write_b128 v112, v[140:143] offset:2048
	ds_write_b128 v112, v[144:147] offset:3072
	ds_read2_b32 v[32:33], v115 offset0:128 offset1:129
	ds_read2_b32 v[34:35], v115 offset0:130 offset1:131
	ds_read2_b32 v[36:37], v115 offset0:136 offset1:137
	ds_read2_b32 v[38:39], v115 offset0:138 offset1:139
	ds_read2_b32 v[40:41], v115 offset0:144 offset1:145
	ds_read2_b32 v[42:43], v115 offset0:146 offset1:147
	ds_read2_b32 v[44:45], v115 offset0:152 offset1:153
	ds_read2_b32 v[46:47], v115 offset0:154 offset1:155
	ds_read_b128 v[116:119], v248
	ds_read_b128 v[120:123], v248 offset:32
	ds_read_b128 v[124:127], v248 offset:64
	ds_read_b128 v[128:131], v248 offset:96
	ds_read_b64_tr_b16 v[72:73], v231
	ds_read_b64_tr_b16 v[74:75], v231 offset:512
	ds_read_b64_tr_b16 v[76:77], v231 offset:2048
	ds_read_b64_tr_b16 v[78:79], v231 offset:2560
	ds_read_b64_tr_b16 v[220:221], v231 offset:1024
	ds_read_b64_tr_b16 v[222:223], v231 offset:1536
	ds_read_b64_tr_b16 v[224:225], v231 offset:3072
	ds_read_b64_tr_b16 v[226:227], v231 offset:3584
	s_waitcnt lgkmcnt(8)
	v_mfma_f32_32x32x16_bf16 v[32:47], v[116:119], v[48:51], v[32:47]
	v_mfma_f32_32x32x16_bf16 v[32:47], v[120:123], v[52:55], v[32:47]
	v_mfma_f32_32x32x16_bf16 v[32:47], v[124:127], v[56:59], v[32:47]
	v_mfma_f32_32x32x16_bf16 v[32:47], v[128:131], v[60:63], v[32:47]
	s_nop 11
	v_exp_f32_e32 v32, v32
	v_exp_f32_e32 v33, v33
	v_exp_f32_e32 v34, v34
	v_exp_f32_e32 v35, v35
	v_exp_f32_e32 v36, v36
	v_exp_f32_e32 v37, v37
	v_exp_f32_e32 v38, v38
	v_exp_f32_e32 v39, v39
	v_exp_f32_e32 v40, v40
	v_exp_f32_e32 v41, v41
	v_exp_f32_e32 v42, v42
	v_exp_f32_e32 v43, v43
	v_exp_f32_e32 v44, v44
	v_exp_f32_e32 v45, v45
	v_exp_f32_e32 v46, v46
	v_exp_f32_e32 v47, v47
	v_cvt_pk_bf16_f32 v64, v32, v33
	v_cvt_pk_bf16_f32 v65, v34, v35
	v_cvt_pk_bf16_f32 v66, v36, v37
	v_cvt_pk_bf16_f32 v67, v38, v39
	v_cvt_pk_bf16_f32 v68, v40, v41
	v_cvt_pk_bf16_f32 v69, v42, v43
	v_cvt_pk_bf16_f32 v70, v44, v45
	v_cvt_pk_bf16_f32 v71, v46, v47
	v_pk_add_f32 v[232:233], v[232:233], v[32:33]
	v_pk_add_f32 v[232:233], v[232:233], v[34:35]
	v_pk_add_f32 v[232:233], v[232:233], v[36:37]
	v_pk_add_f32 v[232:233], v[232:233], v[38:39]
	v_pk_add_f32 v[232:233], v[232:233], v[40:41]
	v_pk_add_f32 v[232:233], v[232:233], v[42:43]
	v_pk_add_f32 v[232:233], v[232:233], v[44:45]
	v_pk_add_f32 v[232:233], v[232:233], v[46:47]
	s_waitcnt lgkmcnt(0)
	v_mfma_f32_32x32x16_bf16 v[0:15], v[64:67], v[72:75], v[0:15]
	v_mfma_f32_32x32x16_bf16 v[16:31], v[64:67], v[76:79], v[16:31]
	v_mfma_f32_32x32x16_bf16 v[0:15], v[68:71], v[220:223], v[0:15]
	v_mfma_f32_32x32x16_bf16 v[16:31], v[68:71], v[224:227], v[16:31]
	global_load_dwordx4 v[116:119], v239, s[86:87]
	global_load_dwordx4 v[120:123], v240, s[86:87]
	global_load_dwordx4 v[124:127], v241, s[86:87]
	global_load_dwordx4 v[128:131], v242, s[86:87]
	global_load_dwordx4 v[132:135], v101, s[86:87] offset:768
	global_load_dwordx4 v[136:139], v150, s[86:87] offset:768
	global_load_dwordx4 v[140:143], v101, s[86:87] offset:832
	global_load_dwordx4 v[144:147], v150, s[86:87] offset:832
	s_waitcnt vmcnt(16)
	ds_write_b128 v247, v[156:159]
	ds_write_b128 v247, v[160:163] offset:1152
	ds_write_b128 v247, v[164:167] offset:2304
	ds_write_b128 v247, v[168:171] offset:3456
	ds_write_b128 v112, v[172:175]
	ds_write_b128 v112, v[176:179] offset:1024
	ds_write_b128 v112, v[180:183] offset:2048
	ds_write_b128 v112, v[184:187] offset:3072
	ds_read2_b32 v[32:33], v115 offset0:160 offset1:161
	ds_read2_b32 v[34:35], v115 offset0:162 offset1:163
	ds_read2_b32 v[36:37], v115 offset0:168 offset1:169
	ds_read2_b32 v[38:39], v115 offset0:170 offset1:171
	ds_read2_b32 v[40:41], v115 offset0:176 offset1:177
	ds_read2_b32 v[42:43], v115 offset0:178 offset1:179
	ds_read2_b32 v[44:45], v115 offset0:184 offset1:185
	ds_read2_b32 v[46:47], v115 offset0:186 offset1:187
	ds_read_b128 v[156:159], v248
	ds_read_b128 v[160:163], v248 offset:32
	ds_read_b128 v[164:167], v248 offset:64
	ds_read_b128 v[168:171], v248 offset:96
	ds_read_b64_tr_b16 v[72:73], v231
	ds_read_b64_tr_b16 v[74:75], v231 offset:512
	ds_read_b64_tr_b16 v[76:77], v231 offset:2048
	ds_read_b64_tr_b16 v[78:79], v231 offset:2560
	ds_read_b64_tr_b16 v[220:221], v231 offset:1024
	ds_read_b64_tr_b16 v[222:223], v231 offset:1536
	ds_read_b64_tr_b16 v[224:225], v231 offset:3072
	ds_read_b64_tr_b16 v[226:227], v231 offset:3584
	s_waitcnt lgkmcnt(8)
	v_mfma_f32_32x32x16_bf16 v[32:47], v[156:159], v[48:51], v[32:47]
	v_mfma_f32_32x32x16_bf16 v[32:47], v[160:163], v[52:55], v[32:47]
	v_mfma_f32_32x32x16_bf16 v[32:47], v[164:167], v[56:59], v[32:47]
	v_mfma_f32_32x32x16_bf16 v[32:47], v[168:171], v[60:63], v[32:47]
	s_nop 11
	v_exp_f32_e32 v32, v32
	v_exp_f32_e32 v33, v33
	v_exp_f32_e32 v34, v34
	v_exp_f32_e32 v35, v35
	v_exp_f32_e32 v36, v36
	v_exp_f32_e32 v37, v37
	v_exp_f32_e32 v38, v38
	v_exp_f32_e32 v39, v39
	v_exp_f32_e32 v40, v40
	v_exp_f32_e32 v41, v41
	v_exp_f32_e32 v42, v42
	v_exp_f32_e32 v43, v43
	v_exp_f32_e32 v44, v44
	v_exp_f32_e32 v45, v45
	v_exp_f32_e32 v46, v46
	v_exp_f32_e32 v47, v47
	v_cvt_pk_bf16_f32 v64, v32, v33
	v_cvt_pk_bf16_f32 v65, v34, v35
	v_cvt_pk_bf16_f32 v66, v36, v37
	v_cvt_pk_bf16_f32 v67, v38, v39
	v_cvt_pk_bf16_f32 v68, v40, v41
	v_cvt_pk_bf16_f32 v69, v42, v43
	v_cvt_pk_bf16_f32 v70, v44, v45
	v_cvt_pk_bf16_f32 v71, v46, v47
	v_pk_add_f32 v[232:233], v[232:233], v[32:33]
	v_pk_add_f32 v[232:233], v[232:233], v[34:35]
	v_pk_add_f32 v[232:233], v[232:233], v[36:37]
	v_pk_add_f32 v[232:233], v[232:233], v[38:39]
	v_pk_add_f32 v[232:233], v[232:233], v[40:41]
	v_pk_add_f32 v[232:233], v[232:233], v[42:43]
	v_pk_add_f32 v[232:233], v[232:233], v[44:45]
	v_pk_add_f32 v[232:233], v[232:233], v[46:47]
	s_waitcnt lgkmcnt(0)
	v_mfma_f32_32x32x16_bf16 v[0:15], v[64:67], v[72:75], v[0:15]
	v_mfma_f32_32x32x16_bf16 v[16:31], v[64:67], v[76:79], v[16:31]
	v_mfma_f32_32x32x16_bf16 v[0:15], v[68:71], v[220:223], v[0:15]
	v_mfma_f32_32x32x16_bf16 v[16:31], v[68:71], v[224:227], v[16:31]
	global_load_dwordx4 v[156:159], v243, s[88:89]
	global_load_dwordx4 v[160:163], v244, s[88:89]
	global_load_dwordx4 v[164:167], v245, s[88:89]
	global_load_dwordx4 v[168:171], v246, s[88:89]
	global_load_dwordx4 v[172:175], v148, s[88:89] offset:768
	global_load_dwordx4 v[176:179], v151, s[88:89] offset:768
	global_load_dwordx4 v[180:183], v148, s[88:89] offset:832
	global_load_dwordx4 v[184:187], v151, s[88:89] offset:832
	s_add_u32 s88, s88, 0x300000
	s_addc_u32 s89, s89, 0
	s_waitcnt vmcnt(16)
	ds_write_b128 v247, v[188:191]
	ds_write_b128 v247, v[192:195] offset:1152
	ds_write_b128 v247, v[196:199] offset:2304
	ds_write_b128 v247, v[200:203] offset:3456
	ds_write_b128 v112, v[204:207]
	ds_write_b128 v112, v[208:211] offset:1024
	ds_write_b128 v112, v[212:215] offset:2048
	ds_write_b128 v112, v[216:219] offset:3072
	ds_read2_b32 v[32:33], v115 offset0:192 offset1:193
	ds_read2_b32 v[34:35], v115 offset0:194 offset1:195
	ds_read2_b32 v[36:37], v115 offset0:200 offset1:201
	ds_read2_b32 v[38:39], v115 offset0:202 offset1:203
	ds_read2_b32 v[40:41], v115 offset0:208 offset1:209
	ds_read2_b32 v[42:43], v115 offset0:210 offset1:211
	ds_read2_b32 v[44:45], v115 offset0:216 offset1:217
	ds_read2_b32 v[46:47], v115 offset0:218 offset1:219
	ds_read_b128 v[188:191], v248
	ds_read_b128 v[192:195], v248 offset:32
	ds_read_b128 v[196:199], v248 offset:64
	ds_read_b128 v[200:203], v248 offset:96
	ds_read_b64_tr_b16 v[72:73], v231
	ds_read_b64_tr_b16 v[74:75], v231 offset:512
	ds_read_b64_tr_b16 v[76:77], v231 offset:2048
	ds_read_b64_tr_b16 v[78:79], v231 offset:2560
	ds_read_b64_tr_b16 v[220:221], v231 offset:1024
	ds_read_b64_tr_b16 v[222:223], v231 offset:1536
	ds_read_b64_tr_b16 v[224:225], v231 offset:3072
	ds_read_b64_tr_b16 v[226:227], v231 offset:3584
	s_waitcnt lgkmcnt(8)
	v_mfma_f32_32x32x16_bf16 v[32:47], v[188:191], v[48:51], v[32:47]
	v_mfma_f32_32x32x16_bf16 v[32:47], v[192:195], v[52:55], v[32:47]
	v_mfma_f32_32x32x16_bf16 v[32:47], v[196:199], v[56:59], v[32:47]
	v_mfma_f32_32x32x16_bf16 v[32:47], v[200:203], v[60:63], v[32:47]
	s_nop 11
	v_exp_f32_e32 v32, v32
	v_exp_f32_e32 v33, v33
	v_exp_f32_e32 v34, v34
	v_exp_f32_e32 v35, v35
	v_exp_f32_e32 v36, v36
	v_exp_f32_e32 v37, v37
	v_exp_f32_e32 v38, v38
	v_exp_f32_e32 v39, v39
	v_exp_f32_e32 v40, v40
	v_exp_f32_e32 v41, v41
	v_exp_f32_e32 v42, v42
	v_exp_f32_e32 v43, v43
	v_exp_f32_e32 v44, v44
	v_exp_f32_e32 v45, v45
	v_exp_f32_e32 v46, v46
	v_exp_f32_e32 v47, v47
	v_cvt_pk_bf16_f32 v64, v32, v33
	v_cvt_pk_bf16_f32 v65, v34, v35
	v_cvt_pk_bf16_f32 v66, v36, v37
	v_cvt_pk_bf16_f32 v67, v38, v39
	v_cvt_pk_bf16_f32 v68, v40, v41
	v_cvt_pk_bf16_f32 v69, v42, v43
	v_cvt_pk_bf16_f32 v70, v44, v45
	v_cvt_pk_bf16_f32 v71, v46, v47
	v_pk_add_f32 v[232:233], v[232:233], v[32:33]
	v_pk_add_f32 v[232:233], v[232:233], v[34:35]
	v_pk_add_f32 v[232:233], v[232:233], v[36:37]
	v_pk_add_f32 v[232:233], v[232:233], v[38:39]
	v_pk_add_f32 v[232:233], v[232:233], v[40:41]
	v_pk_add_f32 v[232:233], v[232:233], v[42:43]
	v_pk_add_f32 v[232:233], v[232:233], v[44:45]
	v_pk_add_f32 v[232:233], v[232:233], v[46:47]
	s_waitcnt lgkmcnt(0)
	v_mfma_f32_32x32x16_bf16 v[0:15], v[64:67], v[72:75], v[0:15]
	v_mfma_f32_32x32x16_bf16 v[16:31], v[64:67], v[76:79], v[16:31]
	v_mfma_f32_32x32x16_bf16 v[0:15], v[68:71], v[220:223], v[0:15]
	v_mfma_f32_32x32x16_bf16 v[16:31], v[68:71], v[224:227], v[16:31]
	global_load_dwordx4 v[188:191], v243, s[88:89]
	global_load_dwordx4 v[192:195], v244, s[88:89]
	global_load_dwordx4 v[196:199], v245, s[88:89]
	global_load_dwordx4 v[200:203], v246, s[88:89]
	global_load_dwordx4 v[204:207], v148, s[88:89] offset:768
	global_load_dwordx4 v[208:211], v151, s[88:89] offset:768
	global_load_dwordx4 v[212:215], v148, s[88:89] offset:832
	global_load_dwordx4 v[216:219], v151, s[88:89] offset:832
	s_add_u32 s88, s88, 0x300000
	s_addc_u32 s89, s89, 0
	s_waitcnt vmcnt(16)
	ds_write_b128 v247, v[116:119]
	ds_write_b128 v247, v[120:123] offset:1152
	ds_write_b128 v247, v[124:127] offset:2304
	ds_write_b128 v247, v[128:131] offset:3456
	ds_write_b128 v112, v[132:135]
	ds_write_b128 v112, v[136:139] offset:1024
	ds_write_b128 v112, v[140:143] offset:2048
	ds_write_b128 v112, v[144:147] offset:3072
	ds_read2_b32 v[32:33], v115 offset0:224 offset1:225
	ds_read2_b32 v[34:35], v115 offset0:226 offset1:227
	ds_read2_b32 v[36:37], v115 offset0:232 offset1:233
	ds_read2_b32 v[38:39], v115 offset0:234 offset1:235
	ds_read2_b32 v[40:41], v115 offset0:240 offset1:241
	ds_read2_b32 v[42:43], v115 offset0:242 offset1:243
	ds_read2_b32 v[44:45], v115 offset0:248 offset1:249
	ds_read2_b32 v[46:47], v115 offset0:250 offset1:251
	ds_read_b128 v[116:119], v248
	ds_read_b128 v[120:123], v248 offset:32
	ds_read_b128 v[124:127], v248 offset:64
	ds_read_b128 v[128:131], v248 offset:96
	ds_read_b64_tr_b16 v[72:73], v231
	ds_read_b64_tr_b16 v[74:75], v231 offset:512
	ds_read_b64_tr_b16 v[76:77], v231 offset:2048
	ds_read_b64_tr_b16 v[78:79], v231 offset:2560
	ds_read_b64_tr_b16 v[220:221], v231 offset:1024
	ds_read_b64_tr_b16 v[222:223], v231 offset:1536
	ds_read_b64_tr_b16 v[224:225], v231 offset:3072
	ds_read_b64_tr_b16 v[226:227], v231 offset:3584
	s_waitcnt lgkmcnt(8)
	v_mfma_f32_32x32x16_bf16 v[32:47], v[116:119], v[48:51], v[32:47]
	v_mfma_f32_32x32x16_bf16 v[32:47], v[120:123], v[52:55], v[32:47]
	v_mfma_f32_32x32x16_bf16 v[32:47], v[124:127], v[56:59], v[32:47]
	v_mfma_f32_32x32x16_bf16 v[32:47], v[128:131], v[60:63], v[32:47]
	s_nop 11
	v_exp_f32_e32 v32, v32
	v_exp_f32_e32 v33, v33
	v_exp_f32_e32 v34, v34
	v_exp_f32_e32 v35, v35
	v_exp_f32_e32 v36, v36
	v_exp_f32_e32 v37, v37
	v_exp_f32_e32 v38, v38
	v_exp_f32_e32 v39, v39
	v_exp_f32_e32 v40, v40
	v_exp_f32_e32 v41, v41
	v_exp_f32_e32 v42, v42
	v_exp_f32_e32 v43, v43
	v_exp_f32_e32 v44, v44
	v_exp_f32_e32 v45, v45
	v_exp_f32_e32 v46, v46
	v_exp_f32_e32 v47, v47
	v_cvt_pk_bf16_f32 v64, v32, v33
	v_cvt_pk_bf16_f32 v65, v34, v35
	v_cvt_pk_bf16_f32 v66, v36, v37
	v_cvt_pk_bf16_f32 v67, v38, v39
	v_cvt_pk_bf16_f32 v68, v40, v41
	v_cvt_pk_bf16_f32 v69, v42, v43
	v_cvt_pk_bf16_f32 v70, v44, v45
	v_cvt_pk_bf16_f32 v71, v46, v47
	v_pk_add_f32 v[232:233], v[232:233], v[32:33]
	v_pk_add_f32 v[232:233], v[232:233], v[34:35]
	v_pk_add_f32 v[232:233], v[232:233], v[36:37]
	v_pk_add_f32 v[232:233], v[232:233], v[38:39]
	v_pk_add_f32 v[232:233], v[232:233], v[40:41]
	v_pk_add_f32 v[232:233], v[232:233], v[42:43]
	v_pk_add_f32 v[232:233], v[232:233], v[44:45]
	v_pk_add_f32 v[232:233], v[232:233], v[46:47]
	s_waitcnt lgkmcnt(0)
	v_mfma_f32_32x32x16_bf16 v[0:15], v[64:67], v[72:75], v[0:15]
	v_mfma_f32_32x32x16_bf16 v[16:31], v[64:67], v[76:79], v[16:31]
	v_mfma_f32_32x32x16_bf16 v[0:15], v[68:71], v[220:223], v[0:15]
	v_mfma_f32_32x32x16_bf16 v[16:31], v[68:71], v[224:227], v[16:31]
	global_load_dwordx4 v[116:119], v243, s[88:89]
	global_load_dwordx4 v[120:123], v244, s[88:89]
	global_load_dwordx4 v[124:127], v245, s[88:89]
	global_load_dwordx4 v[128:131], v246, s[88:89]
	global_load_dwordx4 v[132:135], v148, s[88:89] offset:768
	global_load_dwordx4 v[136:139], v151, s[88:89] offset:768
	global_load_dwordx4 v[140:143], v148, s[88:89] offset:832
	global_load_dwordx4 v[144:147], v151, s[88:89] offset:832
	s_add_u32 s88, s88, 0x300000
	s_addc_u32 s89, s89, 0
	s_waitcnt vmcnt(16)
	ds_write_b128 v247, v[156:159]
	ds_write_b128 v247, v[160:163] offset:1152
	ds_write_b128 v247, v[164:167] offset:2304
	ds_write_b128 v247, v[168:171] offset:3456
	ds_write_b128 v112, v[172:175]
	ds_write_b128 v112, v[176:179] offset:1024
	ds_write_b128 v112, v[180:183] offset:2048
	ds_write_b128 v112, v[184:187] offset:3072
	v_mov_b32_e32 v115, v230
	ds_read2_b32 v[32:33], v115 offset0:0 offset1:1
	ds_read2_b32 v[34:35], v115 offset0:2 offset1:3
	ds_read2_b32 v[36:37], v115 offset0:8 offset1:9
	ds_read2_b32 v[38:39], v115 offset0:10 offset1:11
	ds_read2_b32 v[40:41], v115 offset0:16 offset1:17
	ds_read2_b32 v[42:43], v115 offset0:18 offset1:19
	ds_read2_b32 v[44:45], v115 offset0:24 offset1:25
	ds_read2_b32 v[46:47], v115 offset0:26 offset1:27
	ds_read_b128 v[156:159], v248
	ds_read_b128 v[160:163], v248 offset:32
	ds_read_b128 v[164:167], v248 offset:64
	ds_read_b128 v[168:171], v248 offset:96
	ds_read_b64_tr_b16 v[72:73], v231
	ds_read_b64_tr_b16 v[74:75], v231 offset:512
	ds_read_b64_tr_b16 v[76:77], v231 offset:2048
	ds_read_b64_tr_b16 v[78:79], v231 offset:2560
	ds_read_b64_tr_b16 v[220:221], v231 offset:1024
	ds_read_b64_tr_b16 v[222:223], v231 offset:1536
	ds_read_b64_tr_b16 v[224:225], v231 offset:3072
	ds_read_b64_tr_b16 v[226:227], v231 offset:3584
	s_waitcnt lgkmcnt(8)
	v_mfma_f32_32x32x16_bf16 v[32:47], v[156:159], v[48:51], v[32:47]
	v_mfma_f32_32x32x16_bf16 v[32:47], v[160:163], v[52:55], v[32:47]
	v_mfma_f32_32x32x16_bf16 v[32:47], v[164:167], v[56:59], v[32:47]
	v_mfma_f32_32x32x16_bf16 v[32:47], v[168:171], v[60:63], v[32:47]
	s_nop 11
	v_exp_f32_e32 v32, v32
	v_exp_f32_e32 v33, v33
	v_exp_f32_e32 v34, v34
	v_exp_f32_e32 v35, v35
	v_exp_f32_e32 v36, v36
	v_exp_f32_e32 v37, v37
	v_exp_f32_e32 v38, v38
	v_exp_f32_e32 v39, v39
	v_exp_f32_e32 v40, v40
	v_exp_f32_e32 v41, v41
	v_exp_f32_e32 v42, v42
	v_exp_f32_e32 v43, v43
	v_exp_f32_e32 v44, v44
	v_exp_f32_e32 v45, v45
	v_exp_f32_e32 v46, v46
	v_exp_f32_e32 v47, v47
	v_cvt_pk_bf16_f32 v64, v32, v33
	v_cvt_pk_bf16_f32 v65, v34, v35
	v_cvt_pk_bf16_f32 v66, v36, v37
	v_cvt_pk_bf16_f32 v67, v38, v39
	v_cvt_pk_bf16_f32 v68, v40, v41
	v_cvt_pk_bf16_f32 v69, v42, v43
	v_cvt_pk_bf16_f32 v70, v44, v45
	v_cvt_pk_bf16_f32 v71, v46, v47
	v_pk_add_f32 v[232:233], v[232:233], v[32:33]
	v_pk_add_f32 v[232:233], v[232:233], v[34:35]
	v_pk_add_f32 v[232:233], v[232:233], v[36:37]
	v_pk_add_f32 v[232:233], v[232:233], v[38:39]
	v_pk_add_f32 v[232:233], v[232:233], v[40:41]
	v_pk_add_f32 v[232:233], v[232:233], v[42:43]
	v_pk_add_f32 v[232:233], v[232:233], v[44:45]
	v_pk_add_f32 v[232:233], v[232:233], v[46:47]
	s_waitcnt lgkmcnt(0)
	v_mfma_f32_32x32x16_bf16 v[0:15], v[64:67], v[72:75], v[0:15]
	v_mfma_f32_32x32x16_bf16 v[16:31], v[64:67], v[76:79], v[16:31]
	v_mfma_f32_32x32x16_bf16 v[0:15], v[68:71], v[220:223], v[0:15]
	v_mfma_f32_32x32x16_bf16 v[16:31], v[68:71], v[224:227], v[16:31]
	global_load_dwordx4 v[156:159], v243, s[88:89]
	global_load_dwordx4 v[160:163], v244, s[88:89]
	global_load_dwordx4 v[164:167], v245, s[88:89]
	global_load_dwordx4 v[168:171], v246, s[88:89]
	global_load_dwordx4 v[172:175], v148, s[88:89] offset:768
	global_load_dwordx4 v[176:179], v151, s[88:89] offset:768
	global_load_dwordx4 v[180:183], v148, s[88:89] offset:832
	global_load_dwordx4 v[184:187], v151, s[88:89] offset:832
	s_add_u32 s88, s88, 0x300000
	s_addc_u32 s89, s89, 0
	s_waitcnt vmcnt(16)
	ds_write_b128 v247, v[188:191]
	ds_write_b128 v247, v[192:195] offset:1152
	ds_write_b128 v247, v[196:199] offset:2304
	ds_write_b128 v247, v[200:203] offset:3456
	ds_write_b128 v112, v[204:207]
	ds_write_b128 v112, v[208:211] offset:1024
	ds_write_b128 v112, v[212:215] offset:2048
	ds_write_b128 v112, v[216:219] offset:3072
	ds_read2_b32 v[32:33], v115 offset0:32 offset1:33
	ds_read2_b32 v[34:35], v115 offset0:34 offset1:35
	ds_read2_b32 v[36:37], v115 offset0:40 offset1:41
	ds_read2_b32 v[38:39], v115 offset0:42 offset1:43
	ds_read2_b32 v[40:41], v115 offset0:48 offset1:49
	ds_read2_b32 v[42:43], v115 offset0:50 offset1:51
	ds_read2_b32 v[44:45], v115 offset0:56 offset1:57
	ds_read2_b32 v[46:47], v115 offset0:58 offset1:59
	ds_read_b128 v[188:191], v248
	ds_read_b128 v[192:195], v248 offset:32
	ds_read_b128 v[196:199], v248 offset:64
	ds_read_b128 v[200:203], v248 offset:96
	ds_read_b64_tr_b16 v[72:73], v231
	ds_read_b64_tr_b16 v[74:75], v231 offset:512
	ds_read_b64_tr_b16 v[76:77], v231 offset:2048
	ds_read_b64_tr_b16 v[78:79], v231 offset:2560
	ds_read_b64_tr_b16 v[220:221], v231 offset:1024
	ds_read_b64_tr_b16 v[222:223], v231 offset:1536
	ds_read_b64_tr_b16 v[224:225], v231 offset:3072
	ds_read_b64_tr_b16 v[226:227], v231 offset:3584
	s_waitcnt lgkmcnt(8)
	v_mfma_f32_32x32x16_bf16 v[32:47], v[188:191], v[48:51], v[32:47]
	v_mfma_f32_32x32x16_bf16 v[32:47], v[192:195], v[52:55], v[32:47]
	v_mfma_f32_32x32x16_bf16 v[32:47], v[196:199], v[56:59], v[32:47]
	v_mfma_f32_32x32x16_bf16 v[32:47], v[200:203], v[60:63], v[32:47]
	s_nop 11
	v_exp_f32_e32 v32, v32
	v_exp_f32_e32 v33, v33
	v_exp_f32_e32 v34, v34
	v_exp_f32_e32 v35, v35
	v_exp_f32_e32 v36, v36
	v_exp_f32_e32 v37, v37
	v_exp_f32_e32 v38, v38
	v_exp_f32_e32 v39, v39
	v_exp_f32_e32 v40, v40
	v_exp_f32_e32 v41, v41
	v_exp_f32_e32 v42, v42
	v_exp_f32_e32 v43, v43
	v_exp_f32_e32 v44, v44
	v_exp_f32_e32 v45, v45
	v_exp_f32_e32 v46, v46
	v_exp_f32_e32 v47, v47
	v_cvt_pk_bf16_f32 v64, v32, v33
	v_cvt_pk_bf16_f32 v65, v34, v35
	v_cvt_pk_bf16_f32 v66, v36, v37
	v_cvt_pk_bf16_f32 v67, v38, v39
	v_cvt_pk_bf16_f32 v68, v40, v41
	v_cvt_pk_bf16_f32 v69, v42, v43
	v_cvt_pk_bf16_f32 v70, v44, v45
	v_cvt_pk_bf16_f32 v71, v46, v47
	v_pk_add_f32 v[232:233], v[232:233], v[32:33]
	v_pk_add_f32 v[232:233], v[232:233], v[34:35]
	v_pk_add_f32 v[232:233], v[232:233], v[36:37]
	v_pk_add_f32 v[232:233], v[232:233], v[38:39]
	v_pk_add_f32 v[232:233], v[232:233], v[40:41]
	v_pk_add_f32 v[232:233], v[232:233], v[42:43]
	v_pk_add_f32 v[232:233], v[232:233], v[44:45]
	v_pk_add_f32 v[232:233], v[232:233], v[46:47]
	s_waitcnt lgkmcnt(0)
	v_mfma_f32_32x32x16_bf16 v[0:15], v[64:67], v[72:75], v[0:15]
	v_mfma_f32_32x32x16_bf16 v[16:31], v[64:67], v[76:79], v[16:31]
	v_mfma_f32_32x32x16_bf16 v[0:15], v[68:71], v[220:223], v[0:15]
	v_mfma_f32_32x32x16_bf16 v[16:31], v[68:71], v[224:227], v[16:31]
	global_load_dwordx4 v[188:191], v243, s[88:89]
	global_load_dwordx4 v[192:195], v244, s[88:89]
	global_load_dwordx4 v[196:199], v245, s[88:89]
	global_load_dwordx4 v[200:203], v246, s[88:89]
	global_load_dwordx4 v[204:207], v148, s[88:89] offset:768
	global_load_dwordx4 v[208:211], v151, s[88:89] offset:768
	global_load_dwordx4 v[212:215], v148, s[88:89] offset:832
	global_load_dwordx4 v[216:219], v151, s[88:89] offset:832
	s_waitcnt vmcnt(16)
	ds_write_b128 v247, v[116:119]
	ds_write_b128 v247, v[120:123] offset:1152
	ds_write_b128 v247, v[124:127] offset:2304
	ds_write_b128 v247, v[128:131] offset:3456
	ds_write_b128 v112, v[132:135]
	ds_write_b128 v112, v[136:139] offset:1024
	ds_write_b128 v112, v[140:143] offset:2048
	ds_write_b128 v112, v[144:147] offset:3072
	ds_read2_b32 v[32:33], v115 offset0:64 offset1:65
	ds_read2_b32 v[34:35], v115 offset0:66 offset1:67
	ds_read2_b32 v[36:37], v115 offset0:72 offset1:73
	ds_read2_b32 v[38:39], v115 offset0:74 offset1:75
	ds_read2_b32 v[40:41], v115 offset0:80 offset1:81
	ds_read2_b32 v[42:43], v115 offset0:82 offset1:83
	ds_read2_b32 v[44:45], v115 offset0:88 offset1:89
	ds_read2_b32 v[46:47], v115 offset0:90 offset1:91
	ds_read_b128 v[116:119], v248
	ds_read_b128 v[120:123], v248 offset:32
	ds_read_b128 v[124:127], v248 offset:64
	ds_read_b128 v[128:131], v248 offset:96
	ds_read_b64_tr_b16 v[72:73], v231
	ds_read_b64_tr_b16 v[74:75], v231 offset:512
	ds_read_b64_tr_b16 v[76:77], v231 offset:2048
	ds_read_b64_tr_b16 v[78:79], v231 offset:2560
	ds_read_b64_tr_b16 v[220:221], v231 offset:1024
	ds_read_b64_tr_b16 v[222:223], v231 offset:1536
	ds_read_b64_tr_b16 v[224:225], v231 offset:3072
	ds_read_b64_tr_b16 v[226:227], v231 offset:3584
	s_waitcnt lgkmcnt(8)
	v_mfma_f32_32x32x16_bf16 v[32:47], v[116:119], v[48:51], v[32:47]
	v_mfma_f32_32x32x16_bf16 v[32:47], v[120:123], v[52:55], v[32:47]
	v_mfma_f32_32x32x16_bf16 v[32:47], v[124:127], v[56:59], v[32:47]
	v_mfma_f32_32x32x16_bf16 v[32:47], v[128:131], v[60:63], v[32:47]
	s_nop 11
	v_exp_f32_e32 v32, v32
	v_exp_f32_e32 v33, v33
	v_exp_f32_e32 v34, v34
	v_exp_f32_e32 v35, v35
	v_exp_f32_e32 v36, v36
	v_exp_f32_e32 v37, v37
	v_exp_f32_e32 v38, v38
	v_exp_f32_e32 v39, v39
	v_exp_f32_e32 v40, v40
	v_exp_f32_e32 v41, v41
	v_exp_f32_e32 v42, v42
	v_exp_f32_e32 v43, v43
	v_exp_f32_e32 v44, v44
	v_exp_f32_e32 v45, v45
	v_exp_f32_e32 v46, v46
	v_exp_f32_e32 v47, v47
	v_cvt_pk_bf16_f32 v64, v32, v33
	v_cvt_pk_bf16_f32 v65, v34, v35
	v_cvt_pk_bf16_f32 v66, v36, v37
	v_cvt_pk_bf16_f32 v67, v38, v39
	v_cvt_pk_bf16_f32 v68, v40, v41
	v_cvt_pk_bf16_f32 v69, v42, v43
	v_cvt_pk_bf16_f32 v70, v44, v45
	v_cvt_pk_bf16_f32 v71, v46, v47
	v_pk_add_f32 v[232:233], v[232:233], v[32:33]
	v_pk_add_f32 v[232:233], v[232:233], v[34:35]
	v_pk_add_f32 v[232:233], v[232:233], v[36:37]
	v_pk_add_f32 v[232:233], v[232:233], v[38:39]
	v_pk_add_f32 v[232:233], v[232:233], v[40:41]
	v_pk_add_f32 v[232:233], v[232:233], v[42:43]
	v_pk_add_f32 v[232:233], v[232:233], v[44:45]
	v_pk_add_f32 v[232:233], v[232:233], v[46:47]
	s_waitcnt lgkmcnt(0)
	v_mfma_f32_32x32x16_bf16 v[0:15], v[64:67], v[72:75], v[0:15]
	v_mfma_f32_32x32x16_bf16 v[16:31], v[64:67], v[76:79], v[16:31]
	v_mfma_f32_32x32x16_bf16 v[0:15], v[68:71], v[220:223], v[0:15]
	v_mfma_f32_32x32x16_bf16 v[16:31], v[68:71], v[224:227], v[16:31]
	s_waitcnt vmcnt(8)
	ds_write_b128 v247, v[156:159]
	ds_write_b128 v247, v[160:163] offset:1152
	ds_write_b128 v247, v[164:167] offset:2304
	ds_write_b128 v247, v[168:171] offset:3456
	ds_write_b128 v112, v[172:175]
	ds_write_b128 v112, v[176:179] offset:1024
	ds_write_b128 v112, v[180:183] offset:2048
	ds_write_b128 v112, v[184:187] offset:3072
	ds_read2_b32 v[32:33], v115 offset0:96 offset1:97
	ds_read2_b32 v[34:35], v115 offset0:98 offset1:99
	ds_read2_b32 v[36:37], v115 offset0:104 offset1:105
	ds_read2_b32 v[38:39], v115 offset0:106 offset1:107
	ds_read2_b32 v[40:41], v115 offset0:112 offset1:113
	ds_read2_b32 v[42:43], v115 offset0:114 offset1:115
	ds_read2_b32 v[44:45], v115 offset0:120 offset1:121
	ds_read2_b32 v[46:47], v115 offset0:122 offset1:123
	ds_read_b128 v[156:159], v248
	ds_read_b128 v[160:163], v248 offset:32
	ds_read_b128 v[164:167], v248 offset:64
	ds_read_b128 v[168:171], v248 offset:96
	ds_read_b64_tr_b16 v[72:73], v231
	ds_read_b64_tr_b16 v[74:75], v231 offset:512
	ds_read_b64_tr_b16 v[76:77], v231 offset:2048
	ds_read_b64_tr_b16 v[78:79], v231 offset:2560
	ds_read_b64_tr_b16 v[220:221], v231 offset:1024
	ds_read_b64_tr_b16 v[222:223], v231 offset:1536
	ds_read_b64_tr_b16 v[224:225], v231 offset:3072
	ds_read_b64_tr_b16 v[226:227], v231 offset:3584
	s_waitcnt lgkmcnt(8)
; __device__ __forceinline__ int crow(int r, int hi) { return (r & 3) + 8 * (r >> 2) + 4 * hi; }
; __device__ __forceinline__ void dil_unit(LAS unsigned char* lds, bf16_t* proj, int seq, int hd, int T0, int rho) {
;     ...
;     l += __shfl_xor(l, 32);
; #pragma unroll
;     for (int rr = 0; rr < 16; ++rr) {
;         const int j = crow(rr, hi);
	v_mfma_f32_32x32x16_bf16 v[32:47], v[156:159], v[48:51], v[32:47]
	v_mfma_f32_32x32x16_bf16 v[32:47], v[160:163], v[52:55], v[32:47]
	v_mfma_f32_32x32x16_bf16 v[32:47], v[164:167], v[56:59], v[32:47]
	v_mfma_f32_32x32x16_bf16 v[32:47], v[168:171], v[60:63], v[32:47]
	s_nop 11
	v_exp_f32_e32 v32, v32
	v_exp_f32_e32 v33, v33
	v_exp_f32_e32 v34, v34
	v_exp_f32_e32 v35, v35
	v_exp_f32_e32 v36, v36
	v_exp_f32_e32 v37, v37
	v_exp_f32_e32 v38, v38
	v_exp_f32_e32 v39, v39
	v_exp_f32_e32 v40, v40
	v_exp_f32_e32 v41, v41
	v_exp_f32_e32 v42, v42
	v_exp_f32_e32 v43, v43
	v_exp_f32_e32 v44, v44
	v_exp_f32_e32 v45, v45
	v_exp_f32_e32 v46, v46
	v_exp_f32_e32 v47, v47
	v_cvt_pk_bf16_f32 v64, v32, v33
	v_cvt_pk_bf16_f32 v65, v34, v35
	v_cvt_pk_bf16_f32 v66, v36, v37
	v_cvt_pk_bf16_f32 v67, v38, v39
	v_cvt_pk_bf16_f32 v68, v40, v41
	v_cvt_pk_bf16_f32 v69, v42, v43
	v_cvt_pk_bf16_f32 v70, v44, v45
	v_cvt_pk_bf16_f32 v71, v46, v47
	v_pk_add_f32 v[232:233], v[232:233], v[32:33]
	v_pk_add_f32 v[232:233], v[232:233], v[34:35]
	v_pk_add_f32 v[232:233], v[232:233], v[36:37]
	v_pk_add_f32 v[232:233], v[232:233], v[38:39]
	v_pk_add_f32 v[232:233], v[232:233], v[40:41]
	v_pk_add_f32 v[232:233], v[232:233], v[42:43]
	v_pk_add_f32 v[232:233], v[232:233], v[44:45]
	v_pk_add_f32 v[232:233], v[232:233], v[46:47]
	s_waitcnt lgkmcnt(0)
	v_mfma_f32_32x32x16_bf16 v[0:15], v[64:67], v[72:75], v[0:15]
	v_mfma_f32_32x32x16_bf16 v[16:31], v[64:67], v[76:79], v[16:31]
	v_mfma_f32_32x32x16_bf16 v[0:15], v[68:71], v[220:223], v[0:15]
	v_mfma_f32_32x32x16_bf16 v[16:31], v[68:71], v[224:227], v[16:31]
	s_waitcnt vmcnt(0)
	ds_write_b128 v247, v[188:191]
	ds_write_b128 v247, v[192:195] offset:1152
	ds_write_b128 v247, v[196:199] offset:2304
	ds_write_b128 v247, v[200:203] offset:3456
	ds_write_b128 v112, v[204:207]
	ds_write_b128 v112, v[208:211] offset:1024
	ds_write_b128 v112, v[212:215] offset:2048
	ds_write_b128 v112, v[216:219] offset:3072
	ds_read2_b32 v[32:33], v115 offset0:128 offset1:129
	ds_read2_b32 v[34:35], v115 offset0:130 offset1:131
	ds_read2_b32 v[36:37], v115 offset0:136 offset1:137
	ds_read2_b32 v[38:39], v115 offset0:138 offset1:139
	ds_read2_b32 v[40:41], v115 offset0:144 offset1:145
	ds_read2_b32 v[42:43], v115 offset0:146 offset1:147
	ds_read2_b32 v[44:45], v115 offset0:152 offset1:153
	ds_read2_b32 v[46:47], v115 offset0:154 offset1:155
	ds_read_b128 v[188:191], v248
	ds_read_b128 v[192:195], v248 offset:32
	ds_read_b128 v[196:199], v248 offset:64
	ds_read_b128 v[200:203], v248 offset:96
	ds_read_b64_tr_b16 v[72:73], v231
	ds_read_b64_tr_b16 v[74:75], v231 offset:512
	ds_read_b64_tr_b16 v[76:77], v231 offset:2048
	ds_read_b64_tr_b16 v[78:79], v231 offset:2560
	ds_read_b64_tr_b16 v[220:221], v231 offset:1024
	ds_read_b64_tr_b16 v[222:223], v231 offset:1536
	ds_read_b64_tr_b16 v[224:225], v231 offset:3072
	ds_read_b64_tr_b16 v[226:227], v231 offset:3584
	s_waitcnt lgkmcnt(8)
	v_mfma_f32_32x32x16_bf16 v[32:47], v[188:191], v[48:51], v[32:47]
	v_mfma_f32_32x32x16_bf16 v[32:47], v[192:195], v[52:55], v[32:47]
	v_mfma_f32_32x32x16_bf16 v[32:47], v[196:199], v[56:59], v[32:47]
	v_mfma_f32_32x32x16_bf16 v[32:47], v[200:203], v[60:63], v[32:47]
	s_nop 11
	v_exp_f32_e32 v32, v32
	v_exp_f32_e32 v33, v33
	v_exp_f32_e32 v34, v34
	v_exp_f32_e32 v35, v35
	v_exp_f32_e32 v36, v36
	v_exp_f32_e32 v37, v37
	v_exp_f32_e32 v38, v38
	v_exp_f32_e32 v39, v39
	v_exp_f32_e32 v40, v40
	v_exp_f32_e32 v41, v41
	v_exp_f32_e32 v42, v42
	v_exp_f32_e32 v43, v43
	v_exp_f32_e32 v44, v44
	v_exp_f32_e32 v45, v45
	v_exp_f32_e32 v46, v46
	v_exp_f32_e32 v47, v47
	v_cvt_pk_bf16_f32 v64, v32, v33
	v_cvt_pk_bf16_f32 v65, v34, v35
	v_cvt_pk_bf16_f32 v66, v36, v37
	v_cvt_pk_bf16_f32 v67, v38, v39
	v_cvt_pk_bf16_f32 v68, v40, v41
	v_cvt_pk_bf16_f32 v69, v42, v43
	v_cvt_pk_bf16_f32 v70, v44, v45
	v_cvt_pk_bf16_f32 v71, v46, v47
	v_pk_add_f32 v[232:233], v[232:233], v[32:33]
	v_pk_add_f32 v[232:233], v[232:233], v[34:35]
	v_pk_add_f32 v[232:233], v[232:233], v[36:37]
	v_pk_add_f32 v[232:233], v[232:233], v[38:39]
	v_pk_add_f32 v[232:233], v[232:233], v[40:41]
	v_pk_add_f32 v[232:233], v[232:233], v[42:43]
	v_pk_add_f32 v[232:233], v[232:233], v[44:45]
	v_pk_add_f32 v[232:233], v[232:233], v[46:47]
	s_waitcnt lgkmcnt(0)
	v_mfma_f32_32x32x16_bf16 v[0:15], v[64:67], v[72:75], v[0:15]
	v_mfma_f32_32x32x16_bf16 v[16:31], v[64:67], v[76:79], v[16:31]
	v_mfma_f32_32x32x16_bf16 v[0:15], v[68:71], v[220:223], v[0:15]
	v_mfma_f32_32x32x16_bf16 v[16:31], v[68:71], v[224:227], v[16:31]
	v_add_f32_e32 v113, v232, v233
	v_or_b32_e32 v114, 1, v107
	v_or_b32_e32 v97, 2, v107
	v_or_b32_e32 v96, 3, v107
	v_or_b32_e32 v95, 8, v107
	v_or_b32_e32 v94, 9, v107
	v_or_b32_e32 v93, 10, v107
	v_or_b32_e32 v92, 11, v107
	v_or_b32_e32 v91, 16, v107
	v_or_b32_e32 v90, 17, v107
	v_or_b32_e32 v89, 18, v107
	v_or_b32_e32 v88, 19, v107
	v_or_b32_e32 v87, 24, v107
	v_or_b32_e32 v86, 25, v107
	v_or_b32_e32 v85, 26, v107
	v_or_b32_e32 v84, 27, v107
	s_nop 11
	s_branch .LBB0_1265

; #define LAS __attribute__((address_space(3)))
; #define GRID_SYNC() do { unsigned char* w_ = wsb; asm volatile("" : "+s"(w_)); XcdBarrier b_; b_.bar = (unsigned*)(w_ + WS_CTL); b_.x = xb_xcc_id(); \
;         b_.st = (volatile LAS unsigned*)(lds + LDS_BAR_OFF); xcd_barrier(b_); } while (0)
; #define CPY(off, src, n) for (int i = tid; i < (n); i += 512) pw[(off) + i] = (src)[i]
; __global__ void __launch_bounds__(512) mk_fwd(Args a) {
;     extern __shared__ __attribute__((aligned(16))) unsigned char lds_raw[];
;     LAS unsigned char* lds = (LAS unsigned char*)lds_raw;
;     cg::grid_group grid = cg::this_grid();
;     if (threadIdx.x < 16) ((LAS unsigned*)(lds + LDS_BAR_OFF))[threadIdx.x] = 0u;
;     __syncthreads();
;     (void)xcd_barrier_post((unsigned*)(a.ws + WS_CTL), (volatile LAS unsigned*)(lds + LDS_BAR_OFF));
;     grid.sync();
;     ...
;     unsigned char* wsb = a.ws;
;     const int tid = threadIdx.x, lane = tid & 63, wave = __builtin_amdgcn_readfirstlane(tid >> 6);
;     const int G = gridDim.x, gw = blockIdx.x * 8 + wave, NGW = G * 8;
;     weights_phase(a, lds, gw, NGW, wave, lane);
;     norm_phase<true>(a.in[0], a.in[1], a.out, a.ws, 0, nullptr, gw, NGW, lane);
;     if (blockIdx.x == 0) {
;         float* pw = (float*)(a.ws + WS_PAR);
;     ...
;         CPY(P_CONV, a.in[7], 2304); CPY(P_DQN, a.in[8], 64); CPY(P_DKN, a.in[9], 64); CPY(P_LQ1, a.in[10], 64); CPY(P_LK1, a.in[11], 64); CPY(P_LQ2, a.in[12], 64); CPY(P_LK2, a.in[13], 64);
;         CPY(P_SUBN, a.in[14], 128); CPY(P_LQN, a.in[15], 128); CPY(P_LKN, a.in[16], 128); CPY(P_FIN, a.in[21], 2048); CPY(P_RB, a.in[22], 320);
;     ...
;     }
;     unsigned char* ws = a.ws; float* xout = a.out;
;     GRID_SYNC();
;     asm volatile("" : "+s"(ws), "+s"(xout));
;     ...
;     LAYER(0);
;     LAYER(1);
;     ...
; }
	.amdhsa_kernel _Z6mk_fwd4Args
		.amdhsa_group_segment_fixed_size 0
		.amdhsa_private_segment_fixed_size 0
		.amdhsa_kernarg_size 456
		.amdhsa_user_sgpr_count 2
		.amdhsa_user_sgpr_dispatch_ptr 0
		.amdhsa_user_sgpr_queue_ptr 0
		.amdhsa_user_sgpr_kernarg_segment_ptr 1
		.amdhsa_user_sgpr_dispatch_id 0
		.amdhsa_user_sgpr_kernarg_preload_length 0
		.amdhsa_user_sgpr_kernarg_preload_offset 0
		.amdhsa_user_sgpr_private_segment_size 0
		.amdhsa_uses_dynamic_stack 0
		.amdhsa_enable_private_segment 0
		.amdhsa_system_sgpr_workgroup_id_x 1
		.amdhsa_system_sgpr_workgroup_id_y 0
		.amdhsa_system_sgpr_workgroup_id_z 0
		.amdhsa_system_sgpr_workgroup_info 0
		.amdhsa_system_vgpr_workitem_id 2
		.amdhsa_next_free_vgpr 256
		.amdhsa_next_free_sgpr 102
		.amdhsa_accum_offset 256
		.amdhsa_reserve_vcc 1
		.amdhsa_float_round_mode_32 0
		.amdhsa_float_round_mode_16_64 0
		.amdhsa_float_denorm_mode_32 3
		.amdhsa_float_denorm_mode_16_64 3
		.amdhsa_dx10_clamp 1
		.amdhsa_ieee_mode 1
		.amdhsa_fp16_overflow 0
		.amdhsa_tg_split 0
		.amdhsa_exception_fp_ieee_invalid_op 0
		.amdhsa_exception_fp_denorm_src 0
		.amdhsa_exception_fp_ieee_div_zero 0
		.amdhsa_exception_fp_ieee_overflow 0
		.amdhsa_exception_fp_ieee_underflow 0
		.amdhsa_exception_fp_ieee_inexact 0
		.amdhsa_exception_int_div_zero 0
	.end_amdhsa_kernel

; #define LAS __attribute__((address_space(3)))
; #define GRID_SYNC() do { unsigned char* w_ = wsb; asm volatile("" : "+s"(w_)); XcdBarrier b_; b_.bar = (unsigned*)(w_ + WS_CTL); b_.x = xb_xcc_id(); \
;         b_.st = (volatile LAS unsigned*)(lds + LDS_BAR_OFF); xcd_barrier(b_); } while (0)
; #define CPY(off, src, n) for (int i = tid; i < (n); i += 512) pw[(off) + i] = (src)[i]
; __global__ void __launch_bounds__(512) mk_fwd(Args a) {
;     extern __shared__ __attribute__((aligned(16))) unsigned char lds_raw[];
;     LAS unsigned char* lds = (LAS unsigned char*)lds_raw;
;     cg::grid_group grid = cg::this_grid();
;     if (threadIdx.x < 16) ((LAS unsigned*)(lds + LDS_BAR_OFF))[threadIdx.x] = 0u;
;     __syncthreads();
;     (void)xcd_barrier_post((unsigned*)(a.ws + WS_CTL), (volatile LAS unsigned*)(lds + LDS_BAR_OFF));
;     grid.sync();
;     ...
;     unsigned char* wsb = a.ws;
;     const int tid = threadIdx.x, lane = tid & 63, wave = __builtin_amdgcn_readfirstlane(tid >> 6);
;     const int G = gridDim.x, gw = blockIdx.x * 8 + wave, NGW = G * 8;
;     weights_phase(a, lds, gw, NGW, wave, lane);
;     norm_phase<true>(a.in[0], a.in[1], a.out, a.ws, 0, nullptr, gw, NGW, lane);
;     if (blockIdx.x == 0) {
;         float* pw = (float*)(a.ws + WS_PAR);
;     ...
;         CPY(P_CONV, a.in[7], 2304); CPY(P_DQN, a.in[8], 64); CPY(P_DKN, a.in[9], 64); CPY(P_LQ1, a.in[10], 64); CPY(P_LK1, a.in[11], 64); CPY(P_LQ2, a.in[12], 64); CPY(P_LK2, a.in[13], 64);
;         CPY(P_SUBN, a.in[14], 128); CPY(P_LQN, a.in[15], 128); CPY(P_LKN, a.in[16], 128); CPY(P_FIN, a.in[21], 2048); CPY(P_RB, a.in[22], 320);
;     ...
;     }
;     unsigned char* ws = a.ws; float* xout = a.out;
;     GRID_SYNC();
;     asm volatile("" : "+s"(ws), "+s"(xout));
;     ...
;     LAYER(0);
;     LAYER(1);
;     ...
; }
amdhsa.kernels:
  - .agpr_count:     0
    .args:
      - .offset:         0
        .size:           200
        .value_kind:     by_value
      - .offset:         200
        .size:           4
        .value_kind:     hidden_block_count_x
      - .offset:         204
        .size:           4
        .value_kind:     hidden_block_count_y
      - .offset:         208
        .size:           4
        .value_kind:     hidden_block_count_z
      - .offset:         212
        .size:           2
        .value_kind:     hidden_group_size_x
      - .offset:         214
        .size:           2
        .value_kind:     hidden_group_size_y
      - .offset:         216
        .size:           2
        .value_kind:     hidden_group_size_z
      - .offset:         218
        .size:           2
        .value_kind:     hidden_remainder_x
      - .offset:         220
        .size:           2
        .value_kind:     hidden_remainder_y
      - .offset:         222
        .size:           2
        .value_kind:     hidden_remainder_z
      - .offset:         240
        .size:           8
        .value_kind:     hidden_global_offset_x
      - .offset:         248
        .size:           8
        .value_kind:     hidden_global_offset_y
      - .offset:         256
        .size:           8
        .value_kind:     hidden_global_offset_z
      - .offset:         264
        .size:           2
        .value_kind:     hidden_grid_dims
      - .offset:         288
        .size:           8
        .value_kind:     hidden_multigrid_sync_arg
      - .offset:         320
        .size:           4
        .value_kind:     hidden_dynamic_lds_size
    .group_segment_fixed_size: 0
    .kernarg_segment_align: 8
    .kernarg_segment_size: 456
    .language:       OpenCL C
    .language_version:
      - 2
      - 0
    .max_flat_workgroup_size: 512
    .name:           _Z6mk_fwd4Args
    .private_segment_fixed_size: 0
    .sgpr_count:     108
    .sgpr_spill_count: 48
    .symbol:         _Z6mk_fwd4Args.kd
    .uniform_work_group_size: 1
    .uses_dynamic_stack: false
    .vgpr_count:     256
    .vgpr_spill_count: 0
    .wavefront_size: 64
